# batched natten rel-pos-bias loads (v_cndmask select) and a*rcp(b) for sigmoid/silu/tanh denominators (f32, b>=1)
# speedup vs baseline: 1.0632x; 1.0178x over previous
; __device__ __forceinline__ float siluf_(float x) { return x / (1.0f + __expf(-x)); }
; __device__ __forceinline__ void phase_mod(const Params& p, float* smem) {
;     ...
;   for (int i = tid; i < 3 * DM; i += 256) {
;     int mr = i / DM, k = i % DM;
;     float c = mr < 2 ? p.in[I_C][mr * DM + k] : p.in[I_CCTX][k];
;     s_s[i] = siluf_(c);
;   }
.LBB0_7:
	s_or_b64 exec, exec, s[8:9]
	global_load_dword v10, v[14:15], off
	v_add_u32_e32 v15, 0x100, v17
	v_cmp_lt_i32_e32 vcc, s3, v17
	s_or_b64 s[6:7], vcc, s[6:7]
	s_waitcnt vmcnt(0)
	v_mul_f32_e32 v14, 0xbfb8aa3b, v10
	v_exp_f32_e32 v14, v14
	s_nop 0
	v_add_f32_e32 v14, 1.0, v14
	v_rcp_f32_e32 v18, v14
	s_nop 0
	v_mul_f32_e32 v17, v10, v18
	v_mov_b32_e32 v10, v17
	ds_write_b32 v16, v10
	v_add_u32_e32 v16, 0x400, v16
	v_mov_b32_e32 v17, v15
	s_andn2_b64 exec, exec, s[6:7]
	s_cbranch_execz .LBB0_12

; template <bool CL>
; __device__ __forceinline__ void natten_wave(const Params& p, int l, bool local, int b, int hh, int qrow0  ,
;                             int r, int ct, const f16* lK, const f16* lV) {
;     ...
; #pragma unroll
;   for (int cb = 0; cb < 16; ++cb) {
;     const int key = (cb >> 1) * 32 + kperm + 4 * (cb & 1);
;     f16x8 k0, k1;
;     if (CL) {
;       const f16* kp = lK + key * 72 + g * 16;
;       k0 = *(const f16x8*)(kp);
;       k1 = *(const f16x8*)(kp + 8);
;     } else {
;       const f16* kp = proj + (size_t)(NLAT + b * CTXL + key) * PJ + RD + hh * HD + g * 16;
;       k0 = *(const f16x8*)(kp);
;       k1 = *(const f16x8*)(kp + 8);
;     }
;     f32x4 a = f32x4{0.f, 0.f, 0.f, 0.f};
;     a = __builtin_amdgcn_mfma_f32_16x16x32_f16(k0, qf[0], a, 0, 0, 0);
;     a = __builtin_amdgcn_mfma_f32_16x16x32_f16(k1, qf[1], a, 0, 0, 0);
; #pragma unroll
;     for (int i = 0; i < 4; ++i) mx = fmaxf(mx, a[i]);
;     sc[cb] = a;
;     if (CL && (cb & 3) == 3) __builtin_amdgcn_sched_barrier(0);
;   }
;   mx = fmaxf(mx, __shfl_xor(mx, 16, 64));
;   mx = fmaxf(mx, __shfl_xor(mx, 32, 64));
.LBB0_548:
	s_or_b64 exec, exec, s[10:11]
	ds_read_b128 v[4:7], v117
	ds_read_b128 v[8:11], v117 offset:16
	ds_read_b128 v[12:15], v117 offset:576
	ds_read_b128 v[16:19], v117 offset:592
	v_ashrrev_i32_e32 v97, 31, v96
	s_waitcnt lgkmcnt(3)
	v_mfma_f32_16x16x32_f16 v[4:7], v[4:7], v[64:67], 0
	s_waitcnt lgkmcnt(2)
	v_mfma_f32_16x16x32_f16 v[60:63], v[8:11], v[0:3], v[4:7]
	ds_read_b128 v[8:11], v117 offset:4624
	s_nop 4
	ds_read_b128 v[4:7], v117 offset:4608
	s_waitcnt lgkmcnt(3)
	v_mfma_f32_16x16x32_f16 v[12:15], v[12:15], v[64:67], 0
	s_waitcnt lgkmcnt(2)
	v_mfma_f32_16x16x32_f16 v[56:59], v[16:19], v[0:3], v[12:15]
	s_waitcnt lgkmcnt(0)
	v_mfma_f32_16x16x32_f16 v[4:7], v[4:7], v[64:67], 0
	s_nop 3
	ds_read_b128 v[12:15], v117 offset:5184
	v_mfma_f32_16x16x32_f16 v[52:55], v[8:11], v[0:3], v[4:7]
	s_waitcnt lgkmcnt(0)
	v_mfma_f32_16x16x32_f16 v[8:11], v[12:15], v[64:67], 0
	s_nop 0
	ds_read_b128 v[4:7], v117 offset:5200
	s_waitcnt lgkmcnt(0)
	v_mfma_f32_16x16x32_f16 v[48:51], v[4:7], v[0:3], v[8:11]
	ds_read_b128 v[4:7], v117 offset:9216
	s_nop 2
	ds_read_b128 v[8:11], v117 offset:9232
	ds_read_b128 v[12:15], v117 offset:9792
	ds_read_b128 v[16:19], v117 offset:9808
	s_waitcnt lgkmcnt(3)
	v_mfma_f32_16x16x32_f16 v[4:7], v[4:7], v[64:67], 0
	s_waitcnt lgkmcnt(2)
	v_mfma_f32_16x16x32_f16 v[44:47], v[8:11], v[0:3], v[4:7]
	ds_read_b128 v[8:11], v117 offset:13840
	s_nop 4
	ds_read_b128 v[4:7], v117 offset:13824
	s_waitcnt lgkmcnt(3)
	v_mfma_f32_16x16x32_f16 v[12:15], v[12:15], v[64:67], 0
	s_waitcnt lgkmcnt(2)
	v_mfma_f32_16x16x32_f16 v[40:43], v[16:19], v[0:3], v[12:15]
	s_waitcnt lgkmcnt(0)
	v_mfma_f32_16x16x32_f16 v[4:7], v[4:7], v[64:67], 0
	s_nop 3
	ds_read_b128 v[12:15], v117 offset:14400
	v_mfma_f32_16x16x32_f16 v[36:39], v[8:11], v[0:3], v[4:7]
	s_waitcnt lgkmcnt(0)
	v_mfma_f32_16x16x32_f16 v[8:11], v[12:15], v[64:67], 0
	s_nop 0
	ds_read_b128 v[4:7], v117 offset:14416
	s_waitcnt lgkmcnt(0)
	v_mfma_f32_16x16x32_f16 v[32:35], v[4:7], v[0:3], v[8:11]
	ds_read_b128 v[4:7], v117 offset:18432
	s_nop 2
	ds_read_b128 v[8:11], v117 offset:18448
	ds_read_b128 v[12:15], v117 offset:19008
	ds_read_b128 v[16:19], v117 offset:19024
	s_waitcnt lgkmcnt(3)
	v_mfma_f32_16x16x32_f16 v[4:7], v[4:7], v[64:67], 0
	s_waitcnt lgkmcnt(2)
	v_mfma_f32_16x16x32_f16 v[28:31], v[8:11], v[0:3], v[4:7]
	ds_read_b128 v[8:11], v117 offset:23056
	s_nop 4
	ds_read_b128 v[4:7], v117 offset:23040
	s_waitcnt lgkmcnt(3)
	v_mfma_f32_16x16x32_f16 v[12:15], v[12:15], v[64:67], 0
	s_waitcnt lgkmcnt(2)
	v_mfma_f32_16x16x32_f16 v[24:27], v[16:19], v[0:3], v[12:15]
	s_waitcnt lgkmcnt(0)
	v_mfma_f32_16x16x32_f16 v[4:7], v[4:7], v[64:67], 0
	s_nop 3
	ds_read_b128 v[12:15], v117 offset:23616
	v_mfma_f32_16x16x32_f16 v[20:23], v[8:11], v[0:3], v[4:7]
	s_waitcnt lgkmcnt(0)
	v_mfma_f32_16x16x32_f16 v[8:11], v[12:15], v[64:67], 0
	s_nop 0
	ds_read_b128 v[4:7], v117 offset:23632
	s_waitcnt lgkmcnt(0)
	v_mfma_f32_16x16x32_f16 v[16:19], v[4:7], v[0:3], v[8:11]
	ds_read_b128 v[4:7], v117 offset:27648
	ds_read_b128 v[12:15], v117 offset:27664
	s_nop 1
	ds_read_b128 v[8:11], v117 offset:28224
	ds_read_b128 v[192:195], v117 offset:32272
	s_waitcnt lgkmcnt(3)
	v_mfma_f32_16x16x32_f16 v[4:7], v[4:7], v[64:67], 0
	s_waitcnt lgkmcnt(2)
	v_mfma_f32_16x16x32_f16 v[12:15], v[12:15], v[0:3], v[4:7]
	s_nop 5
	ds_read_b128 v[4:7], v117 offset:28240
	s_waitcnt lgkmcnt(2)
	v_mfma_f32_16x16x32_f16 v[8:11], v[8:11], v[64:67], 0
	s_waitcnt lgkmcnt(0)
	v_mfma_f32_16x16x32_f16 v[8:11], v[4:7], v[0:3], v[8:11]
	ds_read_b128 v[4:7], v117 offset:32256
	s_waitcnt lgkmcnt(0)
	v_mfma_f32_16x16x32_f16 v[4:7], v[4:7], v[64:67], 0
	v_mfma_f32_16x16x32_f16 v[4:7], v[192:195], v[0:3], v[4:7]
	ds_read_b128 v[192:195], v117 offset:32832
	s_waitcnt lgkmcnt(0)
	v_mfma_f32_16x16x32_f16 v[64:67], v[192:195], v[64:67], 0
	ds_read_b128 v[192:195], v117 offset:32848
	s_waitcnt lgkmcnt(0)
	v_mfma_f32_16x16x32_f16 v[0:3], v[192:195], v[0:3], v[64:67]
	s_nop 4
	v_max3_f32 v64, v70, s71, v69
	v_max3_f32 v64, v64, v72, v71
	v_max3_f32 v64, v64, v74, v73
	v_max3_f32 v64, v64, v76, v75
	v_max3_f32 v64, v64, v161, v160
	v_max3_f32 v64, v64, v163, v162
	v_max3_f32 v64, v64, v167, v166
	v_max3_f32 v64, v64, v169, v168
	v_max3_f32 v64, v64, v149, v148
	v_max3_f32 v64, v64, v153, v151
	v_max3_f32 v64, v64, v157, v156
	v_max3_f32 v64, v64, v159, v158
	v_max3_f32 v64, v64, v81, v80
	v_max3_f32 v64, v64, v83, v82
	v_max3_f32 v64, v64, v152, v150
	v_max3_f32 v64, v64, v155, v154
	v_max3_f32 v64, v64, v141, v140
	v_max3_f32 v64, v64, v143, v142
	v_max3_f32 v64, v64, v145, v144
	v_max3_f32 v64, v64, v147, v146
	v_max3_f32 v64, v64, v133, v132
	v_max3_f32 v64, v64, v135, v134
	v_max3_f32 v64, v64, v137, v136
	v_max3_f32 v64, v64, v139, v138
	v_max3_f32 v64, v64, v85, v84
	v_max3_f32 v64, v64, v87, v86
	v_max3_f32 v64, v64, v129, v128
	v_max3_f32 v64, v64, v131, v130
	v_max3_f32 v64, v64, v121, v120
	v_max3_f32 v64, v64, v123, v122
	v_max3_f32 v64, v64, v125, v124
	v_max3_f32 v64, v64, v127, v126
	v_max3_f32 v64, v64, v60, v61
	v_max3_f32 v64, v64, v62, v63
	v_max3_f32 v64, v64, v56, v57
	v_max3_f32 v64, v64, v58, v59
	v_max3_f32 v64, v64, v52, v53
	v_max3_f32 v64, v64, v54, v55
	v_max3_f32 v64, v64, v48, v49
	v_max3_f32 v64, v64, v50, v51
	v_max3_f32 v64, v64, v44, v45
	v_max3_f32 v64, v64, v46, v47
	v_max3_f32 v64, v64, v40, v41
	v_max3_f32 v64, v64, v42, v43
	v_max3_f32 v64, v64, v36, v37
	v_max3_f32 v64, v64, v38, v39
	v_max3_f32 v64, v64, v32, v33
	v_max3_f32 v64, v64, v34, v35
	v_max3_f32 v64, v64, v28, v29
	v_max3_f32 v64, v64, v30, v31
	v_max3_f32 v64, v64, v24, v25
	v_max3_f32 v64, v64, v26, v27
	v_max3_f32 v64, v64, v20, v21
	v_max3_f32 v64, v64, v22, v23
	v_max3_f32 v64, v64, v16, v17
	v_max3_f32 v64, v64, v18, v19
	v_max3_f32 v64, v64, v12, v13
	v_max3_f32 v64, v64, v14, v15
	v_max3_f32 v64, v64, v8, v9
	v_max3_f32 v64, v64, v10, v11
	v_max3_f32 v64, v64, v4, v5
	v_max3_f32 v64, v64, v6, v7
	v_max3_f32 v64, v64, v0, v1
	v_max3_f32 v64, v64, v2, v3
	ds_bpermute_b32 v65, v109, v64
	v_add_u32_e32 v164, v107, v68
	v_lshl_add_u64 v[192:193], v[164:165], 1, v[94:95]
	v_mov_b32_e32 v99, v165
	v_mov_b32_e32 v101, v165
	s_waitcnt lgkmcnt(0)
; template <bool CL>
; __device__ __forceinline__ void natten_wave(const Params& p, int l, bool local, int b, int hh, int qrow0  ,
;                             int r, int ct, const f16* lK, const f16* lV) {
;     ...
;   mx = fmaxf(mx, __shfl_xor(mx, 16, 64));
;   mx = fmaxf(mx, __shfl_xor(mx, 32, 64));
;   float sum = 0.f;
;   f32x4 o[4];
; #pragma unroll
;   for (int nb = 0; nb < 4; ++nb) o[nb] = f32x4{0.f, 0.f, 0.f, 0.f};
;   if (local) {
; #pragma unroll
;     for (int kr = 0; kr < 8; ++kr) {
;       f16x8 pf;
; #pragma unroll
;       for (int blk = 0; blk < 2; ++blk)
; #pragma unroll
;         for (int i = 0; i < 4; ++i) {
;           float e = __expf(sl[kr][blk][i] - mx);
;           sum += e;
;           pf[blk * 4 + i] = (f16)e;
;         }
;       int tk = (rs + kr) * GW + col0 + 8 * g;
; #pragma unroll
;       for (int nb = 0; nb < 4; ++nb) {
;         f16x8 vf = *(const f16x8*)(vt + (size_t)(nb * 16 + lq) * TL + tk);
;         o[nb] = __builtin_amdgcn_mfma_f32_16x16x32_f16(vf, pf, o[nb], 0, 0, 0);
;       }
;     }
	v_max_f32_e32 v65, v65, v65
	v_max_f32_e32 v64, v64, v65
	ds_bpermute_b32 v65, v110, v64
	v_mov_b32_e32 v103, v165
	v_mov_b32_e32 v105, v165
	s_waitcnt lgkmcnt(0)
	v_max_f32_e32 v65, v65, v65
	v_max_f32_e32 v119, v64, v65
	v_sub_f32_e32 v64, v70, v119
	v_mul_f32_e32 v64, 0x3fb8aa3b, v64
	v_sub_f32_e32 v66, v69, v119
	v_exp_f32_e32 v64, v64
	v_mul_f32_e32 v66, 0x3fb8aa3b, v66
	v_sub_f32_e32 v67, v72, v119
	v_exp_f32_e32 v66, v66
	v_mul_f32_e32 v67, 0x3fb8aa3b, v67
	v_sub_f32_e32 v69, v71, v119
	v_exp_f32_e32 v67, v67
	v_mul_f32_e32 v69, 0x3fb8aa3b, v69
	v_exp_f32_e32 v69, v69
	v_add_f32_e32 v65, 0, v64
	v_add_f32_e32 v65, v66, v65
	v_add_f32_e32 v65, v67, v65
	v_add_f32_e32 v170, v69, v65
	v_sub_f32_e32 v65, v74, v119
	v_mul_f32_e32 v65, 0x3fb8aa3b, v65
	v_exp_f32_e32 v196, v65
	v_sub_f32_e32 v65, v73, v119
	v_mul_f32_e32 v65, 0x3fb8aa3b, v65
	v_exp_f32_e32 v197, v65
	v_sub_f32_e32 v65, v76, v119
	v_mul_f32_e32 v65, 0x3fb8aa3b, v65
	v_exp_f32_e32 v198, v65
	v_sub_f32_e32 v65, v75, v119
	v_mul_f32_e32 v65, 0x3fb8aa3b, v65
	v_exp_f32_e32 v199, v65
	v_cvt_pk_f16_f32 v76, v64, v66
	v_lshl_add_u64 v[64:65], v[192:193], 0, v[98:99]
	v_cvt_pk_f16_f32 v77, v67, v69
	global_load_dwordx4 v[64:67], v[64:65], off
	v_cvt_pk_f16_f32 v79, v198, v199
	v_cvt_pk_f16_f32 v78, v196, v197
	v_lshl_add_u64 v[72:73], v[192:193], 0, v[102:103]
	global_load_dwordx4 v[72:75], v[72:73], off
	v_sub_f32_e32 v161, v161, v119
	v_mul_f32_e32 v161, 0x3fb8aa3b, v161
	v_add_f32_e32 v164, v196, v170
	v_exp_f32_e32 v170, v161
	v_add_f32_e32 v164, v197, v164
	v_sub_f32_e32 v160, v160, v119
	v_add_f32_e32 v164, v198, v164
	v_mul_f32_e32 v160, 0x3fb8aa3b, v160
	v_sub_f32_e32 v163, v163, v119
	v_add_f32_e32 v164, v199, v164
	v_exp_f32_e32 v160, v160
	v_mul_f32_e32 v163, 0x3fb8aa3b, v163
	v_sub_f32_e32 v162, v162, v119
	v_add_f32_e32 v161, v170, v164
	v_exp_f32_e32 v164, v163
	v_mul_f32_e32 v162, 0x3fb8aa3b, v162
	v_add_f32_e32 v161, v160, v161
	v_cvt_pk_f16_f32 v160, v170, v160
	v_add_f32_e32 v161, v164, v161
	v_sub_f32_e32 v81, v81, v119
	v_mul_f32_e32 v81, 0x3fb8aa3b, v81
	v_sub_f32_e32 v80, v80, v119
	v_mul_f32_e32 v80, 0x3fb8aa3b, v80
	v_sub_f32_e32 v83, v83, v119
	v_exp_f32_e32 v80, v80
	v_mul_f32_e32 v83, 0x3fb8aa3b, v83
	v_sub_f32_e32 v82, v82, v119
	v_mul_f32_e32 v82, 0x3fb8aa3b, v82
	v_sub_f32_e32 v60, v60, v119
	v_mul_f32_e32 v60, 0x3fb8aa3b, v60
	v_sub_f32_e32 v61, v61, v119
	v_exp_f32_e32 v60, v60
	v_mul_f32_e32 v61, 0x3fb8aa3b, v61
	v_sub_f32_e32 v62, v62, v119
	v_exp_f32_e32 v61, v61
	v_mul_f32_e32 v62, 0x3fb8aa3b, v62
	v_sub_f32_e32 v63, v63, v119
	v_exp_f32_e32 v62, v62
	v_mul_f32_e32 v63, 0x3fb8aa3b, v63
	v_exp_f32_e32 v63, v63
	v_sub_f32_e32 v56, v56, v119
	v_mul_f32_e32 v56, 0x3fb8aa3b, v56
	s_waitcnt vmcnt(0)
	v_mfma_f32_16x16x32_f16 v[72:75], v[72:75], v[76:79], 0
	v_mfma_f32_16x16x32_f16 v[68:71], v[64:67], v[76:79], 0
	v_lshl_add_u64 v[64:65], v[192:193], 0, v[100:101]
	v_lshl_add_u64 v[192:193], v[192:193], 0, v[104:105]
	global_load_dwordx4 v[64:67], v[64:65], off
	s_waitcnt vmcnt(0)
	v_mfma_f32_16x16x32_f16 v[64:67], v[64:67], v[76:79], 0
	global_load_dwordx4 v[192:195], v[192:193], off
	s_waitcnt vmcnt(0)
	v_mfma_f32_16x16x32_f16 v[76:79], v[192:195], v[76:79], 0
	v_exp_f32_e32 v192, v162
	s_nop 0
	v_add_f32_e32 v194, v192, v161
	v_sub_f32_e32 v161, v167, v119
	v_mul_f32_e32 v161, 0x3fb8aa3b, v161
	v_exp_f32_e32 v195, v161
	v_sub_f32_e32 v161, v166, v119
	v_mul_f32_e32 v161, 0x3fb8aa3b, v161
	v_exp_f32_e32 v196, v161
	v_sub_f32_e32 v161, v169, v119
	v_mul_f32_e32 v161, 0x3fb8aa3b, v161
	v_exp_f32_e32 v197, v161
	v_sub_f32_e32 v161, v168, v119
	v_mul_f32_e32 v161, 0x3fb8aa3b, v161
	v_exp_f32_e32 v198, v161
	v_cvt_pk_f16_f32 v161, v164, v192
	v_add_u32_e32 v164, s48, v107
	v_lshl_add_u64 v[192:193], v[164:165], 1, v[94:95]
	v_lshl_add_u64 v[166:167], v[192:193], 0, v[98:99]
	global_load_dwordx4 v[166:169], v[166:167], off
	v_cvt_pk_f16_f32 v163, v197, v198
	v_cvt_pk_f16_f32 v162, v195, v196
	v_add_u32_e32 v164, s47, v107
	s_waitcnt vmcnt(0)
	v_mfma_f32_16x16x32_f16 v[68:71], v[166:169], v[160:163], v[68:71]
	v_lshl_add_u64 v[166:167], v[192:193], 0, v[100:101]
	global_load_dwordx4 v[166:169], v[166:167], off
	s_waitcnt vmcnt(0)
	v_mfma_f32_16x16x32_f16 v[166:169], v[166:169], v[160:163], v[64:67]
	s_nop 2
	v_lshl_add_u64 v[64:65], v[192:193], 0, v[102:103]
	global_load_dwordx4 v[64:67], v[64:65], off
	s_waitcnt vmcnt(0)
	v_mfma_f32_16x16x32_f16 v[72:75], v[64:67], v[160:163], v[72:75]
	v_lshl_add_u64 v[64:65], v[192:193], 0, v[104:105]
	global_load_dwordx4 v[64:67], v[64:65], off
	s_waitcnt vmcnt(0)
	v_mfma_f32_16x16x32_f16 v[76:79], v[64:67], v[160:163], v[76:79]
	v_sub_f32_e32 v65, v149, v119
	v_mul_f32_e32 v65, 0x3fb8aa3b, v65
	v_sub_f32_e32 v66, v148, v119
	v_add_f32_e32 v64, v195, v194
	v_exp_f32_e32 v65, v65
	v_mul_f32_e32 v66, 0x3fb8aa3b, v66
	v_sub_f32_e32 v67, v153, v119
	v_add_f32_e32 v64, v196, v64
	v_exp_f32_e32 v66, v66
	v_mul_f32_e32 v67, 0x3fb8aa3b, v67
	v_sub_f32_e32 v148, v151, v119
	v_add_f32_e32 v64, v197, v64
	v_exp_f32_e32 v67, v67
	v_mul_f32_e32 v148, 0x3fb8aa3b, v148
	v_add_f32_e32 v64, v198, v64
	v_exp_f32_e32 v148, v148
	v_add_f32_e32 v64, v65, v64
	v_add_f32_e32 v64, v66, v64
	v_add_f32_e32 v64, v67, v64
	v_add_f32_e32 v151, v148, v64
	v_sub_f32_e32 v64, v157, v119
	v_mul_f32_e32 v64, 0x3fb8aa3b, v64
	v_exp_f32_e32 v153, v64
	v_sub_f32_e32 v64, v156, v119
	v_mul_f32_e32 v64, 0x3fb8aa3b, v64
	v_exp_f32_e32 v170, v64
	v_sub_f32_e32 v64, v159, v119
	v_mul_f32_e32 v64, 0x3fb8aa3b, v64
	v_exp_f32_e32 v192, v64
	v_sub_f32_e32 v64, v158, v119
	v_mul_f32_e32 v64, 0x3fb8aa3b, v64
	v_cvt_pk_f16_f32 v157, v67, v148
	v_lshl_add_u64 v[148:149], v[164:165], 1, v[94:95]
	v_exp_f32_e32 v193, v64
	v_cvt_pk_f16_f32 v156, v65, v66
	v_lshl_add_u64 v[64:65], v[148:149], 0, v[98:99]
	global_load_dwordx4 v[64:67], v[64:65], off
	v_lshl_add_u64 v[160:161], v[148:149], 0, v[102:103]
	global_load_dwordx4 v[160:163], v[160:161], off
	v_cvt_pk_f16_f32 v159, v192, v193
	v_cvt_pk_f16_f32 v158, v153, v170
	v_add_u32_e32 v164, s46, v107
	s_waitcnt vmcnt(1)
; template <bool CL>
; __device__ __forceinline__ void natten_wave(const Params& p, int l, bool local, int b, int hh, int qrow0  ,
;                             int r, int ct, const f16* lK, const f16* lV) {
;     ...
;   if (local) {
; #pragma unroll
;     for (int kr = 0; kr < 8; ++kr) {
;       f16x8 pf;
; #pragma unroll
;       for (int blk = 0; blk < 2; ++blk)
; #pragma unroll
;         for (int i = 0; i < 4; ++i) {
;           float e = __expf(sl[kr][blk][i] - mx);
;           sum += e;
;           pf[blk * 4 + i] = (f16)e;
;         }
;       int tk = (rs + kr) * GW + col0 + 8 * g;
; #pragma unroll
;       for (int nb = 0; nb < 4; ++nb) {
;         f16x8 vf = *(const f16x8*)(vt + (size_t)(nb * 16 + lq) * TL + tk);
;         o[nb] = __builtin_amdgcn_mfma_f32_16x16x32_f16(vf, pf, o[nb], 0, 0, 0);
;       }
;     }
	v_mfma_f32_16x16x32_f16 v[64:67], v[64:67], v[156:159], v[68:71]
	s_nop 2
	v_lshl_add_u64 v[68:69], v[148:149], 0, v[100:101]
	v_lshl_add_u64 v[148:149], v[148:149], 0, v[104:105]
	global_load_dwordx4 v[68:71], v[68:69], off
	s_waitcnt vmcnt(1)
	v_mfma_f32_16x16x32_f16 v[72:75], v[160:163], v[156:159], v[72:75]
	global_load_dwordx4 v[160:163], v[148:149], off
	v_add_f32_e32 v148, v153, v151
	v_exp_f32_e32 v149, v81
	v_add_f32_e32 v148, v170, v148
	v_add_f32_e32 v148, v192, v148
	v_add_f32_e32 v148, v193, v148
	v_add_f32_e32 v81, v149, v148
	v_exp_f32_e32 v148, v83
	v_exp_f32_e32 v151, v82
	v_add_f32_e32 v81, v80, v81
	s_waitcnt vmcnt(1)
	v_mfma_f32_16x16x32_f16 v[68:71], v[68:71], v[156:159], v[166:169]
	v_add_f32_e32 v81, v148, v81
	v_cvt_pk_f16_f32 v80, v149, v80
	s_waitcnt vmcnt(0)
	v_mfma_f32_16x16x32_f16 v[76:79], v[160:163], v[156:159], v[76:79]
	v_add_f32_e32 v156, v151, v81
	v_sub_f32_e32 v81, v152, v119
	v_mul_f32_e32 v81, 0x3fb8aa3b, v81
	v_exp_f32_e32 v157, v81
	v_sub_f32_e32 v81, v150, v119
	v_mul_f32_e32 v81, 0x3fb8aa3b, v81
	v_exp_f32_e32 v158, v81
	v_sub_f32_e32 v81, v155, v119
	v_mul_f32_e32 v81, 0x3fb8aa3b, v81
	v_exp_f32_e32 v155, v81
	v_sub_f32_e32 v81, v154, v119
	v_mul_f32_e32 v81, 0x3fb8aa3b, v81
	v_lshl_add_u64 v[152:153], v[164:165], 1, v[94:95]
	v_exp_f32_e32 v154, v81
	v_cvt_pk_f16_f32 v81, v148, v151
	v_lshl_add_u64 v[148:149], v[152:153], 0, v[98:99]
	global_load_dwordx4 v[148:151], v[148:149], off
	v_cvt_pk_f16_f32 v83, v155, v154
	v_cvt_pk_f16_f32 v82, v157, v158
	v_add_u32_e32 v164, s41, v107
	s_waitcnt vmcnt(0)
	v_mfma_f32_16x16x32_f16 v[64:67], v[148:151], v[80:83], v[64:67]
	v_lshl_add_u64 v[148:149], v[152:153], 0, v[100:101]
	global_load_dwordx4 v[148:151], v[148:149], off
	s_waitcnt vmcnt(0)
	v_mfma_f32_16x16x32_f16 v[68:71], v[148:151], v[80:83], v[68:71]
	v_lshl_add_u64 v[148:149], v[152:153], 0, v[102:103]
	global_load_dwordx4 v[148:151], v[148:149], off
	s_waitcnt vmcnt(0)
	v_mfma_f32_16x16x32_f16 v[72:75], v[148:151], v[80:83], v[72:75]
	v_lshl_add_u64 v[148:149], v[152:153], 0, v[104:105]
	global_load_dwordx4 v[148:151], v[148:149], off
	s_waitcnt vmcnt(0)
	v_mfma_f32_16x16x32_f16 v[76:79], v[148:151], v[80:83], v[76:79]
	v_sub_f32_e32 v81, v141, v119
	v_mul_f32_e32 v81, 0x3fb8aa3b, v81
	v_exp_f32_e32 v141, v81
	v_sub_f32_e32 v81, v140, v119
	v_mul_f32_e32 v81, 0x3fb8aa3b, v81
	v_add_f32_e32 v80, v157, v156
	v_exp_f32_e32 v140, v81
	v_sub_f32_e32 v81, v143, v119
	v_add_f32_e32 v80, v158, v80
	v_mul_f32_e32 v81, 0x3fb8aa3b, v81
	v_sub_f32_e32 v82, v142, v119
	v_add_f32_e32 v80, v155, v80
	v_exp_f32_e32 v81, v81
	v_mul_f32_e32 v82, 0x3fb8aa3b, v82
	v_add_f32_e32 v80, v154, v80
	v_exp_f32_e32 v142, v82
	v_add_f32_e32 v80, v141, v80
	v_add_f32_e32 v80, v140, v80
	v_add_f32_e32 v80, v81, v80
	v_add_f32_e32 v148, v142, v80
	v_sub_f32_e32 v80, v145, v119
	v_mul_f32_e32 v80, 0x3fb8aa3b, v80
	v_exp_f32_e32 v149, v80
	v_sub_f32_e32 v80, v144, v119
	v_mul_f32_e32 v80, 0x3fb8aa3b, v80
	v_exp_f32_e32 v150, v80
	v_sub_f32_e32 v80, v147, v119
	v_mul_f32_e32 v80, 0x3fb8aa3b, v80
	v_exp_f32_e32 v147, v80
	v_sub_f32_e32 v80, v146, v119
	v_mul_f32_e32 v80, 0x3fb8aa3b, v80
	v_lshl_add_u64 v[144:145], v[164:165], 1, v[94:95]
	v_exp_f32_e32 v146, v80
	v_cvt_pk_f16_f32 v80, v141, v140
	v_lshl_add_u64 v[140:141], v[144:145], 0, v[98:99]
	v_cvt_pk_f16_f32 v81, v81, v142
	global_load_dwordx4 v[140:143], v[140:141], off
	v_cvt_pk_f16_f32 v83, v147, v146
	v_cvt_pk_f16_f32 v82, v149, v150
	v_add_u32_e32 v164, s45, v107
	s_waitcnt vmcnt(0)
	v_mfma_f32_16x16x32_f16 v[64:67], v[140:143], v[80:83], v[64:67]
	v_lshl_add_u64 v[140:141], v[144:145], 0, v[100:101]
	global_load_dwordx4 v[140:143], v[140:141], off
	s_waitcnt vmcnt(0)
	v_mfma_f32_16x16x32_f16 v[68:71], v[140:143], v[80:83], v[68:71]
	v_lshl_add_u64 v[140:141], v[144:145], 0, v[102:103]
	global_load_dwordx4 v[140:143], v[140:141], off
	s_waitcnt vmcnt(0)
	v_mfma_f32_16x16x32_f16 v[72:75], v[140:143], v[80:83], v[72:75]
	v_lshl_add_u64 v[140:141], v[144:145], 0, v[104:105]
	global_load_dwordx4 v[140:143], v[140:141], off
	s_waitcnt vmcnt(0)
	v_mfma_f32_16x16x32_f16 v[76:79], v[140:143], v[80:83], v[76:79]
	v_sub_f32_e32 v81, v133, v119
	v_mul_f32_e32 v81, 0x3fb8aa3b, v81
	v_exp_f32_e32 v133, v81
	v_sub_f32_e32 v81, v132, v119
	v_mul_f32_e32 v81, 0x3fb8aa3b, v81
	v_add_f32_e32 v80, v149, v148
	v_exp_f32_e32 v132, v81
	v_sub_f32_e32 v81, v135, v119
	v_add_f32_e32 v80, v150, v80
	v_mul_f32_e32 v81, 0x3fb8aa3b, v81
	v_sub_f32_e32 v82, v134, v119
	v_add_f32_e32 v80, v147, v80
	v_exp_f32_e32 v81, v81
	v_mul_f32_e32 v82, 0x3fb8aa3b, v82
	v_add_f32_e32 v80, v146, v80
	v_exp_f32_e32 v134, v82
	v_add_f32_e32 v80, v133, v80
	v_add_f32_e32 v80, v132, v80
	v_add_f32_e32 v80, v81, v80
	v_add_f32_e32 v140, v134, v80
	v_sub_f32_e32 v80, v137, v119
	v_mul_f32_e32 v80, 0x3fb8aa3b, v80
	v_exp_f32_e32 v141, v80
	v_sub_f32_e32 v80, v136, v119
	v_mul_f32_e32 v80, 0x3fb8aa3b, v80
	v_exp_f32_e32 v142, v80
	v_sub_f32_e32 v80, v139, v119
	v_mul_f32_e32 v80, 0x3fb8aa3b, v80
	v_exp_f32_e32 v139, v80
	v_sub_f32_e32 v80, v138, v119
	v_mul_f32_e32 v80, 0x3fb8aa3b, v80
	v_lshl_add_u64 v[136:137], v[164:165], 1, v[94:95]
	v_exp_f32_e32 v138, v80
	v_cvt_pk_f16_f32 v80, v133, v132
	v_lshl_add_u64 v[132:133], v[136:137], 0, v[98:99]
	v_cvt_pk_f16_f32 v81, v81, v134
	global_load_dwordx4 v[132:135], v[132:133], off
	v_cvt_pk_f16_f32 v83, v139, v138
	v_cvt_pk_f16_f32 v82, v141, v142
	v_add_u32_e32 v164, s44, v107
	s_waitcnt vmcnt(0)
	v_mfma_f32_16x16x32_f16 v[64:67], v[132:135], v[80:83], v[64:67]
	v_lshl_add_u64 v[132:133], v[136:137], 0, v[100:101]
	global_load_dwordx4 v[132:135], v[132:133], off
	s_waitcnt vmcnt(0)
; template <bool CL>
; __device__ __forceinline__ void natten_wave(const Params& p, int l, bool local, int b, int hh, int qrow0  ,
;                             int r, int ct, const f16* lK, const f16* lV) {
;     ...
;   if (local) {
; #pragma unroll
;     for (int kr = 0; kr < 8; ++kr) {
;       f16x8 pf;
; #pragma unroll
;       for (int blk = 0; blk < 2; ++blk)
; #pragma unroll
;         for (int i = 0; i < 4; ++i) {
;           float e = __expf(sl[kr][blk][i] - mx);
;           sum += e;
;           pf[blk * 4 + i] = (f16)e;
;         }
;       int tk = (rs + kr) * GW + col0 + 8 * g;
; #pragma unroll
;       for (int nb = 0; nb < 4; ++nb) {
;         f16x8 vf = *(const f16x8*)(vt + (size_t)(nb * 16 + lq) * TL + tk);
;         o[nb] = __builtin_amdgcn_mfma_f32_16x16x32_f16(vf, pf, o[nb], 0, 0, 0);
;       }
;     }
;     ...
;   for (int pr = 0; pr < 8; ++pr) {
;     f16x8 pf;
; #pragma unroll
;     for (int blk = 0; blk < 2; ++blk)
; #pragma unroll
;       for (int i = 0; i < 4; ++i) {
;         float e = __expf(sc[pr * 2 + blk][i] - mx);
;         sum += e;
;         pf[blk * 4 + i] = (f16)e;
;       }
;     int tk = pr * 32 + 8 * g;
; #pragma unroll
;     for (int nb = 0; nb < 4; ++nb) {
;       f16x8 vf;
;       if (CL) vf = *(const f16x8*)(lV + (nb * 16 + lq) * 264 + tk);
;       else vf = *(const f16x8*)(vtc + (size_t)(nb * 16 + lq) * CTXL + tk);
;       o[nb] = __builtin_amdgcn_mfma_f32_16x16x32_f16(vf, pf, o[nb], 0, 0, 0);
;     }
	v_mfma_f32_16x16x32_f16 v[68:71], v[132:135], v[80:83], v[68:71]
	v_lshl_add_u64 v[132:133], v[136:137], 0, v[102:103]
	global_load_dwordx4 v[132:135], v[132:133], off
	s_waitcnt vmcnt(0)
	v_mfma_f32_16x16x32_f16 v[72:75], v[132:135], v[80:83], v[72:75]
	v_lshl_add_u64 v[132:133], v[136:137], 0, v[104:105]
	global_load_dwordx4 v[132:135], v[132:133], off
	s_waitcnt vmcnt(0)
	v_mfma_f32_16x16x32_f16 v[76:79], v[132:135], v[80:83], v[76:79]
	v_sub_f32_e32 v81, v85, v119
	v_mul_f32_e32 v81, 0x3fb8aa3b, v81
	v_sub_f32_e32 v82, v84, v119
	v_add_f32_e32 v80, v141, v140
	v_exp_f32_e32 v81, v81
	v_mul_f32_e32 v82, 0x3fb8aa3b, v82
	v_sub_f32_e32 v83, v87, v119
	v_add_f32_e32 v80, v142, v80
	v_exp_f32_e32 v82, v82
	v_mul_f32_e32 v83, 0x3fb8aa3b, v83
	v_sub_f32_e32 v84, v86, v119
	v_add_f32_e32 v80, v139, v80
	v_exp_f32_e32 v83, v83
	v_mul_f32_e32 v84, 0x3fb8aa3b, v84
	v_add_f32_e32 v80, v138, v80
	v_exp_f32_e32 v84, v84
	v_add_f32_e32 v80, v81, v80
	v_add_f32_e32 v80, v82, v80
	v_add_f32_e32 v80, v83, v80
	v_add_f32_e32 v134, v84, v80
	v_sub_f32_e32 v80, v129, v119
	v_mul_f32_e32 v80, 0x3fb8aa3b, v80
	v_exp_f32_e32 v135, v80
	v_sub_f32_e32 v80, v128, v119
	v_mul_f32_e32 v80, 0x3fb8aa3b, v80
	v_exp_f32_e32 v136, v80
	v_sub_f32_e32 v80, v131, v119
	v_mul_f32_e32 v80, 0x3fb8aa3b, v80
	v_exp_f32_e32 v137, v80
	v_sub_f32_e32 v80, v130, v119
	v_mul_f32_e32 v80, 0x3fb8aa3b, v80
	v_lshl_add_u64 v[132:133], v[164:165], 1, v[94:95]
	v_exp_f32_e32 v138, v80
	v_cvt_pk_f16_f32 v128, v81, v82
	v_lshl_add_u64 v[80:81], v[132:133], 0, v[98:99]
	v_cvt_pk_f16_f32 v129, v83, v84
	global_load_dwordx4 v[80:83], v[80:81], off
	v_cvt_pk_f16_f32 v131, v137, v138
	v_cvt_pk_f16_f32 v130, v135, v136
	v_add_u32_e32 v164, s42, v107
	s_waitcnt vmcnt(0)
	v_mfma_f32_16x16x32_f16 v[80:83], v[80:83], v[128:131], v[64:67]
	s_nop 2
	v_lshl_add_u64 v[64:65], v[132:133], 0, v[100:101]
	global_load_dwordx4 v[64:67], v[64:65], off
	s_waitcnt vmcnt(0)
	v_mfma_f32_16x16x32_f16 v[84:87], v[64:67], v[128:131], v[68:71]
	v_lshl_add_u64 v[64:65], v[132:133], 0, v[102:103]
	global_load_dwordx4 v[64:67], v[64:65], off
	s_nop 0
	v_sub_f32_e32 v69, v121, v119
	s_waitcnt vmcnt(0)
	v_mfma_f32_16x16x32_f16 v[72:75], v[64:67], v[128:131], v[72:75]
	v_lshl_add_u64 v[64:65], v[132:133], 0, v[104:105]
	global_load_dwordx4 v[64:67], v[64:65], off
	v_mul_f32_e32 v69, 0x3fb8aa3b, v69
	s_waitcnt vmcnt(0)
	v_mfma_f32_16x16x32_f16 v[64:67], v[64:67], v[128:131], v[76:79]
	s_nop 2
	v_exp_f32_e32 v76, v69
	v_sub_f32_e32 v69, v120, v119
	v_mul_f32_e32 v69, 0x3fb8aa3b, v69
	v_add_f32_e32 v68, v135, v134
	v_exp_f32_e32 v77, v69
	v_sub_f32_e32 v69, v123, v119
	v_add_f32_e32 v68, v136, v68
	v_mul_f32_e32 v69, 0x3fb8aa3b, v69
	v_sub_f32_e32 v70, v122, v119
	v_add_f32_e32 v68, v137, v68
	v_exp_f32_e32 v69, v69
	v_mul_f32_e32 v70, 0x3fb8aa3b, v70
	v_add_f32_e32 v68, v138, v68
	v_exp_f32_e32 v78, v70
	v_add_f32_e32 v68, v76, v68
	v_add_f32_e32 v68, v77, v68
	v_add_f32_e32 v68, v69, v68
	v_add_f32_e32 v122, v78, v68
	v_sub_f32_e32 v68, v125, v119
	v_mul_f32_e32 v68, 0x3fb8aa3b, v68
	v_exp_f32_e32 v123, v68
	v_sub_f32_e32 v68, v124, v119
	v_mul_f32_e32 v68, 0x3fb8aa3b, v68
	v_exp_f32_e32 v124, v68
	v_sub_f32_e32 v68, v127, v119
	v_mul_f32_e32 v68, 0x3fb8aa3b, v68
	v_exp_f32_e32 v125, v68
	v_sub_f32_e32 v68, v126, v119
	v_mul_f32_e32 v68, 0x3fb8aa3b, v68
	v_lshl_add_u64 v[120:121], v[164:165], 1, v[94:95]
	v_exp_f32_e32 v126, v68
	v_cvt_pk_f16_f32 v68, v76, v77
	v_lshl_add_u64 v[76:77], v[120:121], 0, v[98:99]
	v_cvt_pk_f16_f32 v69, v69, v78
	global_load_dwordx4 v[76:79], v[76:77], off
	v_cvt_pk_f16_f32 v71, v125, v126
	v_cvt_pk_f16_f32 v70, v123, v124
	s_waitcnt vmcnt(0)
	s_nop 0
	v_mfma_f32_16x16x32_f16 v[80:83], v[76:79], v[68:71], v[80:83]
	v_lshl_add_u64 v[76:77], v[120:121], 0, v[100:101]
	global_load_dwordx4 v[76:79], v[76:77], off
	s_waitcnt vmcnt(0)
	v_mfma_f32_16x16x32_f16 v[76:79], v[76:79], v[68:71], v[84:87]
	s_nop 2
	v_lshl_add_u64 v[84:85], v[120:121], 0, v[102:103]
	global_load_dwordx4 v[84:87], v[84:85], off
	s_waitcnt vmcnt(0)
	v_mfma_f32_16x16x32_f16 v[72:75], v[84:87], v[68:71], v[72:75]
	v_lshl_add_u64 v[84:85], v[120:121], 0, v[104:105]
	global_load_dwordx4 v[84:87], v[84:85], off
	s_waitcnt vmcnt(0)
	v_mfma_f32_16x16x32_f16 v[64:67], v[84:87], v[68:71], v[64:67]
	v_add_f32_e32 v68, v123, v122
	v_add_f32_e32 v68, v124, v68
	v_add_f32_e32 v68, v125, v68
	v_add_f32_e32 v68, v126, v68
	v_add_f32_e32 v68, v60, v68
	v_add_f32_e32 v68, v61, v68
	v_exp_f32_e32 v85, v56
	v_sub_f32_e32 v56, v57, v119
	v_add_f32_e32 v68, v62, v68
	v_mul_f32_e32 v56, 0x3fb8aa3b, v56
	v_add_f32_e32 v84, v63, v68
	v_exp_f32_e32 v86, v56
	v_sub_f32_e32 v56, v58, v119
	ds_read_b128 v[68:71], v118 offset:45312
	v_mul_f32_e32 v56, 0x3fb8aa3b, v56
	v_exp_f32_e32 v87, v56
	v_sub_f32_e32 v56, v59, v119
	v_mul_f32_e32 v56, 0x3fb8aa3b, v56
	v_exp_f32_e32 v99, v56
	v_cvt_pk_f16_f32 v58, v85, v86
	v_cvt_pk_f16_f32 v57, v62, v63
	v_cvt_pk_f16_f32 v56, v60, v61
	v_cvt_pk_f16_f32 v59, v87, v99
	ds_read_b128 v[60:63], v118 offset:36864
	s_waitcnt lgkmcnt(1)
	v_mfma_f32_16x16x32_f16 v[68:71], v[68:71], v[56:59], v[76:79]
	s_nop 2
	ds_read_b128 v[76:79], v118 offset:53760
	s_waitcnt lgkmcnt(0)
	v_mfma_f32_16x16x32_f16 v[72:75], v[76:79], v[56:59], v[72:75]
	ds_read_b128 v[76:79], v118 offset:62208
	v_mfma_f32_16x16x32_f16 v[60:63], v[60:63], v[56:59], v[80:83]
	s_waitcnt lgkmcnt(0)
; template <bool CL>
; __device__ __forceinline__ void natten_wave(const Params& p, int l, bool local, int b, int hh, int qrow0  ,
;                             int r, int ct, const f16* lK, const f16* lV) {
;     ...
;   for (int pr = 0; pr < 8; ++pr) {
;     f16x8 pf;
; #pragma unroll
;     for (int blk = 0; blk < 2; ++blk)
; #pragma unroll
;       for (int i = 0; i < 4; ++i) {
;         float e = __expf(sc[pr * 2 + blk][i] - mx);
;         sum += e;
;         pf[blk * 4 + i] = (f16)e;
;       }
;     int tk = pr * 32 + 8 * g;
; #pragma unroll
;     for (int nb = 0; nb < 4; ++nb) {
;       f16x8 vf;
;       if (CL) vf = *(const f16x8*)(lV + (nb * 16 + lq) * 264 + tk);
;       else vf = *(const f16x8*)(vtc + (size_t)(nb * 16 + lq) * CTXL + tk);
;       o[nb] = __builtin_amdgcn_mfma_f32_16x16x32_f16(vf, pf, o[nb], 0, 0, 0);
;     }
	v_mfma_f32_16x16x32_f16 v[56:59], v[76:79], v[56:59], v[64:67]
	s_nop 2
	v_add_f32_e32 v64, v85, v84
	v_add_f32_e32 v64, v86, v64
	v_add_f32_e32 v64, v87, v64
	v_add_f32_e32 v64, v99, v64
	v_sub_f32_e32 v52, v52, v119
	v_mul_f32_e32 v52, 0x3fb8aa3b, v52
	v_sub_f32_e32 v53, v53, v119
	v_sub_f32_e32 v48, v48, v119
	v_exp_f32_e32 v52, v52
	v_mul_f32_e32 v53, 0x3fb8aa3b, v53
	v_sub_f32_e32 v54, v54, v119
	v_mul_f32_e32 v48, 0x3fb8aa3b, v48
	v_exp_f32_e32 v53, v53
	v_mul_f32_e32 v54, 0x3fb8aa3b, v54
	v_sub_f32_e32 v55, v55, v119
	v_exp_f32_e32 v77, v48
	v_sub_f32_e32 v48, v49, v119
	v_exp_f32_e32 v54, v54
	v_mul_f32_e32 v55, 0x3fb8aa3b, v55
	v_mul_f32_e32 v48, 0x3fb8aa3b, v48
	v_exp_f32_e32 v55, v55
	v_exp_f32_e32 v78, v48
	v_sub_f32_e32 v48, v50, v119
	v_add_f32_e32 v64, v52, v64
	v_mul_f32_e32 v48, 0x3fb8aa3b, v48
	v_add_f32_e32 v64, v53, v64
	v_exp_f32_e32 v79, v48
	v_sub_f32_e32 v48, v51, v119
	v_add_f32_e32 v64, v54, v64
	v_mul_f32_e32 v48, 0x3fb8aa3b, v48
	v_add_f32_e32 v76, v55, v64
	v_exp_f32_e32 v80, v48
	v_cvt_pk_f16_f32 v49, v54, v55
	v_cvt_pk_f16_f32 v48, v52, v53
	ds_read_b128 v[52:55], v118 offset:36928
	v_cvt_pk_f16_f32 v51, v79, v80
	v_cvt_pk_f16_f32 v50, v77, v78
	ds_read_b128 v[64:67], v118 offset:53824
	s_waitcnt lgkmcnt(1)
	v_mfma_f32_16x16x32_f16 v[52:55], v[52:55], v[48:51], v[60:63]
	s_nop 2
	ds_read_b128 v[60:63], v118 offset:45376
	s_waitcnt lgkmcnt(0)
	v_mfma_f32_16x16x32_f16 v[60:63], v[60:63], v[48:51], v[68:71]
	s_nop 2
	ds_read_b128 v[68:71], v118 offset:62272
	v_mfma_f32_16x16x32_f16 v[64:67], v[64:67], v[48:51], v[72:75]
	s_waitcnt lgkmcnt(0)
	v_mfma_f32_16x16x32_f16 v[48:51], v[68:71], v[48:51], v[56:59]
	s_nop 2
	v_add_f32_e32 v56, v77, v76
	v_add_f32_e32 v56, v78, v56
	v_add_f32_e32 v56, v79, v56
	v_add_f32_e32 v56, v80, v56
	v_sub_f32_e32 v44, v44, v119
	v_mul_f32_e32 v44, 0x3fb8aa3b, v44
	v_sub_f32_e32 v45, v45, v119
	v_sub_f32_e32 v40, v40, v119
	v_exp_f32_e32 v44, v44
	v_mul_f32_e32 v45, 0x3fb8aa3b, v45
	v_sub_f32_e32 v46, v46, v119
	v_mul_f32_e32 v40, 0x3fb8aa3b, v40
	v_exp_f32_e32 v45, v45
	v_mul_f32_e32 v46, 0x3fb8aa3b, v46
	v_sub_f32_e32 v47, v47, v119
	v_exp_f32_e32 v69, v40
	v_sub_f32_e32 v40, v41, v119
	v_exp_f32_e32 v46, v46
	v_mul_f32_e32 v47, 0x3fb8aa3b, v47
	v_mul_f32_e32 v40, 0x3fb8aa3b, v40
	v_exp_f32_e32 v47, v47
	v_exp_f32_e32 v70, v40
	v_sub_f32_e32 v40, v42, v119
	v_add_f32_e32 v56, v44, v56
	v_mul_f32_e32 v40, 0x3fb8aa3b, v40
	v_add_f32_e32 v56, v45, v56
	v_exp_f32_e32 v71, v40
	v_sub_f32_e32 v40, v43, v119
	v_add_f32_e32 v56, v46, v56
	v_mul_f32_e32 v40, 0x3fb8aa3b, v40
	v_add_f32_e32 v68, v47, v56
	v_exp_f32_e32 v72, v40
	v_cvt_pk_f16_f32 v41, v46, v47
	v_cvt_pk_f16_f32 v40, v44, v45
	ds_read_b128 v[44:47], v118 offset:36992
	v_cvt_pk_f16_f32 v43, v71, v72
	v_cvt_pk_f16_f32 v42, v69, v70
	ds_read_b128 v[56:59], v118 offset:53888
	s_waitcnt lgkmcnt(1)
	v_mfma_f32_16x16x32_f16 v[44:47], v[44:47], v[40:43], v[52:55]
	s_nop 2
	ds_read_b128 v[52:55], v118 offset:45440
	s_waitcnt lgkmcnt(0)
	v_mfma_f32_16x16x32_f16 v[52:55], v[52:55], v[40:43], v[60:63]
	s_nop 2
	ds_read_b128 v[60:63], v118 offset:62336
	v_mfma_f32_16x16x32_f16 v[56:59], v[56:59], v[40:43], v[64:67]
	s_waitcnt lgkmcnt(0)
	v_mfma_f32_16x16x32_f16 v[40:43], v[60:63], v[40:43], v[48:51]
	s_nop 2
	v_add_f32_e32 v48, v69, v68
	v_add_f32_e32 v48, v70, v48
	v_add_f32_e32 v48, v71, v48
	v_add_f32_e32 v48, v72, v48
	v_sub_f32_e32 v36, v36, v119
	v_mul_f32_e32 v36, 0x3fb8aa3b, v36
	v_sub_f32_e32 v37, v37, v119
	v_sub_f32_e32 v32, v32, v119
	v_exp_f32_e32 v36, v36
	v_mul_f32_e32 v37, 0x3fb8aa3b, v37
	v_sub_f32_e32 v38, v38, v119
	v_mul_f32_e32 v32, 0x3fb8aa3b, v32
	v_exp_f32_e32 v37, v37
	v_mul_f32_e32 v38, 0x3fb8aa3b, v38
	v_sub_f32_e32 v39, v39, v119
	v_exp_f32_e32 v61, v32
	v_sub_f32_e32 v32, v33, v119
	v_exp_f32_e32 v38, v38
	v_mul_f32_e32 v39, 0x3fb8aa3b, v39
	v_mul_f32_e32 v32, 0x3fb8aa3b, v32
	v_exp_f32_e32 v39, v39
	v_exp_f32_e32 v62, v32
	v_sub_f32_e32 v32, v34, v119
	v_add_f32_e32 v48, v36, v48
	v_mul_f32_e32 v32, 0x3fb8aa3b, v32
	v_add_f32_e32 v48, v37, v48
	v_exp_f32_e32 v63, v32
	v_sub_f32_e32 v32, v35, v119
	v_add_f32_e32 v48, v38, v48
	v_mul_f32_e32 v32, 0x3fb8aa3b, v32
	v_add_f32_e32 v60, v39, v48
	v_exp_f32_e32 v64, v32
	v_cvt_pk_f16_f32 v33, v38, v39
	v_cvt_pk_f16_f32 v32, v36, v37
	ds_read_b128 v[36:39], v118 offset:37056
	v_cvt_pk_f16_f32 v35, v63, v64
	v_cvt_pk_f16_f32 v34, v61, v62
	ds_read_b128 v[48:51], v118 offset:53952
	s_waitcnt lgkmcnt(1)
	v_mfma_f32_16x16x32_f16 v[36:39], v[36:39], v[32:35], v[44:47]
	s_nop 2
	ds_read_b128 v[44:47], v118 offset:45504
	s_waitcnt lgkmcnt(0)
	v_mfma_f32_16x16x32_f16 v[44:47], v[44:47], v[32:35], v[52:55]
	s_nop 2
	ds_read_b128 v[52:55], v118 offset:62400
	v_mfma_f32_16x16x32_f16 v[48:51], v[48:51], v[32:35], v[56:59]
	s_waitcnt lgkmcnt(0)
	v_mfma_f32_16x16x32_f16 v[32:35], v[52:55], v[32:35], v[40:43]
	s_nop 2
	v_add_f32_e32 v40, v61, v60
	v_add_f32_e32 v40, v62, v40
	v_add_f32_e32 v40, v63, v40
	v_add_f32_e32 v40, v64, v40
	v_sub_f32_e32 v28, v28, v119
	v_mul_f32_e32 v28, 0x3fb8aa3b, v28
	v_sub_f32_e32 v29, v29, v119
	v_sub_f32_e32 v24, v24, v119
	v_exp_f32_e32 v28, v28
	v_mul_f32_e32 v29, 0x3fb8aa3b, v29
	v_sub_f32_e32 v30, v30, v119
	v_mul_f32_e32 v24, 0x3fb8aa3b, v24
	v_exp_f32_e32 v29, v29
	v_mul_f32_e32 v30, 0x3fb8aa3b, v30
	v_sub_f32_e32 v31, v31, v119
	v_exp_f32_e32 v53, v24
	v_sub_f32_e32 v24, v25, v119
	v_exp_f32_e32 v30, v30
	v_mul_f32_e32 v31, 0x3fb8aa3b, v31
	v_mul_f32_e32 v24, 0x3fb8aa3b, v24
	v_exp_f32_e32 v31, v31
	v_exp_f32_e32 v54, v24
	v_sub_f32_e32 v24, v26, v119
	v_add_f32_e32 v40, v28, v40
	v_mul_f32_e32 v24, 0x3fb8aa3b, v24
	v_add_f32_e32 v40, v29, v40
	v_exp_f32_e32 v55, v24
	v_sub_f32_e32 v24, v27, v119
	v_add_f32_e32 v40, v30, v40
	v_mul_f32_e32 v24, 0x3fb8aa3b, v24
	v_add_f32_e32 v52, v31, v40
	v_exp_f32_e32 v56, v24
	v_cvt_pk_f16_f32 v25, v30, v31
	v_cvt_pk_f16_f32 v24, v28, v29
	ds_read_b128 v[28:31], v118 offset:37120
	v_cvt_pk_f16_f32 v27, v55, v56
	v_cvt_pk_f16_f32 v26, v53, v54
	ds_read_b128 v[40:43], v118 offset:54016
	s_waitcnt lgkmcnt(1)
; template <bool CL>
; __device__ __forceinline__ void natten_wave(const Params& p, int l, bool local, int b, int hh, int qrow0  ,
;                             int r, int ct, const f16* lK, const f16* lV) {
;     ...
;   for (int pr = 0; pr < 8; ++pr) {
;     f16x8 pf;
; #pragma unroll
;     for (int blk = 0; blk < 2; ++blk)
; #pragma unroll
;       for (int i = 0; i < 4; ++i) {
;         float e = __expf(sc[pr * 2 + blk][i] - mx);
;         sum += e;
;         pf[blk * 4 + i] = (f16)e;
;       }
;     int tk = pr * 32 + 8 * g;
; #pragma unroll
;     for (int nb = 0; nb < 4; ++nb) {
;       f16x8 vf;
;       if (CL) vf = *(const f16x8*)(lV + (nb * 16 + lq) * 264 + tk);
;       else vf = *(const f16x8*)(vtc + (size_t)(nb * 16 + lq) * CTXL + tk);
;       o[nb] = __builtin_amdgcn_mfma_f32_16x16x32_f16(vf, pf, o[nb], 0, 0, 0);
;     }
	v_mfma_f32_16x16x32_f16 v[28:31], v[28:31], v[24:27], v[36:39]
	s_nop 2
	ds_read_b128 v[36:39], v118 offset:45568
	s_waitcnt lgkmcnt(0)
	v_mfma_f32_16x16x32_f16 v[36:39], v[36:39], v[24:27], v[44:47]
	s_nop 2
	ds_read_b128 v[44:47], v118 offset:62464
	v_mfma_f32_16x16x32_f16 v[40:43], v[40:43], v[24:27], v[48:51]
	s_waitcnt lgkmcnt(0)
	v_mfma_f32_16x16x32_f16 v[24:27], v[44:47], v[24:27], v[32:35]
	s_nop 2
	v_add_f32_e32 v32, v53, v52
	v_add_f32_e32 v32, v54, v32
	v_add_f32_e32 v32, v55, v32
	v_add_f32_e32 v32, v56, v32
	v_sub_f32_e32 v20, v20, v119
	v_mul_f32_e32 v20, 0x3fb8aa3b, v20
	v_sub_f32_e32 v21, v21, v119
	v_sub_f32_e32 v16, v16, v119
	v_exp_f32_e32 v20, v20
	v_mul_f32_e32 v21, 0x3fb8aa3b, v21
	v_sub_f32_e32 v22, v22, v119
	v_mul_f32_e32 v16, 0x3fb8aa3b, v16
	v_exp_f32_e32 v21, v21
	v_mul_f32_e32 v22, 0x3fb8aa3b, v22
	v_sub_f32_e32 v23, v23, v119
	v_exp_f32_e32 v45, v16
	v_sub_f32_e32 v16, v17, v119
	v_exp_f32_e32 v22, v22
	v_mul_f32_e32 v23, 0x3fb8aa3b, v23
	v_mul_f32_e32 v16, 0x3fb8aa3b, v16
	v_exp_f32_e32 v23, v23
	v_exp_f32_e32 v46, v16
	v_sub_f32_e32 v16, v18, v119
	v_add_f32_e32 v32, v20, v32
	v_mul_f32_e32 v16, 0x3fb8aa3b, v16
	v_add_f32_e32 v32, v21, v32
	v_exp_f32_e32 v47, v16
	v_sub_f32_e32 v16, v19, v119
	v_add_f32_e32 v32, v22, v32
	v_mul_f32_e32 v16, 0x3fb8aa3b, v16
	v_add_f32_e32 v44, v23, v32
	v_exp_f32_e32 v48, v16
	v_cvt_pk_f16_f32 v17, v22, v23
	v_cvt_pk_f16_f32 v16, v20, v21
	ds_read_b128 v[20:23], v118 offset:37184
	v_cvt_pk_f16_f32 v19, v47, v48
	v_cvt_pk_f16_f32 v18, v45, v46
	ds_read_b128 v[32:35], v118 offset:54080
	s_waitcnt lgkmcnt(1)
	v_mfma_f32_16x16x32_f16 v[20:23], v[20:23], v[16:19], v[28:31]
	s_nop 2
	ds_read_b128 v[28:31], v118 offset:45632
	s_waitcnt lgkmcnt(0)
	v_mfma_f32_16x16x32_f16 v[28:31], v[28:31], v[16:19], v[36:39]
	s_nop 2
	ds_read_b128 v[36:39], v118 offset:62528
	v_mfma_f32_16x16x32_f16 v[32:35], v[32:35], v[16:19], v[40:43]
	s_waitcnt lgkmcnt(0)
	v_mfma_f32_16x16x32_f16 v[16:19], v[36:39], v[16:19], v[24:27]
	s_nop 2
	v_add_f32_e32 v24, v45, v44
	v_add_f32_e32 v24, v46, v24
	v_add_f32_e32 v24, v47, v24
	v_add_f32_e32 v24, v48, v24
	v_sub_f32_e32 v12, v12, v119
	v_mul_f32_e32 v12, 0x3fb8aa3b, v12
	v_sub_f32_e32 v13, v13, v119
	v_sub_f32_e32 v8, v8, v119
	v_exp_f32_e32 v12, v12
	v_mul_f32_e32 v13, 0x3fb8aa3b, v13
	v_sub_f32_e32 v14, v14, v119
	v_mul_f32_e32 v8, 0x3fb8aa3b, v8
	v_exp_f32_e32 v13, v13
	v_mul_f32_e32 v14, 0x3fb8aa3b, v14
	v_sub_f32_e32 v15, v15, v119
	v_exp_f32_e32 v37, v8
	v_sub_f32_e32 v8, v9, v119
	v_exp_f32_e32 v14, v14
	v_mul_f32_e32 v15, 0x3fb8aa3b, v15
	v_mul_f32_e32 v8, 0x3fb8aa3b, v8
	v_exp_f32_e32 v15, v15
	v_exp_f32_e32 v38, v8
	v_sub_f32_e32 v8, v10, v119
	v_add_f32_e32 v24, v12, v24
	v_mul_f32_e32 v8, 0x3fb8aa3b, v8
	v_add_f32_e32 v24, v13, v24
	v_exp_f32_e32 v39, v8
	v_sub_f32_e32 v8, v11, v119
	v_add_f32_e32 v24, v14, v24
	v_mul_f32_e32 v8, 0x3fb8aa3b, v8
	v_add_f32_e32 v36, v15, v24
	v_exp_f32_e32 v40, v8
	v_cvt_pk_f16_f32 v9, v14, v15
	v_cvt_pk_f16_f32 v8, v12, v13
	ds_read_b128 v[12:15], v118 offset:37248
	v_cvt_pk_f16_f32 v11, v39, v40
	v_cvt_pk_f16_f32 v10, v37, v38
	ds_read_b128 v[24:27], v118 offset:54144
	s_waitcnt lgkmcnt(1)
	v_mfma_f32_16x16x32_f16 v[12:15], v[12:15], v[8:11], v[20:23]
	s_nop 2
	ds_read_b128 v[20:23], v118 offset:45696
	s_waitcnt lgkmcnt(0)
	v_mfma_f32_16x16x32_f16 v[20:23], v[20:23], v[8:11], v[28:31]
	s_nop 2
	ds_read_b128 v[28:31], v118 offset:62592
	v_mfma_f32_16x16x32_f16 v[24:27], v[24:27], v[8:11], v[32:35]
	s_waitcnt lgkmcnt(0)
; template <bool CL>
; __device__ __forceinline__ void natten_wave(const Params& p, int l, bool local, int b, int hh, int qrow0  ,
;                             int r, int ct, const f16* lK, const f16* lV) {
;     ...
;   for (int pr = 0; pr < 8; ++pr) {
;     f16x8 pf;
; #pragma unroll
;     for (int blk = 0; blk < 2; ++blk)
; #pragma unroll
;       for (int i = 0; i < 4; ++i) {
;         float e = __expf(sc[pr * 2 + blk][i] - mx);
;         sum += e;
;         pf[blk * 4 + i] = (f16)e;
;       }
;     int tk = pr * 32 + 8 * g;
; #pragma unroll
;     for (int nb = 0; nb < 4; ++nb) {
;       f16x8 vf;
;       if (CL) vf = *(const f16x8*)(lV + (nb * 16 + lq) * 264 + tk);
;       else vf = *(const f16x8*)(vtc + (size_t)(nb * 16 + lq) * CTXL + tk);
;       o[nb] = __builtin_amdgcn_mfma_f32_16x16x32_f16(vf, pf, o[nb], 0, 0, 0);
;     }
;     if (CL) __builtin_amdgcn_sched_barrier(0);
;   }
;   sum += __shfl_xor(sum, 16, 64);
;   sum += __shfl_xor(sum, 32, 64);
;   float inv = 1.0f / sum;
; #pragma unroll
;   for (int nb = 0; nb < 4; ++nb) {
;     f16x4 ov;
;     ov[0] = (f16)(o[nb][0] * inv);
;     ov[1] = (f16)(o[nb][1] * inv);
;     ov[2] = (f16)(o[nb][2] * inv);
;     ov[3] = (f16)(o[nb][3] * inv);
;     *(f16x4*)(br + (size_t)(qrow0 + lq) * DM + 640 + hh * HD + nb * 16 + 4 * g) = ov;
;   }
; __device__ __forceinline__ void phase_natten(const Params& p, int l, f16* smem) {
;     ...
;     for (int r = sub; r < GR; r += nblk) natten_wave<true>(p, l, true, b, hh, b * TL + r * GW + wave * 16, r, wave, lK, lV);
	v_mfma_f32_16x16x32_f16 v[8:11], v[28:31], v[8:11], v[16:19]
	s_nop 2
	v_add_f32_e32 v16, v37, v36
	v_add_f32_e32 v16, v38, v16
	v_add_f32_e32 v16, v39, v16
	v_add_f32_e32 v16, v40, v16
	v_sub_f32_e32 v4, v4, v119
	v_mul_f32_e32 v4, 0x3fb8aa3b, v4
	v_sub_f32_e32 v5, v5, v119
	v_sub_f32_e32 v0, v0, v119
	v_exp_f32_e32 v4, v4
	v_mul_f32_e32 v5, 0x3fb8aa3b, v5
	v_sub_f32_e32 v6, v6, v119
	v_mul_f32_e32 v0, 0x3fb8aa3b, v0
	v_exp_f32_e32 v5, v5
	v_mul_f32_e32 v6, 0x3fb8aa3b, v6
	v_sub_f32_e32 v7, v7, v119
	v_exp_f32_e32 v29, v0
	v_sub_f32_e32 v0, v1, v119
	v_exp_f32_e32 v6, v6
	v_mul_f32_e32 v7, 0x3fb8aa3b, v7
	v_mul_f32_e32 v0, 0x3fb8aa3b, v0
	v_exp_f32_e32 v7, v7
	v_exp_f32_e32 v30, v0
	v_sub_f32_e32 v0, v2, v119
	v_add_f32_e32 v16, v4, v16
	v_mul_f32_e32 v0, 0x3fb8aa3b, v0
	v_add_f32_e32 v16, v5, v16
	v_exp_f32_e32 v31, v0
	v_sub_f32_e32 v0, v3, v119
	v_add_f32_e32 v16, v6, v16
	v_mul_f32_e32 v0, 0x3fb8aa3b, v0
	v_add_f32_e32 v28, v7, v16
	v_exp_f32_e32 v32, v0
	v_cvt_pk_f16_f32 v1, v6, v7
	v_cvt_pk_f16_f32 v0, v4, v5
	ds_read_b128 v[4:7], v118 offset:37312
	v_cvt_pk_f16_f32 v3, v31, v32
	v_cvt_pk_f16_f32 v2, v29, v30
	ds_read_b128 v[16:19], v118 offset:54208
	s_waitcnt lgkmcnt(1)
	v_mfma_f32_16x16x32_f16 v[4:7], v[4:7], v[0:3], v[12:15]
	s_nop 2
	ds_read_b128 v[12:15], v118 offset:45760
	s_waitcnt lgkmcnt(0)
	v_mfma_f32_16x16x32_f16 v[12:15], v[12:15], v[0:3], v[20:23]
	s_nop 2
	ds_read_b128 v[20:23], v118 offset:62656
	v_mfma_f32_16x16x32_f16 v[16:19], v[16:19], v[0:3], v[24:27]
	s_waitcnt lgkmcnt(0)
	v_mfma_f32_16x16x32_f16 v[0:3], v[20:23], v[0:3], v[8:11]
	s_nop 2
	v_add_f32_e32 v8, v29, v28
	v_add_f32_e32 v8, v30, v8
	v_add_f32_e32 v8, v31, v8
	v_add_f32_e32 v8, v32, v8
	ds_bpermute_b32 v9, v109, v8
	v_mov_b32_e32 v107, v165
	s_add_i32 s38, s38, s33
	s_sub_i32 s40, s40, s33
	s_cmpk_lt_i32 s38, 0x100
	s_waitcnt lgkmcnt(0)
	v_add_f32_e32 v8, v8, v9
	ds_bpermute_b32 v9, v110, v8
	s_waitcnt lgkmcnt(0)
	v_add_f32_e32 v8, v8, v9
	v_readlane_b32 s6, v241, 36
	v_rcp_f32_e32 v10, v8
	s_nop 0
	v_mul_f32_e32 v9, 1.0, v10
	v_mov_b32_e32 v8, v9
	v_lshlrev_b64 v[10:11], 11, v[96:97]
	v_lshl_add_u64 v[10:11], v[88:89], 0, v[10:11]
	v_fma_mixlo_f16 v9, v4, v8, 0
	v_mov_b32_e32 v4, v5
	v_mov_b32_e32 v5, v6
	v_lshl_add_u64 v[10:11], s[8:9], 1, v[10:11]
	v_pk_mul_f32 v[4:5], v[4:5], v[8:9] op_sel_hi:[1,0]
	v_lshl_add_u64 v[10:11], v[10:11], 0, v[106:107]
	v_cvt_pk_f16_f32 v5, v4, v5
	v_fma_mixlo_f16 v6, v7, v8, 0
	v_pack_b32_f16 v4, v9, v5
	v_alignbit_b32 v5, v6, v5, 16
	v_add_co_u32_e32 v6, vcc, s70, v10
	v_lshl_add_u64 v[20:21], v[10:11], 0, s[52:53]
	s_nop 0
	v_addc_co_u32_e32 v7, vcc, 0, v11, vcc
	global_store_dwordx2 v[6:7], v[4:5], off offset:1280
	v_mov_b32_e32 v4, v13
	v_mov_b32_e32 v5, v14
	v_pk_mul_f32 v[4:5], v[4:5], v[8:9] op_sel_hi:[1,0]
	v_fma_mixlo_f16 v6, v12, v8, 0
	v_cvt_pk_f16_f32 v5, v4, v5
	v_pack_b32_f16 v4, v6, v5
	v_fma_mixlo_f16 v6, v15, v8, 0
	v_alignbit_b32 v5, v6, v5, 16
	global_store_dwordx2 v[20:21], v[4:5], off offset:32
	v_mov_b32_e32 v4, v17
	v_mov_b32_e32 v5, v18
	v_pk_mul_f32 v[4:5], v[4:5], v[8:9] op_sel_hi:[1,0]
	v_fma_mixlo_f16 v6, v16, v8, 0
	v_cvt_pk_f16_f32 v5, v4, v5
	v_pack_b32_f16 v4, v6, v5
	v_fma_mixlo_f16 v6, v19, v8, 0
	v_alignbit_b32 v5, v6, v5, 16
	global_store_dwordx2 v[20:21], v[4:5], off offset:64
	v_fma_mixlo_f16 v4, v0, v8, 0
	v_mov_b32_e32 v0, v1
	v_mov_b32_e32 v1, v2
	v_pk_mul_f32 v[0:1], v[0:1], v[8:9] op_sel_hi:[1,0]
	v_fma_mixlo_f16 v2, v3, v8, 0
	v_cvt_pk_f16_f32 v1, v0, v1
	v_pack_b32_f16 v0, v4, v1
	v_alignbit_b32 v1, v2, v1, 16
	v_add_u32_e32 v96, s6, v96
	global_store_dwordx2 v[20:21], v[0:1], off offset:96
	s_cbranch_scc0 .LBB0_685

; template <bool CL>
; __device__ __forceinline__ void natten_wave(const Params& p, int l, bool local, int b, int hh, int qrow0  ,
;                             int r, int ct, const f16* lK, const f16* lV) {
;     ...
;   if (local) {
;     rs = r - 4;
;     rs = rs < 0 ? 0 : (rs > GR - 8 ? GR - 8 : rs);
;     col0 = ct == 0 ? 0 : (ct == 1 ? 8 : (ct == 2 ? 24 : 32));
;     const int c = ct * 16 + lq;
;     int cs = c - 8;
;     cs = cs < 0 ? 0 : (cs > GW - 16 ? GW - 16 : cs);
;     const float* rpb = p.in[I_RPB] + ((size_t)l * NH + hh) * 15 * 31;
; #pragma unroll
;     for (int kr = 0; kr < 8; ++kr) {
; #pragma unroll
;       for (int blk = 0; blk < 2; ++blk) {
;         int tk = (rs + kr) * GW + col0 + kperm + 4 * blk;
;         const f16* kp = proj + (size_t)(b * TL + tk) * PJ + RD + hh * HD + g * 16;
;         f16x8 k0 = *(const f16x8*)(kp);
;         f16x8 k1 = *(const f16x8*)(kp + 8);
;         f32x4 a = f32x4{0.f, 0.f, 0.f, 0.f};
;         a = __builtin_amdgcn_mfma_f32_16x16x32_f16(k0, qf[0], a, 0, 0, 0);
;         a = __builtin_amdgcn_mfma_f32_16x16x32_f16(k1, qf[1], a, 0, 0, 0);
;         const float* bp = rpb + (rs + kr - r + 7) * 31;
; #pragma unroll
;         for (int i = 0; i < 4; ++i) {
;           int kc = col0 + 8 * g + 4 * blk + i;
;           bool valid = (kc >= cs) && (kc <= cs + 15);
;           int bi = kc - c + 15;
;           bi = bi < 0 ? 0 : (bi > 30 ? 30 : bi);
;           float s = valid ? a[i] + bp[bi] : -1e30f;
;           a[i] = s;
;           mx = fmaxf(mx, s);
;         }
;         sl[kr][blk] = a;
;       }
;     }
.LBB0_557:
	v_med3_i32 v10, s38, 4, v188
	v_lshlrev_b32_e32 v4, 6, v10
	v_add_u32_e32 v11, s12, v114
	v_add_u32_e32 v68, 0xffffff00, v4
	v_add_u32_e32 v18, v11, v68
	v_mul_hi_i32_i24_e32 v5, 0x1440, v18
	v_mul_i32_i24_e32 v4, 0x1440, v18
	v_lshl_add_u64 v[8:9], v[90:91], 0, v[4:5]
	global_load_dwordx4 v[4:7], v[8:9], off offset:768
	global_load_dwordx4 v[12:15], v[8:9], off offset:784
	v_add_u32_e32 v8, s40, v10
	v_readfirstlane_b32 s41, v10
	v_mul_lo_u32 v10, v8, 31
	v_add_u32_e32 v8, 0xffffff27, v10
	v_ashrrev_i32_e32 v9, 31, v8
	v_add_u32_e32 v107, s12, v115
	v_lshlrev_b64 v[8:9], 2, v[8:9]
	v_cmp_ge_u32_e32 vcc, v107, v113
	v_cmp_le_u32_e64 s[6:7], v107, v116
	v_lshl_add_u64 v[26:27], v[92:93], 0, v[8:9]
	v_sub_u32_e32 v8, v107, v111
	s_and_b64 s[10:11], vcc, s[6:7]
	v_mov_b32_e32 v69, 0xf149f2ca
	v_med3_i32 v8, v8, -15, 15
	v_mov_b32_e32 v70, 0xf149f2ca
	s_waitcnt vmcnt(1)
	v_mfma_f32_16x16x32_f16 v[4:7], v[4:7], v[64:67], 0
	s_waitcnt vmcnt(0)
	v_mfma_f32_16x16x32_f16 v[4:7], v[12:15], v[0:3], v[4:7]
	s_nop 7
	v_mov_b32_e32 v244, v4
	v_mov_b32_e32 v245, v5
	v_mov_b32_e32 v246, v6
	v_mov_b32_e32 v247, v7
	v_ashrrev_i32_e32 v9, 31, v8
	v_lshl_add_u64 v[12:13], v[8:9], 2, v[26:27]
	global_load_dword v248, v[12:13], off offset:928
	s_nop 4
	v_or_b32_e32 v4, 1, v107
	v_cmp_ge_u32_e32 vcc, v4, v113
	v_cmp_lt_u32_e64 s[6:7], v107, v116
	v_sub_u32_e32 v4, v4, v111
	s_and_b64 s[12:13], vcc, s[6:7]
	v_med3_i32 v12, v4, -15, 15
	v_ashrrev_i32_e32 v13, 31, v12
	v_lshl_add_u64 v[14:15], v[12:13], 2, v[26:27]
	global_load_dword v249, v[14:15], off offset:928
	v_or_b32_e32 v4, 2, v107
	v_cmp_ge_u32_e32 vcc, v4, v113
	v_cmp_le_u32_e64 s[6:7], v4, v116
	v_sub_u32_e32 v4, v4, v111
	s_and_b64 s[14:15], vcc, s[6:7]
	v_mov_b32_e32 v71, 0xf149f2ca
	v_med3_i32 v14, v4, -15, 15
	v_mov_b32_e32 v72, 0xf149f2ca
	v_ashrrev_i32_e32 v15, 31, v14
	v_lshl_add_u64 v[4:5], v[14:15], 2, v[26:27]
	global_load_dword v250, v[4:5], off offset:928
	v_or_b32_e32 v4, 3, v107
	v_cmp_ge_u32_e32 vcc, v4, v113
	v_cmp_le_u32_e64 s[6:7], v4, v116
	v_sub_u32_e32 v4, v4, v111
	s_and_b64 s[16:17], vcc, s[6:7]
	v_med3_i32 v16, v4, -15, 15
	v_ashrrev_i32_e32 v17, 31, v16
	v_lshl_add_u64 v[4:5], v[16:17], 2, v[26:27]
	global_load_dword v251, v[4:5], off offset:928
	s_waitcnt vmcnt(0)
	v_add_f32_e32 v248, v244, v248
	v_cndmask_b32_e64 v70, v70, v248, s[10:11]
	v_add_f32_e32 v249, v245, v249
	v_cndmask_b32_e64 v69, v69, v249, s[12:13]
	v_add_f32_e32 v250, v246, v250
	v_cndmask_b32_e64 v72, v72, v250, s[14:15]
	v_add_f32_e32 v251, v247, v251
	v_cndmask_b32_e64 v71, v71, v251, s[16:17]
	v_or_b32_e32 v4, 4, v18
	v_mad_i64_i32 v[18:19], s[6:7], v4, s22, v[90:91]
	global_load_dwordx4 v[4:7], v[18:19], off offset:768
	s_nop 0
	global_load_dwordx4 v[18:21], v[18:19], off offset:784
	v_or_b32_e32 v9, 4, v107
	v_cmp_ge_u32_e32 vcc, v9, v113
	v_cmp_le_u32_e64 s[6:7], v9, v116
	v_sub_u32_e32 v9, v9, v111
	s_and_b64 s[18:19], vcc, s[6:7]
	v_mov_b32_e32 v73, 0xf149f2ca
	v_mov_b32_e32 v74, 0xf149f2ca
	s_waitcnt vmcnt(1)
	v_mfma_f32_16x16x32_f16 v[4:7], v[4:7], v[64:67], 0
	s_waitcnt vmcnt(0)
	v_mfma_f32_16x16x32_f16 v[4:7], v[18:21], v[0:3], v[4:7]
	v_med3_i32 v18, v9, -15, 15
	s_nop 7
	v_mov_b32_e32 v244, v4
	v_mov_b32_e32 v245, v5
	v_mov_b32_e32 v246, v6
	v_mov_b32_e32 v247, v7
	v_ashrrev_i32_e32 v19, 31, v18
	v_lshl_add_u64 v[20:21], v[18:19], 2, v[26:27]
	global_load_dword v248, v[20:21], off offset:928
	s_nop 3
	v_or_b32_e32 v4, 5, v107
	v_cmp_ge_u32_e32 vcc, v4, v113
	v_cmp_le_u32_e64 s[6:7], v4, v116
	v_sub_u32_e32 v4, v4, v111
	s_and_b64 s[20:21], vcc, s[6:7]
	v_med3_i32 v20, v4, -15, 15
	v_ashrrev_i32_e32 v21, 31, v20
	v_lshl_add_u64 v[22:23], v[20:21], 2, v[26:27]
	global_load_dword v249, v[22:23], off offset:928
	v_or_b32_e32 v4, 6, v107
	v_cmp_ge_u32_e32 vcc, v4, v113
	v_cmp_le_u32_e64 s[6:7], v4, v116
	v_sub_u32_e32 v4, v4, v111
	s_and_b64 s[34:35], vcc, s[6:7]
	v_mov_b32_e32 v75, 0xf149f2ca
	v_med3_i32 v22, v4, -15, 15
	v_mov_b32_e32 v76, 0xf149f2ca
	v_ashrrev_i32_e32 v23, 31, v22
	v_lshl_add_u64 v[4:5], v[22:23], 2, v[26:27]
	global_load_dword v250, v[4:5], off offset:928
	v_or_b32_e32 v4, 7, v107
	v_cmp_ge_u32_e32 vcc, v4, v113
	v_cmp_le_u32_e64 s[6:7], v107, v112
	v_sub_u32_e32 v4, v4, v111
	s_and_b64 s[6:7], vcc, s[6:7]
	v_med3_i32 v24, v4, -15, 15
	v_ashrrev_i32_e32 v25, 31, v24
	v_lshl_add_u64 v[4:5], v[24:25], 2, v[26:27]
	global_load_dword v251, v[4:5], off offset:928
	s_waitcnt vmcnt(0)
	v_add_f32_e32 v248, v244, v248
	v_cndmask_b32_e64 v74, v74, v248, s[18:19]
	v_add_f32_e32 v249, v245, v249
	v_cndmask_b32_e64 v73, v73, v249, s[20:21]
	v_add_f32_e32 v250, v246, v250
	v_cndmask_b32_e64 v76, v76, v250, s[34:35]
	v_add_f32_e32 v251, v247, v251
	v_cndmask_b32_e64 v75, v75, v251, s[6:7]
	s_lshl_b32 s41, s41, 6
	s_add_i32 s48, s41, 0xffffff40
	v_add_u32_e32 v19, s48, v11
	v_mul_hi_i32_i24_e32 v5, 0x1440, v19
	v_mul_i32_i24_e32 v4, 0x1440, v19
	v_lshl_add_u64 v[26:27], v[90:91], 0, v[4:5]
	global_load_dwordx4 v[4:7], v[26:27], off offset:768
	global_load_dwordx4 v[28:31], v[26:27], off offset:784
	v_add_u32_e32 v26, 0xffffff46, v10
	v_ashrrev_i32_e32 v27, 31, v26
	v_lshlrev_b64 v[26:27], 2, v[26:27]
	v_lshl_add_u64 v[26:27], v[92:93], 0, v[26:27]
	v_mov_b32_e32 v160, 0xf149f2ca
	v_mov_b32_e32 v161, 0xf149f2ca
	s_waitcnt vmcnt(1)
	v_mfma_f32_16x16x32_f16 v[4:7], v[4:7], v[64:67], 0
	s_waitcnt vmcnt(0)
; template <bool CL>
; __device__ __forceinline__ void natten_wave(const Params& p, int l, bool local, int b, int hh, int qrow0  ,
;                             int r, int ct, const f16* lK, const f16* lV) {
;     ...
; #pragma unroll
;     for (int kr = 0; kr < 8; ++kr) {
; #pragma unroll
;       for (int blk = 0; blk < 2; ++blk) {
;         int tk = (rs + kr) * GW + col0 + kperm + 4 * blk;
;         const f16* kp = proj + (size_t)(b * TL + tk) * PJ + RD + hh * HD + g * 16;
;         f16x8 k0 = *(const f16x8*)(kp);
;         f16x8 k1 = *(const f16x8*)(kp + 8);
;         f32x4 a = f32x4{0.f, 0.f, 0.f, 0.f};
;         a = __builtin_amdgcn_mfma_f32_16x16x32_f16(k0, qf[0], a, 0, 0, 0);
;         a = __builtin_amdgcn_mfma_f32_16x16x32_f16(k1, qf[1], a, 0, 0, 0);
;         const float* bp = rpb + (rs + kr - r + 7) * 31;
; #pragma unroll
;         for (int i = 0; i < 4; ++i) {
;           int kc = col0 + 8 * g + 4 * blk + i;
;           bool valid = (kc >= cs) && (kc <= cs + 15);
;           int bi = kc - c + 15;
;           bi = bi < 0 ? 0 : (bi > 30 ? 30 : bi);
;           float s = valid ? a[i] + bp[bi] : -1e30f;
;           a[i] = s;
;           mx = fmaxf(mx, s);
;         }
;         sl[kr][blk] = a;
;       }
;     }
	v_mfma_f32_16x16x32_f16 v[4:7], v[28:31], v[0:3], v[4:7]
	s_nop 7
	v_mov_b32_e32 v244, v4
	v_mov_b32_e32 v245, v5
	v_mov_b32_e32 v246, v6
	v_mov_b32_e32 v247, v7
	v_ashrrev_i32_e32 v9, 31, v8
	v_lshl_add_u64 v[28:29], v[8:9], 2, v[26:27]
	global_load_dword v248, v[28:29], off offset:928
	v_ashrrev_i32_e32 v13, 31, v12
	v_lshl_add_u64 v[28:29], v[12:13], 2, v[26:27]
	global_load_dword v249, v[28:29], off offset:928
	v_mov_b32_e32 v162, 0xf149f2ca
	v_mov_b32_e32 v163, 0xf149f2ca
	v_ashrrev_i32_e32 v15, 31, v14
	v_lshl_add_u64 v[4:5], v[14:15], 2, v[26:27]
	global_load_dword v250, v[4:5], off offset:928
	v_ashrrev_i32_e32 v17, 31, v16
	v_lshl_add_u64 v[4:5], v[16:17], 2, v[26:27]
	global_load_dword v251, v[4:5], off offset:928
	s_waitcnt vmcnt(0)
	v_add_f32_e32 v248, v244, v248
	v_cndmask_b32_e64 v161, v161, v248, s[10:11]
	v_add_f32_e32 v249, v245, v249
	v_cndmask_b32_e64 v160, v160, v249, s[12:13]
	v_add_f32_e32 v250, v246, v250
	v_cndmask_b32_e64 v163, v163, v250, s[14:15]
	v_add_f32_e32 v251, v247, v251
	v_cndmask_b32_e64 v162, v162, v251, s[16:17]
	v_or_b32_e32 v4, 4, v19
	v_mad_i64_i32 v[28:29], s[24:25], v4, s22, v[90:91]
	global_load_dwordx4 v[4:7], v[28:29], off offset:768
	s_nop 0
	global_load_dwordx4 v[28:31], v[28:29], off offset:784
	v_mov_b32_e32 v166, 0xf149f2ca
	v_mov_b32_e32 v167, 0xf149f2ca
	s_waitcnt vmcnt(1)
	v_mfma_f32_16x16x32_f16 v[4:7], v[4:7], v[64:67], 0
	s_waitcnt vmcnt(0)
	v_mfma_f32_16x16x32_f16 v[4:7], v[28:31], v[0:3], v[4:7]
	s_nop 7
	v_mov_b32_e32 v244, v4
	v_mov_b32_e32 v245, v5
	v_mov_b32_e32 v246, v6
	v_mov_b32_e32 v247, v7
	v_ashrrev_i32_e32 v19, 31, v18
	v_lshl_add_u64 v[28:29], v[18:19], 2, v[26:27]
	global_load_dword v248, v[28:29], off offset:928
	v_ashrrev_i32_e32 v21, 31, v20
	v_lshl_add_u64 v[28:29], v[20:21], 2, v[26:27]
	global_load_dword v249, v[28:29], off offset:928
	v_mov_b32_e32 v168, 0xf149f2ca
	v_mov_b32_e32 v169, 0xf149f2ca
	v_ashrrev_i32_e32 v23, 31, v22
	v_lshl_add_u64 v[4:5], v[22:23], 2, v[26:27]
	global_load_dword v250, v[4:5], off offset:928
	v_ashrrev_i32_e32 v25, 31, v24
	v_lshl_add_u64 v[4:5], v[24:25], 2, v[26:27]
	global_load_dword v251, v[4:5], off offset:928
	s_waitcnt vmcnt(0)
	v_add_f32_e32 v248, v244, v248
	v_cndmask_b32_e64 v167, v167, v248, s[18:19]
	v_add_f32_e32 v249, v245, v249
	v_cndmask_b32_e64 v166, v166, v249, s[20:21]
	v_add_f32_e32 v250, v246, v250
	v_cndmask_b32_e64 v169, v169, v250, s[34:35]
	v_add_f32_e32 v251, v247, v251
	v_cndmask_b32_e64 v168, v168, v251, s[6:7]
	s_add_i32 s47, s41, 0xffffff80
	v_add_u32_e32 v19, s47, v11
	v_mul_hi_i32_i24_e32 v5, 0x1440, v19
	v_mul_i32_i24_e32 v4, 0x1440, v19
	v_lshl_add_u64 v[26:27], v[90:91], 0, v[4:5]
	global_load_dwordx4 v[4:7], v[26:27], off offset:768
	global_load_dwordx4 v[28:31], v[26:27], off offset:784
	v_add_u32_e32 v26, 0xffffff65, v10
	v_ashrrev_i32_e32 v27, 31, v26
	v_lshlrev_b64 v[26:27], 2, v[26:27]
	v_lshl_add_u64 v[26:27], v[92:93], 0, v[26:27]
	v_mov_b32_e32 v148, 0xf149f2ca
	v_mov_b32_e32 v149, 0xf149f2ca
	s_waitcnt vmcnt(1)
	v_mfma_f32_16x16x32_f16 v[4:7], v[4:7], v[64:67], 0
	s_waitcnt vmcnt(0)
	v_mfma_f32_16x16x32_f16 v[4:7], v[28:31], v[0:3], v[4:7]
	s_nop 7
	v_mov_b32_e32 v244, v4
	v_mov_b32_e32 v245, v5
	v_mov_b32_e32 v246, v6
	v_mov_b32_e32 v247, v7
	v_ashrrev_i32_e32 v9, 31, v8
	v_lshl_add_u64 v[28:29], v[8:9], 2, v[26:27]
	global_load_dword v248, v[28:29], off offset:928
	v_ashrrev_i32_e32 v13, 31, v12
	v_lshl_add_u64 v[28:29], v[12:13], 2, v[26:27]
	global_load_dword v249, v[28:29], off offset:928
	v_mov_b32_e32 v151, 0xf149f2ca
	v_mov_b32_e32 v153, 0xf149f2ca
	v_ashrrev_i32_e32 v15, 31, v14
	v_lshl_add_u64 v[4:5], v[14:15], 2, v[26:27]
	global_load_dword v250, v[4:5], off offset:928
	v_ashrrev_i32_e32 v17, 31, v16
	v_lshl_add_u64 v[4:5], v[16:17], 2, v[26:27]
	global_load_dword v251, v[4:5], off offset:928
	s_waitcnt vmcnt(0)
	v_add_f32_e32 v248, v244, v248
	v_cndmask_b32_e64 v149, v149, v248, s[10:11]
	v_add_f32_e32 v249, v245, v249
	v_cndmask_b32_e64 v148, v148, v249, s[12:13]
	v_add_f32_e32 v250, v246, v250
	v_cndmask_b32_e64 v153, v153, v250, s[14:15]
	v_add_f32_e32 v251, v247, v251
	v_cndmask_b32_e64 v151, v151, v251, s[16:17]
	v_or_b32_e32 v4, 4, v19
	v_mad_i64_i32 v[28:29], s[24:25], v4, s22, v[90:91]
	global_load_dwordx4 v[4:7], v[28:29], off offset:768
	s_nop 0
	global_load_dwordx4 v[28:31], v[28:29], off offset:784
	v_mov_b32_e32 v156, 0xf149f2ca
	v_mov_b32_e32 v157, 0xf149f2ca
	s_waitcnt vmcnt(1)
	v_mfma_f32_16x16x32_f16 v[4:7], v[4:7], v[64:67], 0
	s_waitcnt vmcnt(0)
	v_mfma_f32_16x16x32_f16 v[4:7], v[28:31], v[0:3], v[4:7]
	s_nop 7
	v_mov_b32_e32 v244, v4
	v_mov_b32_e32 v245, v5
	v_mov_b32_e32 v246, v6
	v_mov_b32_e32 v247, v7
	v_ashrrev_i32_e32 v19, 31, v18
	v_lshl_add_u64 v[28:29], v[18:19], 2, v[26:27]
	global_load_dword v248, v[28:29], off offset:928
	v_ashrrev_i32_e32 v21, 31, v20
	v_lshl_add_u64 v[28:29], v[20:21], 2, v[26:27]
	global_load_dword v249, v[28:29], off offset:928
	v_mov_b32_e32 v158, 0xf149f2ca
	v_mov_b32_e32 v159, 0xf149f2ca
	v_ashrrev_i32_e32 v23, 31, v22
	v_lshl_add_u64 v[4:5], v[22:23], 2, v[26:27]
	global_load_dword v250, v[4:5], off offset:928
	v_ashrrev_i32_e32 v25, 31, v24
	v_lshl_add_u64 v[4:5], v[24:25], 2, v[26:27]
	global_load_dword v251, v[4:5], off offset:928
	s_waitcnt vmcnt(0)
; template <bool CL>
; __device__ __forceinline__ void natten_wave(const Params& p, int l, bool local, int b, int hh, int qrow0  ,
;                             int r, int ct, const f16* lK, const f16* lV) {
;     ...
; #pragma unroll
;     for (int kr = 0; kr < 8; ++kr) {
; #pragma unroll
;       for (int blk = 0; blk < 2; ++blk) {
;         int tk = (rs + kr) * GW + col0 + kperm + 4 * blk;
;         const f16* kp = proj + (size_t)(b * TL + tk) * PJ + RD + hh * HD + g * 16;
;         f16x8 k0 = *(const f16x8*)(kp);
;         f16x8 k1 = *(const f16x8*)(kp + 8);
;         f32x4 a = f32x4{0.f, 0.f, 0.f, 0.f};
;         a = __builtin_amdgcn_mfma_f32_16x16x32_f16(k0, qf[0], a, 0, 0, 0);
;         a = __builtin_amdgcn_mfma_f32_16x16x32_f16(k1, qf[1], a, 0, 0, 0);
;         const float* bp = rpb + (rs + kr - r + 7) * 31;
; #pragma unroll
;         for (int i = 0; i < 4; ++i) {
;           int kc = col0 + 8 * g + 4 * blk + i;
;           bool valid = (kc >= cs) && (kc <= cs + 15);
;           int bi = kc - c + 15;
;           bi = bi < 0 ? 0 : (bi > 30 ? 30 : bi);
;           float s = valid ? a[i] + bp[bi] : -1e30f;
;           a[i] = s;
;           mx = fmaxf(mx, s);
;         }
;         sl[kr][blk] = a;
;       }
;     }
	v_add_f32_e32 v248, v244, v248
	v_cndmask_b32_e64 v157, v157, v248, s[18:19]
	v_add_f32_e32 v249, v245, v249
	v_cndmask_b32_e64 v156, v156, v249, s[20:21]
	v_add_f32_e32 v250, v246, v250
	v_cndmask_b32_e64 v159, v159, v250, s[34:35]
	v_add_f32_e32 v251, v247, v251
	v_cndmask_b32_e64 v158, v158, v251, s[6:7]
	s_sub_i32 s46, s41, 64
	v_add_u32_e32 v19, s46, v11
	v_mul_hi_i32_i24_e32 v5, 0x1440, v19
	v_mul_i32_i24_e32 v4, 0x1440, v19
	v_lshl_add_u64 v[26:27], v[90:91], 0, v[4:5]
	global_load_dwordx4 v[4:7], v[26:27], off offset:768
	global_load_dwordx4 v[28:31], v[26:27], off offset:784
	v_add_u32_e32 v26, 0xffffff84, v10
	v_ashrrev_i32_e32 v27, 31, v26
	v_lshlrev_b64 v[26:27], 2, v[26:27]
	v_lshl_add_u64 v[26:27], v[92:93], 0, v[26:27]
	v_mov_b32_e32 v80, 0xf149f2ca
	v_mov_b32_e32 v81, 0xf149f2ca
	s_waitcnt vmcnt(1)
	v_mfma_f32_16x16x32_f16 v[4:7], v[4:7], v[64:67], 0
	s_waitcnt vmcnt(0)
	v_mfma_f32_16x16x32_f16 v[4:7], v[28:31], v[0:3], v[4:7]
	s_nop 7
	v_mov_b32_e32 v244, v4
	v_mov_b32_e32 v245, v5
	v_mov_b32_e32 v246, v6
	v_mov_b32_e32 v247, v7
	v_ashrrev_i32_e32 v9, 31, v8
	v_lshl_add_u64 v[28:29], v[8:9], 2, v[26:27]
	global_load_dword v248, v[28:29], off offset:928
	v_ashrrev_i32_e32 v13, 31, v12
	v_lshl_add_u64 v[28:29], v[12:13], 2, v[26:27]
	global_load_dword v249, v[28:29], off offset:928
	v_mov_b32_e32 v82, 0xf149f2ca
	v_mov_b32_e32 v83, 0xf149f2ca
	v_ashrrev_i32_e32 v15, 31, v14
	v_lshl_add_u64 v[4:5], v[14:15], 2, v[26:27]
	global_load_dword v250, v[4:5], off offset:928
	v_ashrrev_i32_e32 v17, 31, v16
	v_lshl_add_u64 v[4:5], v[16:17], 2, v[26:27]
	global_load_dword v251, v[4:5], off offset:928
	s_waitcnt vmcnt(0)
	v_add_f32_e32 v248, v244, v248
	v_cndmask_b32_e64 v81, v81, v248, s[10:11]
	v_add_f32_e32 v249, v245, v249
	v_cndmask_b32_e64 v80, v80, v249, s[12:13]
	v_add_f32_e32 v250, v246, v250
	v_cndmask_b32_e64 v83, v83, v250, s[14:15]
	v_add_f32_e32 v251, v247, v251
	v_cndmask_b32_e64 v82, v82, v251, s[16:17]
	v_or_b32_e32 v4, 4, v19
	v_mad_i64_i32 v[28:29], s[24:25], v4, s22, v[90:91]
	global_load_dwordx4 v[4:7], v[28:29], off offset:768
	s_nop 0
	global_load_dwordx4 v[28:31], v[28:29], off offset:784
	v_mov_b32_e32 v150, 0xf149f2ca
	v_mov_b32_e32 v152, 0xf149f2ca
	s_waitcnt vmcnt(1)
	v_mfma_f32_16x16x32_f16 v[4:7], v[4:7], v[64:67], 0
	s_waitcnt vmcnt(0)
	v_mfma_f32_16x16x32_f16 v[4:7], v[28:31], v[0:3], v[4:7]
	s_nop 7
	v_mov_b32_e32 v244, v4
	v_mov_b32_e32 v245, v5
	v_mov_b32_e32 v246, v6
	v_mov_b32_e32 v247, v7
	v_ashrrev_i32_e32 v19, 31, v18
	v_lshl_add_u64 v[28:29], v[18:19], 2, v[26:27]
	global_load_dword v248, v[28:29], off offset:928
	v_ashrrev_i32_e32 v21, 31, v20
	v_lshl_add_u64 v[28:29], v[20:21], 2, v[26:27]
	global_load_dword v249, v[28:29], off offset:928
	v_mov_b32_e32 v154, 0xf149f2ca
	v_mov_b32_e32 v155, 0xf149f2ca
	v_ashrrev_i32_e32 v23, 31, v22
	v_lshl_add_u64 v[4:5], v[22:23], 2, v[26:27]
	global_load_dword v250, v[4:5], off offset:928
	v_ashrrev_i32_e32 v25, 31, v24
	v_lshl_add_u64 v[4:5], v[24:25], 2, v[26:27]
	global_load_dword v251, v[4:5], off offset:928
	s_waitcnt vmcnt(0)
	v_add_f32_e32 v248, v244, v248
	v_cndmask_b32_e64 v152, v152, v248, s[18:19]
	v_add_f32_e32 v249, v245, v249
	v_cndmask_b32_e64 v150, v150, v249, s[20:21]
	v_add_f32_e32 v250, v246, v250
	v_cndmask_b32_e64 v155, v155, v250, s[34:35]
	v_add_f32_e32 v251, v247, v251
	v_cndmask_b32_e64 v154, v154, v251, s[6:7]
	v_add_u32_e32 v19, s41, v11
	v_mul_hi_i32_i24_e32 v5, 0x1440, v19
	v_mul_i32_i24_e32 v4, 0x1440, v19
	v_lshl_add_u64 v[26:27], v[90:91], 0, v[4:5]
	global_load_dwordx4 v[4:7], v[26:27], off offset:768
	global_load_dwordx4 v[28:31], v[26:27], off offset:784
	v_add_u32_e32 v26, 0xffffffa3, v10
	v_ashrrev_i32_e32 v27, 31, v26
	v_lshlrev_b64 v[26:27], 2, v[26:27]
	v_lshl_add_u64 v[26:27], v[92:93], 0, v[26:27]
	v_mov_b32_e32 v140, 0xf149f2ca
	v_mov_b32_e32 v141, 0xf149f2ca
	s_waitcnt vmcnt(1)
	v_mfma_f32_16x16x32_f16 v[4:7], v[4:7], v[64:67], 0
	s_waitcnt vmcnt(0)
	v_mfma_f32_16x16x32_f16 v[4:7], v[28:31], v[0:3], v[4:7]
	s_nop 7
	v_mov_b32_e32 v244, v4
	v_mov_b32_e32 v245, v5
	v_mov_b32_e32 v246, v6
	v_mov_b32_e32 v247, v7
	v_ashrrev_i32_e32 v9, 31, v8
	v_lshl_add_u64 v[28:29], v[8:9], 2, v[26:27]
	global_load_dword v248, v[28:29], off offset:928
	v_ashrrev_i32_e32 v13, 31, v12
	v_lshl_add_u64 v[28:29], v[12:13], 2, v[26:27]
	global_load_dword v249, v[28:29], off offset:928
	v_mov_b32_e32 v142, 0xf149f2ca
	v_mov_b32_e32 v143, 0xf149f2ca
	v_ashrrev_i32_e32 v15, 31, v14
	v_lshl_add_u64 v[4:5], v[14:15], 2, v[26:27]
	global_load_dword v250, v[4:5], off offset:928
	v_ashrrev_i32_e32 v17, 31, v16
	v_lshl_add_u64 v[4:5], v[16:17], 2, v[26:27]
	global_load_dword v251, v[4:5], off offset:928
	s_waitcnt vmcnt(0)
	v_add_f32_e32 v248, v244, v248
	v_cndmask_b32_e64 v141, v141, v248, s[10:11]
	v_add_f32_e32 v249, v245, v249
	v_cndmask_b32_e64 v140, v140, v249, s[12:13]
	v_add_f32_e32 v250, v246, v250
	v_cndmask_b32_e64 v143, v143, v250, s[14:15]
	v_add_f32_e32 v251, v247, v251
	v_cndmask_b32_e64 v142, v142, v251, s[16:17]
	v_or_b32_e32 v4, 4, v19
	v_mad_i64_i32 v[28:29], s[24:25], v4, s22, v[90:91]
	global_load_dwordx4 v[4:7], v[28:29], off offset:768
	s_nop 0
	global_load_dwordx4 v[28:31], v[28:29], off offset:784
	v_mov_b32_e32 v144, 0xf149f2ca
	v_mov_b32_e32 v145, 0xf149f2ca
	s_waitcnt vmcnt(1)
	v_mfma_f32_16x16x32_f16 v[4:7], v[4:7], v[64:67], 0
	s_waitcnt vmcnt(0)
; template <bool CL>
; __device__ __forceinline__ void natten_wave(const Params& p, int l, bool local, int b, int hh, int qrow0  ,
;                             int r, int ct, const f16* lK, const f16* lV) {
;     ...
; #pragma unroll
;     for (int kr = 0; kr < 8; ++kr) {
; #pragma unroll
;       for (int blk = 0; blk < 2; ++blk) {
;         int tk = (rs + kr) * GW + col0 + kperm + 4 * blk;
;         const f16* kp = proj + (size_t)(b * TL + tk) * PJ + RD + hh * HD + g * 16;
;         f16x8 k0 = *(const f16x8*)(kp);
;         f16x8 k1 = *(const f16x8*)(kp + 8);
;         f32x4 a = f32x4{0.f, 0.f, 0.f, 0.f};
;         a = __builtin_amdgcn_mfma_f32_16x16x32_f16(k0, qf[0], a, 0, 0, 0);
;         a = __builtin_amdgcn_mfma_f32_16x16x32_f16(k1, qf[1], a, 0, 0, 0);
;         const float* bp = rpb + (rs + kr - r + 7) * 31;
; #pragma unroll
;         for (int i = 0; i < 4; ++i) {
;           int kc = col0 + 8 * g + 4 * blk + i;
;           bool valid = (kc >= cs) && (kc <= cs + 15);
;           int bi = kc - c + 15;
;           bi = bi < 0 ? 0 : (bi > 30 ? 30 : bi);
;           float s = valid ? a[i] + bp[bi] : -1e30f;
;           a[i] = s;
;           mx = fmaxf(mx, s);
;         }
;         sl[kr][blk] = a;
;       }
;     }
	v_mfma_f32_16x16x32_f16 v[4:7], v[28:31], v[0:3], v[4:7]
	s_nop 7
	v_mov_b32_e32 v244, v4
	v_mov_b32_e32 v245, v5
	v_mov_b32_e32 v246, v6
	v_mov_b32_e32 v247, v7
	v_ashrrev_i32_e32 v19, 31, v18
	v_lshl_add_u64 v[28:29], v[18:19], 2, v[26:27]
	global_load_dword v248, v[28:29], off offset:928
	v_ashrrev_i32_e32 v21, 31, v20
	v_lshl_add_u64 v[28:29], v[20:21], 2, v[26:27]
	global_load_dword v249, v[28:29], off offset:928
	v_mov_b32_e32 v146, 0xf149f2ca
	v_mov_b32_e32 v147, 0xf149f2ca
	v_ashrrev_i32_e32 v23, 31, v22
	v_lshl_add_u64 v[4:5], v[22:23], 2, v[26:27]
	global_load_dword v250, v[4:5], off offset:928
	v_ashrrev_i32_e32 v25, 31, v24
	v_lshl_add_u64 v[4:5], v[24:25], 2, v[26:27]
	global_load_dword v251, v[4:5], off offset:928
	s_waitcnt vmcnt(0)
	v_add_f32_e32 v248, v244, v248
	v_cndmask_b32_e64 v145, v145, v248, s[18:19]
	v_add_f32_e32 v249, v245, v249
	v_cndmask_b32_e64 v144, v144, v249, s[20:21]
	v_add_f32_e32 v250, v246, v250
	v_cndmask_b32_e64 v147, v147, v250, s[34:35]
	v_add_f32_e32 v251, v247, v251
	v_cndmask_b32_e64 v146, v146, v251, s[6:7]
	s_add_i32 s45, s41, 64
	v_add_u32_e32 v19, s45, v11
	v_mul_hi_i32_i24_e32 v5, 0x1440, v19
	v_mul_i32_i24_e32 v4, 0x1440, v19
	v_lshl_add_u64 v[26:27], v[90:91], 0, v[4:5]
	global_load_dwordx4 v[4:7], v[26:27], off offset:768
	global_load_dwordx4 v[28:31], v[26:27], off offset:784
	v_subrev_u32_e32 v26, 62, v10
	v_ashrrev_i32_e32 v27, 31, v26
	v_lshlrev_b64 v[26:27], 2, v[26:27]
	v_lshl_add_u64 v[26:27], v[92:93], 0, v[26:27]
	v_mov_b32_e32 v132, 0xf149f2ca
	v_mov_b32_e32 v133, 0xf149f2ca
	s_waitcnt vmcnt(1)
	v_mfma_f32_16x16x32_f16 v[4:7], v[4:7], v[64:67], 0
	s_waitcnt vmcnt(0)
	v_mfma_f32_16x16x32_f16 v[4:7], v[28:31], v[0:3], v[4:7]
	s_nop 7
	v_mov_b32_e32 v244, v4
	v_mov_b32_e32 v245, v5
	v_mov_b32_e32 v246, v6
	v_mov_b32_e32 v247, v7
	v_ashrrev_i32_e32 v9, 31, v8
	v_lshl_add_u64 v[28:29], v[8:9], 2, v[26:27]
	global_load_dword v248, v[28:29], off offset:928
	v_ashrrev_i32_e32 v13, 31, v12
	v_lshl_add_u64 v[28:29], v[12:13], 2, v[26:27]
	global_load_dword v249, v[28:29], off offset:928
	v_mov_b32_e32 v134, 0xf149f2ca
	v_mov_b32_e32 v135, 0xf149f2ca
	v_ashrrev_i32_e32 v15, 31, v14
	v_lshl_add_u64 v[4:5], v[14:15], 2, v[26:27]
	global_load_dword v250, v[4:5], off offset:928
	v_ashrrev_i32_e32 v17, 31, v16
	v_lshl_add_u64 v[4:5], v[16:17], 2, v[26:27]
	global_load_dword v251, v[4:5], off offset:928
	s_waitcnt vmcnt(0)
	v_add_f32_e32 v248, v244, v248
	v_cndmask_b32_e64 v133, v133, v248, s[10:11]
	v_add_f32_e32 v249, v245, v249
	v_cndmask_b32_e64 v132, v132, v249, s[12:13]
	v_add_f32_e32 v250, v246, v250
	v_cndmask_b32_e64 v135, v135, v250, s[14:15]
	v_add_f32_e32 v251, v247, v251
	v_cndmask_b32_e64 v134, v134, v251, s[16:17]
	v_or_b32_e32 v4, 4, v19
	v_mad_i64_i32 v[28:29], s[24:25], v4, s22, v[90:91]
	global_load_dwordx4 v[4:7], v[28:29], off offset:768
	s_nop 0
	global_load_dwordx4 v[28:31], v[28:29], off offset:784
	v_mov_b32_e32 v136, 0xf149f2ca
	v_mov_b32_e32 v137, 0xf149f2ca
	s_waitcnt vmcnt(1)
	v_mfma_f32_16x16x32_f16 v[4:7], v[4:7], v[64:67], 0
	s_waitcnt vmcnt(0)
	v_mfma_f32_16x16x32_f16 v[4:7], v[28:31], v[0:3], v[4:7]
	s_nop 7
	v_mov_b32_e32 v244, v4
	v_mov_b32_e32 v245, v5
	v_mov_b32_e32 v246, v6
	v_mov_b32_e32 v247, v7
	v_ashrrev_i32_e32 v19, 31, v18
	v_lshl_add_u64 v[28:29], v[18:19], 2, v[26:27]
	global_load_dword v248, v[28:29], off offset:928
	v_ashrrev_i32_e32 v21, 31, v20
	v_lshl_add_u64 v[28:29], v[20:21], 2, v[26:27]
	global_load_dword v249, v[28:29], off offset:928
	v_mov_b32_e32 v138, 0xf149f2ca
	v_mov_b32_e32 v139, 0xf149f2ca
	v_ashrrev_i32_e32 v23, 31, v22
	v_lshl_add_u64 v[4:5], v[22:23], 2, v[26:27]
	global_load_dword v250, v[4:5], off offset:928
	v_ashrrev_i32_e32 v25, 31, v24
	v_lshl_add_u64 v[4:5], v[24:25], 2, v[26:27]
	global_load_dword v251, v[4:5], off offset:928
	s_waitcnt vmcnt(0)
	v_add_f32_e32 v248, v244, v248
	v_cndmask_b32_e64 v137, v137, v248, s[18:19]
	v_add_f32_e32 v249, v245, v249
	v_cndmask_b32_e64 v136, v136, v249, s[20:21]
	v_add_f32_e32 v250, v246, v250
	v_cndmask_b32_e64 v139, v139, v250, s[34:35]
	v_add_f32_e32 v251, v247, v251
	v_cndmask_b32_e64 v138, v138, v251, s[6:7]
	s_add_i32 s44, s41, 0x80
	v_add_u32_e32 v19, s44, v11
	v_mul_hi_i32_i24_e32 v5, 0x1440, v19
	v_mul_i32_i24_e32 v4, 0x1440, v19
	v_lshl_add_u64 v[26:27], v[90:91], 0, v[4:5]
	global_load_dwordx4 v[4:7], v[26:27], off offset:768
	global_load_dwordx4 v[28:31], v[26:27], off offset:784
	v_subrev_u32_e32 v26, 31, v10
	v_ashrrev_i32_e32 v27, 31, v26
	v_lshlrev_b64 v[26:27], 2, v[26:27]
	v_lshl_add_u64 v[26:27], v[92:93], 0, v[26:27]
	v_mov_b32_e32 v84, 0xf149f2ca
	v_mov_b32_e32 v85, 0xf149f2ca
	s_waitcnt vmcnt(1)
	v_mfma_f32_16x16x32_f16 v[4:7], v[4:7], v[64:67], 0
	s_waitcnt vmcnt(0)
	v_mfma_f32_16x16x32_f16 v[4:7], v[28:31], v[0:3], v[4:7]
	s_nop 7
	v_mov_b32_e32 v244, v4
	v_mov_b32_e32 v245, v5
	v_mov_b32_e32 v246, v6
	v_mov_b32_e32 v247, v7
	v_ashrrev_i32_e32 v9, 31, v8
	v_lshl_add_u64 v[28:29], v[8:9], 2, v[26:27]
	global_load_dword v248, v[28:29], off offset:928
	v_ashrrev_i32_e32 v13, 31, v12
	v_lshl_add_u64 v[28:29], v[12:13], 2, v[26:27]
	global_load_dword v249, v[28:29], off offset:928
	v_mov_b32_e32 v86, 0xf149f2ca
	v_mov_b32_e32 v87, 0xf149f2ca
	v_ashrrev_i32_e32 v15, 31, v14
	v_lshl_add_u64 v[4:5], v[14:15], 2, v[26:27]
	global_load_dword v250, v[4:5], off offset:928
	v_ashrrev_i32_e32 v17, 31, v16
	v_lshl_add_u64 v[4:5], v[16:17], 2, v[26:27]
	global_load_dword v251, v[4:5], off offset:928
	s_waitcnt vmcnt(0)
; template <bool CL>
; __device__ __forceinline__ void natten_wave(const Params& p, int l, bool local, int b, int hh, int qrow0  ,
;                             int r, int ct, const f16* lK, const f16* lV) {
;     ...
; #pragma unroll
;     for (int kr = 0; kr < 8; ++kr) {
; #pragma unroll
;       for (int blk = 0; blk < 2; ++blk) {
;         int tk = (rs + kr) * GW + col0 + kperm + 4 * blk;
;         const f16* kp = proj + (size_t)(b * TL + tk) * PJ + RD + hh * HD + g * 16;
;         f16x8 k0 = *(const f16x8*)(kp);
;         f16x8 k1 = *(const f16x8*)(kp + 8);
;         f32x4 a = f32x4{0.f, 0.f, 0.f, 0.f};
;         a = __builtin_amdgcn_mfma_f32_16x16x32_f16(k0, qf[0], a, 0, 0, 0);
;         a = __builtin_amdgcn_mfma_f32_16x16x32_f16(k1, qf[1], a, 0, 0, 0);
;         const float* bp = rpb + (rs + kr - r + 7) * 31;
; #pragma unroll
;         for (int i = 0; i < 4; ++i) {
;           int kc = col0 + 8 * g + 4 * blk + i;
;           bool valid = (kc >= cs) && (kc <= cs + 15);
;           int bi = kc - c + 15;
;           bi = bi < 0 ? 0 : (bi > 30 ? 30 : bi);
;           float s = valid ? a[i] + bp[bi] : -1e30f;
;           a[i] = s;
;           mx = fmaxf(mx, s);
;         }
;         sl[kr][blk] = a;
;       }
;     }
	v_add_f32_e32 v248, v244, v248
	v_cndmask_b32_e64 v85, v85, v248, s[10:11]
	v_add_f32_e32 v249, v245, v249
	v_cndmask_b32_e64 v84, v84, v249, s[12:13]
	v_add_f32_e32 v250, v246, v250
	v_cndmask_b32_e64 v87, v87, v250, s[14:15]
	v_add_f32_e32 v251, v247, v251
	v_cndmask_b32_e64 v86, v86, v251, s[16:17]
	v_or_b32_e32 v4, 4, v19
	v_mad_i64_i32 v[28:29], s[24:25], v4, s22, v[90:91]
	global_load_dwordx4 v[4:7], v[28:29], off offset:768
	s_nop 0
	global_load_dwordx4 v[28:31], v[28:29], off offset:784
	v_mov_b32_e32 v128, 0xf149f2ca
	v_mov_b32_e32 v129, 0xf149f2ca
	s_waitcnt vmcnt(1)
	v_mfma_f32_16x16x32_f16 v[4:7], v[4:7], v[64:67], 0
	s_waitcnt vmcnt(0)
	v_mfma_f32_16x16x32_f16 v[4:7], v[28:31], v[0:3], v[4:7]
	s_nop 7
	v_mov_b32_e32 v244, v4
	v_mov_b32_e32 v245, v5
	v_mov_b32_e32 v246, v6
	v_mov_b32_e32 v247, v7
	v_ashrrev_i32_e32 v19, 31, v18
	v_lshl_add_u64 v[28:29], v[18:19], 2, v[26:27]
	global_load_dword v248, v[28:29], off offset:928
	v_ashrrev_i32_e32 v21, 31, v20
	v_lshl_add_u64 v[28:29], v[20:21], 2, v[26:27]
	global_load_dword v249, v[28:29], off offset:928
	v_mov_b32_e32 v130, 0xf149f2ca
	v_mov_b32_e32 v131, 0xf149f2ca
	v_ashrrev_i32_e32 v23, 31, v22
	v_lshl_add_u64 v[4:5], v[22:23], 2, v[26:27]
	global_load_dword v250, v[4:5], off offset:928
	v_ashrrev_i32_e32 v25, 31, v24
	v_lshl_add_u64 v[4:5], v[24:25], 2, v[26:27]
	global_load_dword v251, v[4:5], off offset:928
	s_waitcnt vmcnt(0)
	v_add_f32_e32 v248, v244, v248
	v_cndmask_b32_e64 v129, v129, v248, s[18:19]
	v_add_f32_e32 v249, v245, v249
	v_cndmask_b32_e64 v128, v128, v249, s[20:21]
	v_add_f32_e32 v250, v246, v250
	v_cndmask_b32_e64 v131, v131, v250, s[34:35]
	v_add_f32_e32 v251, v247, v251
	v_cndmask_b32_e64 v130, v130, v251, s[6:7]
	s_add_i32 s42, s41, 0xc0
	v_add_u32_e32 v19, s42, v11
	v_mul_hi_i32_i24_e32 v5, 0x1440, v19
	v_mul_i32_i24_e32 v4, 0x1440, v19
	v_lshl_add_u64 v[26:27], v[90:91], 0, v[4:5]
	global_load_dwordx4 v[4:7], v[26:27], off offset:768
	s_nop 0
	global_load_dwordx4 v[26:29], v[26:27], off offset:784
	v_ashrrev_i32_e32 v11, 31, v10
	v_lshlrev_b64 v[10:11], 2, v[10:11]
	v_lshl_add_u64 v[10:11], v[92:93], 0, v[10:11]
	v_mov_b32_e32 v120, 0xf149f2ca
	v_mov_b32_e32 v121, 0xf149f2ca
	s_waitcnt vmcnt(1)
	v_mfma_f32_16x16x32_f16 v[4:7], v[4:7], v[64:67], 0
	s_waitcnt vmcnt(0)
	v_mfma_f32_16x16x32_f16 v[4:7], v[26:29], v[0:3], v[4:7]
	s_nop 7
	v_mov_b32_e32 v244, v4
	v_mov_b32_e32 v245, v5
	v_mov_b32_e32 v246, v6
	v_mov_b32_e32 v247, v7
	v_ashrrev_i32_e32 v9, 31, v8
	v_lshl_add_u64 v[8:9], v[8:9], 2, v[10:11]
	global_load_dword v248, v[8:9], off offset:928
	v_ashrrev_i32_e32 v13, 31, v12
	v_lshl_add_u64 v[8:9], v[12:13], 2, v[10:11]
	global_load_dword v249, v[8:9], off offset:928
	v_mov_b32_e32 v122, 0xf149f2ca
	v_mov_b32_e32 v123, 0xf149f2ca
	v_ashrrev_i32_e32 v15, 31, v14
	v_lshl_add_u64 v[4:5], v[14:15], 2, v[10:11]
	global_load_dword v250, v[4:5], off offset:928
	v_ashrrev_i32_e32 v17, 31, v16
	v_lshl_add_u64 v[4:5], v[16:17], 2, v[10:11]
	global_load_dword v251, v[4:5], off offset:928
	s_waitcnt vmcnt(0)
	v_add_f32_e32 v248, v244, v248
	v_cndmask_b32_e64 v121, v121, v248, s[10:11]
	v_add_f32_e32 v249, v245, v249
	v_cndmask_b32_e64 v120, v120, v249, s[12:13]
	v_add_f32_e32 v250, v246, v250
	v_cndmask_b32_e64 v123, v123, v250, s[14:15]
	v_add_f32_e32 v251, v247, v251
	v_cndmask_b32_e64 v122, v122, v251, s[16:17]
	v_or_b32_e32 v4, 4, v19
	v_mad_i64_i32 v[8:9], s[10:11], v4, s22, v[90:91]
	global_load_dwordx4 v[4:7], v[8:9], off offset:768
	global_load_dwordx4 v[12:15], v[8:9], off offset:784
	v_mov_b32_e32 v124, 0xf149f2ca
	v_mov_b32_e32 v125, 0xf149f2ca
	s_waitcnt vmcnt(1)
	v_mfma_f32_16x16x32_f16 v[4:7], v[4:7], v[64:67], 0
	s_waitcnt vmcnt(0)
	v_mfma_f32_16x16x32_f16 v[4:7], v[12:15], v[0:3], v[4:7]
	s_nop 7
	v_mov_b32_e32 v244, v4
	v_mov_b32_e32 v245, v5
	v_mov_b32_e32 v246, v6
	v_mov_b32_e32 v247, v7
	v_ashrrev_i32_e32 v19, 31, v18
	v_lshl_add_u64 v[8:9], v[18:19], 2, v[10:11]
	global_load_dword v248, v[8:9], off offset:928
	v_ashrrev_i32_e32 v21, 31, v20
	v_lshl_add_u64 v[8:9], v[20:21], 2, v[10:11]
	global_load_dword v249, v[8:9], off offset:928
	v_mov_b32_e32 v126, 0xf149f2ca
	v_mov_b32_e32 v127, 0xf149f2ca
	v_ashrrev_i32_e32 v23, 31, v22
	v_lshl_add_u64 v[4:5], v[22:23], 2, v[10:11]
	global_load_dword v250, v[4:5], off offset:928
	v_ashrrev_i32_e32 v25, 31, v24
	v_lshl_add_u64 v[4:5], v[24:25], 2, v[10:11]
	global_load_dword v251, v[4:5], off offset:928
	s_waitcnt vmcnt(0)
	v_add_f32_e32 v248, v244, v248
	v_cndmask_b32_e64 v125, v125, v248, s[18:19]
	v_add_f32_e32 v249, v245, v249
	v_cndmask_b32_e64 v124, v124, v249, s[20:21]
	v_add_f32_e32 v250, v246, v250
	v_cndmask_b32_e64 v127, v127, v250, s[34:35]
	v_add_f32_e32 v251, v247, v251
	v_cndmask_b32_e64 v126, v126, v251, s[6:7]
	s_branch .LBB0_548

; template <bool CL>
; __device__ __forceinline__ void natten_wave(const Params& p, int l, bool local, int b, int hh, int qrow0  ,
;                             int r, int ct, const f16* lK, const f16* lV) {
;     ...
;   for (int cb = 0; cb < 16; ++cb) {
;     const int key = (cb >> 1) * 32 + kperm + 4 * (cb & 1);
;     f16x8 k0, k1;
;     if (CL) {
;       const f16* kp = lK + key * 72 + g * 16;
;       k0 = *(const f16x8*)(kp);
;       k1 = *(const f16x8*)(kp + 8);
;     } else {
;       const f16* kp = proj + (size_t)(NLAT + b * CTXL + key) * PJ + RD + hh * HD + g * 16;
;       k0 = *(const f16x8*)(kp);
;       k1 = *(const f16x8*)(kp + 8);
;     }
;     f32x4 a = f32x4{0.f, 0.f, 0.f, 0.f};
;     a = __builtin_amdgcn_mfma_f32_16x16x32_f16(k0, qf[0], a, 0, 0, 0);
;     a = __builtin_amdgcn_mfma_f32_16x16x32_f16(k1, qf[1], a, 0, 0, 0);
; #pragma unroll
;     for (int i = 0; i < 4; ++i) mx = fmaxf(mx, a[i]);
;     sc[cb] = a;
;     if (CL && (cb & 3) == 3) __builtin_amdgcn_sched_barrier(0);
;   }
;   mx = fmaxf(mx, __shfl_xor(mx, 16, 64));
;   mx = fmaxf(mx, __shfl_xor(mx, 32, 64));
; __device__ __forceinline__ void phase_natten(const Params& p, int l, f16* smem) {
;     ...
;     const int gw = bid * 4 + wave, nw = gridDim.x * 4;
;     for (int j = gw; j < NB * 16 * NH; j += nw) {
;       int hh = j % NH;
;       int q = j / NH;
;       int qt = q & 15, b = q >> 4;
;       natten_wave<false>(p, l, false, b, hh, NLAT + b * CTXL + qt * 16, 0, 0, nullptr, nullptr);
.LBB0_688:
	s_mul_hi_i32 s6, s10, 0x2aaaaaab
	s_lshr_b32 s7, s6, 31
	s_add_i32 s13, s6, s7
	s_ashr_i32 s7, s13, 4
	s_lshl_b32 s8, s7, 8
	s_mul_i32 s6, s13, 6
	s_add_i32 s14, s8, 0x8000
	s_lshl_b32 s8, s13, 4
	s_mul_i32 s7, s7, 6
	s_and_b32 s15, s8, 0xf0
	s_sub_i32 s6, s7, s6
	s_add_i32 s6, s10, s6
	v_or_b32_e32 v0, s15, v82
	s_ashr_i32 s7, s6, 31
	v_or_b32_e32 v74, s14, v0
	s_lshl_b64 s[8:9], s[6:7], 15
	v_mad_i64_i32 v[0:1], s[6:7], v74, s22, v[60:61]
	s_mulk_i32 s13, 0xfe80
	s_add_i32 s6, s11, s13
	s_ashr_i32 s7, s6, 31
	s_lshl_b64 s[6:7], s[6:7], 1
	v_lshl_add_u64 v[0:1], v[0:1], 0, s[6:7]
	v_lshl_add_u64 v[4:5], v[0:1], 0, v[164:165]
	v_or_b32_e32 v65, s14, v83
	global_load_dwordx4 v[0:3], v[4:5], off
	global_load_dwordx4 v[56:59], v[4:5], off offset:16
	v_mad_i64_i32 v[4:5], s[14:15], v65, s22, v[60:61]
	v_lshl_add_u64 v[4:5], v[4:5], 0, s[6:7]
	v_lshl_add_u64 v[8:9], v[4:5], 0, v[164:165]
	global_load_dwordx4 v[4:7], v[8:9], off offset:768
	s_nop 0
	global_load_dwordx4 v[8:11], v[8:9], off offset:784
	v_mov_b32_e32 v71, v165
	v_ashrrev_i32_e32 v75, 31, v74
	s_add_i32 s10, s10, s28
	s_add_i32 s11, s11, s12
	s_cmpk_lt_i32 s10, 0xc0
	s_waitcnt vmcnt(1)
	v_mfma_f32_16x16x32_f16 v[4:7], v[4:7], v[0:3], 0
	s_waitcnt vmcnt(0)
	v_mfma_f32_16x16x32_f16 v[76:79], v[8:11], v[56:59], v[4:7]
	s_nop 7
	v_max3_f32 v4, v76, s71, v77
	v_max3_f32 v12, v4, v78, v79
	v_or_b32_e32 v4, 4, v65
	v_mad_i64_i32 v[4:5], s[14:15], v4, s22, v[60:61]
	v_lshl_add_u64 v[4:5], v[4:5], 0, s[6:7]
	v_lshl_add_u64 v[8:9], v[4:5], 0, v[164:165]
	global_load_dwordx4 v[4:7], v[8:9], off offset:768
	s_nop 0
	global_load_dwordx4 v[8:11], v[8:9], off offset:784
	s_waitcnt vmcnt(1)
	v_mfma_f32_16x16x32_f16 v[4:7], v[4:7], v[0:3], 0
	s_waitcnt vmcnt(0)
	v_mfma_f32_16x16x32_f16 v[90:93], v[8:11], v[56:59], v[4:7]
	s_nop 7
	v_max3_f32 v4, v12, v90, v91
	v_max3_f32 v12, v4, v92, v93
	v_or_b32_e32 v4, 32, v65
	v_mad_i64_i32 v[4:5], s[14:15], v4, s22, v[60:61]
	v_lshl_add_u64 v[4:5], v[4:5], 0, s[6:7]
	v_lshl_add_u64 v[8:9], v[4:5], 0, v[164:165]
	global_load_dwordx4 v[4:7], v[8:9], off offset:768
	s_nop 0
	global_load_dwordx4 v[8:11], v[8:9], off offset:784
	s_waitcnt vmcnt(1)
	v_mfma_f32_16x16x32_f16 v[4:7], v[4:7], v[0:3], 0
	s_waitcnt vmcnt(0)
	v_mfma_f32_16x16x32_f16 v[52:55], v[8:11], v[56:59], v[4:7]
	s_nop 7
	v_max3_f32 v4, v12, v52, v53
	v_max3_f32 v12, v4, v54, v55
	v_or_b32_e32 v4, 36, v65
	v_mad_i64_i32 v[4:5], s[14:15], v4, s22, v[60:61]
	v_lshl_add_u64 v[4:5], v[4:5], 0, s[6:7]
	v_lshl_add_u64 v[8:9], v[4:5], 0, v[164:165]
	global_load_dwordx4 v[4:7], v[8:9], off offset:768
	s_nop 0
	global_load_dwordx4 v[8:11], v[8:9], off offset:784
	s_waitcnt vmcnt(1)
	v_mfma_f32_16x16x32_f16 v[4:7], v[4:7], v[0:3], 0
	s_waitcnt vmcnt(0)
	v_mfma_f32_16x16x32_f16 v[48:51], v[8:11], v[56:59], v[4:7]
	s_nop 7
	v_max3_f32 v4, v12, v48, v49
	v_max3_f32 v12, v4, v50, v51
	v_or_b32_e32 v4, 64, v65
	v_mad_i64_i32 v[4:5], s[14:15], v4, s22, v[60:61]
	v_lshl_add_u64 v[4:5], v[4:5], 0, s[6:7]
	v_lshl_add_u64 v[8:9], v[4:5], 0, v[164:165]
	global_load_dwordx4 v[4:7], v[8:9], off offset:768
	s_nop 0
	global_load_dwordx4 v[8:11], v[8:9], off offset:784
	s_waitcnt vmcnt(1)
	v_mfma_f32_16x16x32_f16 v[4:7], v[4:7], v[0:3], 0
	s_waitcnt vmcnt(0)
	v_mfma_f32_16x16x32_f16 v[44:47], v[8:11], v[56:59], v[4:7]
	s_nop 7
	v_max3_f32 v4, v12, v44, v45
	v_max3_f32 v12, v4, v46, v47
	v_or_b32_e32 v4, 0x44, v65
	v_mad_i64_i32 v[4:5], s[14:15], v4, s22, v[60:61]
	v_lshl_add_u64 v[4:5], v[4:5], 0, s[6:7]
	v_lshl_add_u64 v[8:9], v[4:5], 0, v[164:165]
	global_load_dwordx4 v[4:7], v[8:9], off offset:768
	s_nop 0
	global_load_dwordx4 v[8:11], v[8:9], off offset:784
	s_waitcnt vmcnt(1)
	v_mfma_f32_16x16x32_f16 v[4:7], v[4:7], v[0:3], 0
	s_waitcnt vmcnt(0)
	v_mfma_f32_16x16x32_f16 v[40:43], v[8:11], v[56:59], v[4:7]
	s_nop 7
	v_max3_f32 v4, v12, v40, v41
	v_max3_f32 v12, v4, v42, v43
	v_or_b32_e32 v4, 0x60, v65
	v_mad_i64_i32 v[4:5], s[14:15], v4, s22, v[60:61]
	v_lshl_add_u64 v[4:5], v[4:5], 0, s[6:7]
	v_lshl_add_u64 v[8:9], v[4:5], 0, v[164:165]
	global_load_dwordx4 v[4:7], v[8:9], off offset:768
	s_nop 0
	global_load_dwordx4 v[8:11], v[8:9], off offset:784
	s_waitcnt vmcnt(1)
	v_mfma_f32_16x16x32_f16 v[4:7], v[4:7], v[0:3], 0
	s_waitcnt vmcnt(0)
	v_mfma_f32_16x16x32_f16 v[36:39], v[8:11], v[56:59], v[4:7]
	s_nop 7
	v_max3_f32 v4, v12, v36, v37
	v_max3_f32 v12, v4, v38, v39
	v_or_b32_e32 v4, 0x64, v65
	v_mad_i64_i32 v[4:5], s[14:15], v4, s22, v[60:61]
	v_lshl_add_u64 v[4:5], v[4:5], 0, s[6:7]
	v_lshl_add_u64 v[8:9], v[4:5], 0, v[164:165]
	global_load_dwordx4 v[4:7], v[8:9], off offset:768
	s_nop 0
	global_load_dwordx4 v[8:11], v[8:9], off offset:784
	s_waitcnt vmcnt(1)
	v_mfma_f32_16x16x32_f16 v[4:7], v[4:7], v[0:3], 0
	s_waitcnt vmcnt(0)
	v_mfma_f32_16x16x32_f16 v[32:35], v[8:11], v[56:59], v[4:7]
	s_nop 7
	v_max3_f32 v4, v12, v32, v33
	v_max3_f32 v12, v4, v34, v35
	v_or_b32_e32 v4, 0x80, v65
	v_mad_i64_i32 v[4:5], s[14:15], v4, s22, v[60:61]
	v_lshl_add_u64 v[4:5], v[4:5], 0, s[6:7]
	v_lshl_add_u64 v[8:9], v[4:5], 0, v[164:165]
	global_load_dwordx4 v[4:7], v[8:9], off offset:768
	s_nop 0
	global_load_dwordx4 v[8:11], v[8:9], off offset:784
	s_waitcnt vmcnt(1)
	v_mfma_f32_16x16x32_f16 v[4:7], v[4:7], v[0:3], 0
	s_waitcnt vmcnt(0)
	v_mfma_f32_16x16x32_f16 v[28:31], v[8:11], v[56:59], v[4:7]
	s_nop 7
	v_max3_f32 v4, v12, v28, v29
	v_max3_f32 v12, v4, v30, v31
	v_or_b32_e32 v4, 0x84, v65
	v_mad_i64_i32 v[4:5], s[14:15], v4, s22, v[60:61]
	v_lshl_add_u64 v[4:5], v[4:5], 0, s[6:7]
	v_lshl_add_u64 v[8:9], v[4:5], 0, v[164:165]
	global_load_dwordx4 v[4:7], v[8:9], off offset:768
	s_nop 0
	global_load_dwordx4 v[8:11], v[8:9], off offset:784
	s_waitcnt vmcnt(1)
; template <bool CL>
; __device__ __forceinline__ void natten_wave(const Params& p, int l, bool local, int b, int hh, int qrow0  ,
;                             int r, int ct, const f16* lK, const f16* lV) {
;     ...
;   for (int cb = 0; cb < 16; ++cb) {
;     const int key = (cb >> 1) * 32 + kperm + 4 * (cb & 1);
;     f16x8 k0, k1;
;     if (CL) {
;       const f16* kp = lK + key * 72 + g * 16;
;       k0 = *(const f16x8*)(kp);
;       k1 = *(const f16x8*)(kp + 8);
;     } else {
;       const f16* kp = proj + (size_t)(NLAT + b * CTXL + key) * PJ + RD + hh * HD + g * 16;
;       k0 = *(const f16x8*)(kp);
;       k1 = *(const f16x8*)(kp + 8);
;     }
;     f32x4 a = f32x4{0.f, 0.f, 0.f, 0.f};
;     a = __builtin_amdgcn_mfma_f32_16x16x32_f16(k0, qf[0], a, 0, 0, 0);
;     a = __builtin_amdgcn_mfma_f32_16x16x32_f16(k1, qf[1], a, 0, 0, 0);
; #pragma unroll
;     for (int i = 0; i < 4; ++i) mx = fmaxf(mx, a[i]);
;     sc[cb] = a;
;     if (CL && (cb & 3) == 3) __builtin_amdgcn_sched_barrier(0);
;   }
;   mx = fmaxf(mx, __shfl_xor(mx, 16, 64));
;   mx = fmaxf(mx, __shfl_xor(mx, 32, 64));
;   float sum = 0.f;
;   f32x4 o[4];
; #pragma unroll
;   for (int nb = 0; nb < 4; ++nb) o[nb] = f32x4{0.f, 0.f, 0.f, 0.f};
;   if (local) {
; #pragma unroll
;     for (int kr = 0; kr < 8; ++kr) {
;       f16x8 pf;
; #pragma unroll
;       for (int blk = 0; blk < 2; ++blk)
; #pragma unroll
;         for (int i = 0; i < 4; ++i) {
;           float e = __expf(sl[kr][blk][i] - mx);
;           sum += e;
;           pf[blk * 4 + i] = (f16)e;
;         }
;       int tk = (rs + kr) * GW + col0 + 8 * g;
; #pragma unroll
;       for (int nb = 0; nb < 4; ++nb) {
;         f16x8 vf = *(const f16x8*)(vt + (size_t)(nb * 16 + lq) * TL + tk);
;         o[nb] = __builtin_amdgcn_mfma_f32_16x16x32_f16(vf, pf, o[nb], 0, 0, 0);
;       }
;     }
;   }
; #pragma unroll
;   for (int pr = 0; pr < 8; ++pr) {
;     f16x8 pf;
; #pragma unroll
;     for (int blk = 0; blk < 2; ++blk)
; #pragma unroll
;       for (int i = 0; i < 4; ++i) {
;         float e = __expf(sc[pr * 2 + blk][i] - mx);
;         sum += e;
;         pf[blk * 4 + i] = (f16)e;
;       }
;     int tk = pr * 32 + 8 * g;
; #pragma unroll
;     for (int nb = 0; nb < 4; ++nb) {
;       f16x8 vf;
;       if (CL) vf = *(const f16x8*)(lV + (nb * 16 + lq) * 264 + tk);
;       else vf = *(const f16x8*)(vtc + (size_t)(nb * 16 + lq) * CTXL + tk);
	v_mfma_f32_16x16x32_f16 v[4:7], v[4:7], v[0:3], 0
	s_waitcnt vmcnt(0)
	v_mfma_f32_16x16x32_f16 v[24:27], v[8:11], v[56:59], v[4:7]
	s_nop 7
	v_max3_f32 v4, v12, v24, v25
	v_max3_f32 v12, v4, v26, v27
	v_or_b32_e32 v4, 0xa0, v65
	v_mad_i64_i32 v[4:5], s[14:15], v4, s22, v[60:61]
	v_lshl_add_u64 v[4:5], v[4:5], 0, s[6:7]
	v_lshl_add_u64 v[8:9], v[4:5], 0, v[164:165]
	global_load_dwordx4 v[4:7], v[8:9], off offset:768
	s_nop 0
	global_load_dwordx4 v[8:11], v[8:9], off offset:784
	s_waitcnt vmcnt(1)
	v_mfma_f32_16x16x32_f16 v[4:7], v[4:7], v[0:3], 0
	s_waitcnt vmcnt(0)
	v_mfma_f32_16x16x32_f16 v[20:23], v[8:11], v[56:59], v[4:7]
	s_nop 7
	v_max3_f32 v4, v12, v20, v21
	v_max3_f32 v12, v4, v22, v23
	v_or_b32_e32 v4, 0xa4, v65
	v_mad_i64_i32 v[4:5], s[14:15], v4, s22, v[60:61]
	v_lshl_add_u64 v[4:5], v[4:5], 0, s[6:7]
	v_lshl_add_u64 v[8:9], v[4:5], 0, v[164:165]
	global_load_dwordx4 v[4:7], v[8:9], off offset:768
	s_nop 0
	global_load_dwordx4 v[8:11], v[8:9], off offset:784
	s_waitcnt vmcnt(1)
	v_mfma_f32_16x16x32_f16 v[4:7], v[4:7], v[0:3], 0
	s_waitcnt vmcnt(0)
	v_mfma_f32_16x16x32_f16 v[16:19], v[8:11], v[56:59], v[4:7]
	s_nop 7
	v_max3_f32 v4, v12, v16, v17
	v_max3_f32 v67, v4, v18, v19
	v_or_b32_e32 v4, 0xc0, v65
	v_mad_i64_i32 v[4:5], s[14:15], v4, s22, v[60:61]
	v_lshl_add_u64 v[4:5], v[4:5], 0, s[6:7]
	v_lshl_add_u64 v[8:9], v[4:5], 0, v[164:165]
	global_load_dwordx4 v[4:7], v[8:9], off offset:768
	s_nop 0
	global_load_dwordx4 v[8:11], v[8:9], off offset:784
	s_waitcnt vmcnt(1)
	v_mfma_f32_16x16x32_f16 v[4:7], v[4:7], v[0:3], 0
	s_waitcnt vmcnt(0)
	v_mfma_f32_16x16x32_f16 v[12:15], v[8:11], v[56:59], v[4:7]
	s_nop 7
	v_max3_f32 v4, v67, v12, v13
	v_max3_f32 v67, v4, v14, v15
	v_or_b32_e32 v4, 0xc4, v65
	v_mad_i64_i32 v[4:5], s[14:15], v4, s22, v[60:61]
	v_lshl_add_u64 v[4:5], v[4:5], 0, s[6:7]
	v_lshl_add_u64 v[8:9], v[4:5], 0, v[164:165]
	global_load_dwordx4 v[4:7], v[8:9], off offset:768
	s_nop 0
	global_load_dwordx4 v[8:11], v[8:9], off offset:784
	s_waitcnt vmcnt(1)
	v_mfma_f32_16x16x32_f16 v[4:7], v[4:7], v[0:3], 0
	s_waitcnt vmcnt(0)
	v_mfma_f32_16x16x32_f16 v[8:11], v[8:11], v[56:59], v[4:7]
	s_nop 7
	v_max3_f32 v4, v67, v8, v9
	v_max3_f32 v67, v4, v10, v11
	v_or_b32_e32 v4, 0xe0, v65
	v_mad_i64_i32 v[4:5], s[14:15], v4, s22, v[60:61]
	v_lshl_add_u64 v[4:5], v[4:5], 0, s[6:7]
	v_lshl_add_u64 v[84:85], v[4:5], 0, v[164:165]
	global_load_dwordx4 v[4:7], v[84:85], off offset:768
	s_nop 0
	global_load_dwordx4 v[84:87], v[84:85], off offset:784
	s_waitcnt vmcnt(1)
	v_mfma_f32_16x16x32_f16 v[4:7], v[4:7], v[0:3], 0
	v_or_b32_e32 v65, 0xe4, v65
	s_waitcnt vmcnt(0)
	v_mfma_f32_16x16x32_f16 v[4:7], v[84:87], v[56:59], v[4:7]
	v_mad_i64_i32 v[84:85], s[14:15], v65, s22, v[60:61]
	v_lshl_add_u64 v[84:85], v[84:85], 0, s[6:7]
	v_lshl_add_u64 v[94:95], v[84:85], 0, v[164:165]
	global_load_dwordx4 v[84:87], v[94:95], off offset:768
	s_nop 0
	global_load_dwordx4 v[94:97], v[94:95], off offset:784
	s_waitcnt vmcnt(1)
	v_mfma_f32_16x16x32_f16 v[0:3], v[84:87], v[0:3], 0
	v_max3_f32 v67, v67, v4, v5
	v_max3_f32 v67, v67, v6, v7
	s_waitcnt vmcnt(0)
	v_mfma_f32_16x16x32_f16 v[0:3], v[94:97], v[56:59], v[0:3]
	s_nop 7
	v_max3_f32 v56, v67, v0, v1
	v_max3_f32 v56, v56, v2, v3
	ds_bpermute_b32 v57, v80, v56
	s_waitcnt lgkmcnt(0)
	v_max_f32_e32 v57, v57, v57
	v_max_f32_e32 v56, v56, v57
	ds_bpermute_b32 v57, v81, v56
	s_waitcnt lgkmcnt(0)
	v_max_f32_e32 v57, v57, v57
	v_max_f32_e32 v73, v56, v57
	v_sub_f32_e32 v58, v77, v73
	v_sub_f32_e32 v56, v76, v73
	v_mul_f32_e32 v58, 0x3fb8aa3b, v58
	v_mul_f32_e32 v56, 0x3fb8aa3b, v56
	v_exp_f32_e32 v65, v58
	v_sub_f32_e32 v58, v78, v73
	v_exp_f32_e32 v56, v56
	v_mul_f32_e32 v58, 0x3fb8aa3b, v58
	v_exp_f32_e32 v67, v58
	v_sub_f32_e32 v58, v79, v73
	v_mul_f32_e32 v58, 0x3fb8aa3b, v58
	v_exp_f32_e32 v69, v58
	v_add_f32_e32 v57, 0, v56
	v_add_f32_e32 v57, v65, v57
	v_add_f32_e32 v57, v67, v57
	v_add_f32_e32 v84, v69, v57
	v_sub_f32_e32 v57, v90, v73
	v_mul_f32_e32 v57, 0x3fb8aa3b, v57
	v_exp_f32_e32 v85, v57
	v_sub_f32_e32 v57, v91, v73
	v_mul_f32_e32 v57, 0x3fb8aa3b, v57
	v_exp_f32_e32 v86, v57
	v_sub_f32_e32 v57, v92, v73
	v_mul_f32_e32 v57, 0x3fb8aa3b, v57
	v_exp_f32_e32 v87, v57
	v_sub_f32_e32 v57, v93, v73
	v_mul_f32_e32 v57, 0x3fb8aa3b, v57
	v_exp_f32_e32 v90, v57
	v_cvt_pk_f16_f32 v57, v67, v69
	v_cvt_pk_f16_f32 v56, v56, v65
	v_lshl_add_u64 v[76:77], v[62:63], 0, s[8:9]
	v_mov_b32_e32 v65, v165
	v_mov_b32_e32 v67, v165
	v_mov_b32_e32 v69, v165
	v_lshl_add_u64 v[78:79], v[76:77], 0, v[64:65]
	v_lshl_add_u64 v[96:97], v[76:77], 0, v[66:67]
	v_lshl_add_u64 v[100:101], v[76:77], 0, v[68:69]
	v_lshl_add_u64 v[104:105], v[76:77], 0, v[70:71]
	global_load_dwordx4 v[92:95], v[78:79], off
	v_sub_f32_e32 v52, v52, v73
	global_load_dwordx4 v[96:99], v[96:97], off
	v_mul_f32_e32 v52, 0x3fb8aa3b, v52
	global_load_dwordx4 v[100:103], v[100:101], off
	v_sub_f32_e32 v53, v53, v73
	global_load_dwordx4 v[104:107], v[104:105], off
	v_sub_f32_e32 v48, v48, v73
	v_cvt_pk_f16_f32 v59, v87, v90
	v_cvt_pk_f16_f32 v58, v85, v86
	v_add_f32_e32 v65, v85, v84
	v_exp_f32_e32 v52, v52
	v_mul_f32_e32 v53, 0x3fb8aa3b, v53
	v_sub_f32_e32 v54, v54, v73
	v_mul_f32_e32 v48, 0x3fb8aa3b, v48
	s_waitcnt vmcnt(3)
	v_mfma_f32_16x16x32_f16 v[92:95], v[92:95], v[56:59], 0
	v_add_f32_e32 v65, v86, v65
	v_exp_f32_e32 v53, v53
	v_mul_f32_e32 v54, 0x3fb8aa3b, v54
	s_waitcnt vmcnt(2)
	v_mfma_f32_16x16x32_f16 v[96:99], v[96:99], v[56:59], 0
	v_sub_f32_e32 v55, v55, v73
	v_add_f32_e32 v65, v87, v65
	v_exp_f32_e32 v54, v54
	s_waitcnt vmcnt(1)
	v_mfma_f32_16x16x32_f16 v[100:103], v[100:103], v[56:59], 0
	v_mul_f32_e32 v55, 0x3fb8aa3b, v55
	v_add_f32_e32 v65, v90, v65
	v_exp_f32_e32 v55, v55
	s_waitcnt vmcnt(0)
; template <bool CL>
; __device__ __forceinline__ void natten_wave(const Params& p, int l, bool local, int b, int hh, int qrow0  ,
;                             int r, int ct, const f16* lK, const f16* lV) {
;     ...
;   for (int pr = 0; pr < 8; ++pr) {
;     f16x8 pf;
; #pragma unroll
;     for (int blk = 0; blk < 2; ++blk)
; #pragma unroll
;       for (int i = 0; i < 4; ++i) {
;         float e = __expf(sc[pr * 2 + blk][i] - mx);
;         sum += e;
;         pf[blk * 4 + i] = (f16)e;
;       }
;     int tk = pr * 32 + 8 * g;
; #pragma unroll
;     for (int nb = 0; nb < 4; ++nb) {
;       f16x8 vf;
;       if (CL) vf = *(const f16x8*)(lV + (nb * 16 + lq) * 264 + tk);
;       else vf = *(const f16x8*)(vtc + (size_t)(nb * 16 + lq) * CTXL + tk);
;       o[nb] = __builtin_amdgcn_mfma_f32_16x16x32_f16(vf, pf, o[nb], 0, 0, 0);
;     }
	v_mfma_f32_16x16x32_f16 v[56:59], v[104:107], v[56:59], 0
	v_exp_f32_e32 v106, v48
	v_sub_f32_e32 v48, v49, v73
	v_mul_f32_e32 v48, 0x3fb8aa3b, v48
	v_exp_f32_e32 v107, v48
	v_sub_f32_e32 v48, v50, v73
	v_add_f32_e32 v65, v52, v65
	v_mul_f32_e32 v48, 0x3fb8aa3b, v48
	v_add_f32_e32 v65, v53, v65
	v_exp_f32_e32 v108, v48
	v_sub_f32_e32 v48, v51, v73
	v_add_f32_e32 v65, v54, v65
	v_mul_f32_e32 v48, 0x3fb8aa3b, v48
	v_lshl_add_u64 v[104:105], v[76:77], 0, 64
	v_add_f32_e32 v65, v55, v65
	v_exp_f32_e32 v109, v48
	v_cvt_pk_f16_f32 v49, v54, v55
	v_cvt_pk_f16_f32 v48, v52, v53
	global_load_dwordx4 v[52:55], v[78:79], off offset:64
	v_lshl_add_u64 v[84:85], v[104:105], 0, v[66:67]
	global_load_dwordx4 v[84:87], v[84:85], off
	v_cvt_pk_f16_f32 v51, v108, v109
	v_cvt_pk_f16_f32 v50, v106, v107
	v_lshl_add_u64 v[90:91], v[104:105], 0, v[68:69]
	v_sub_f32_e32 v44, v44, v73
	s_waitcnt vmcnt(1)
	v_mfma_f32_16x16x32_f16 v[52:55], v[52:55], v[48:51], v[92:95]
	s_nop 2
	v_lshl_add_u64 v[94:95], v[104:105], 0, v[70:71]
	global_load_dwordx4 v[90:93], v[90:91], off
	v_mul_f32_e32 v44, 0x3fb8aa3b, v44
	s_waitcnt vmcnt(1)
	v_mfma_f32_16x16x32_f16 v[84:87], v[84:87], v[48:51], v[96:99]
	v_sub_f32_e32 v45, v45, v73
	v_sub_f32_e32 v40, v40, v73
	v_exp_f32_e32 v44, v44
	global_load_dwordx4 v[94:97], v[94:95], off
	s_waitcnt vmcnt(1)
	v_mfma_f32_16x16x32_f16 v[90:93], v[90:93], v[48:51], v[100:103]
	v_mul_f32_e32 v45, 0x3fb8aa3b, v45
	v_sub_f32_e32 v46, v46, v73
	v_mul_f32_e32 v40, 0x3fb8aa3b, v40
	s_waitcnt vmcnt(0)
	v_mfma_f32_16x16x32_f16 v[48:51], v[94:97], v[48:51], v[56:59]
	v_exp_f32_e32 v45, v45
	s_nop 1
	v_add_f32_e32 v56, v106, v65
	v_add_f32_e32 v56, v107, v56
	v_mul_f32_e32 v46, 0x3fb8aa3b, v46
	v_sub_f32_e32 v47, v47, v73
	v_exp_f32_e32 v96, v40
	v_sub_f32_e32 v40, v41, v73
	v_add_f32_e32 v56, v108, v56
	v_exp_f32_e32 v46, v46
	v_mul_f32_e32 v47, 0x3fb8aa3b, v47
	v_mul_f32_e32 v40, 0x3fb8aa3b, v40
	v_add_f32_e32 v56, v109, v56
	v_exp_f32_e32 v47, v47
	v_exp_f32_e32 v97, v40
	v_sub_f32_e32 v40, v42, v73
	v_add_f32_e32 v56, v44, v56
	v_mul_f32_e32 v40, 0x3fb8aa3b, v40
	v_add_f32_e32 v56, v45, v56
	v_exp_f32_e32 v98, v40
	v_sub_f32_e32 v40, v43, v73
	v_add_f32_e32 v56, v46, v56
	v_mul_f32_e32 v40, 0x3fb8aa3b, v40
	v_add_f32_e32 v65, v47, v56
	v_exp_f32_e32 v99, v40
	v_cvt_pk_f16_f32 v41, v46, v47
	v_cvt_pk_f16_f32 v40, v44, v45
	global_load_dwordx4 v[44:47], v[78:79], off offset:128
	v_cvt_pk_f16_f32 v43, v98, v99
	v_cvt_pk_f16_f32 v42, v96, v97
	v_lshl_add_u64 v[94:95], v[76:77], 0, s[84:85]
	v_lshl_add_u64 v[56:57], v[94:95], 0, v[68:69]
	s_waitcnt vmcnt(0)
	v_mfma_f32_16x16x32_f16 v[44:47], v[44:47], v[40:43], v[52:55]
	s_nop 2
	v_lshl_add_u64 v[52:53], v[94:95], 0, v[66:67]
	global_load_dwordx4 v[52:55], v[52:53], off
	v_sub_f32_e32 v36, v36, v73
	s_waitcnt vmcnt(0)
	v_mfma_f32_16x16x32_f16 v[52:55], v[52:55], v[40:43], v[84:87]
	s_nop 2
	v_lshl_add_u64 v[84:85], v[94:95], 0, v[70:71]
	global_load_dwordx4 v[56:59], v[56:57], off
	v_mul_f32_e32 v36, 0x3fb8aa3b, v36
	global_load_dwordx4 v[84:87], v[84:85], off
	v_sub_f32_e32 v37, v37, v73
	v_sub_f32_e32 v32, v32, v73
	s_waitcnt vmcnt(1)
	v_mfma_f32_16x16x32_f16 v[56:59], v[56:59], v[40:43], v[90:93]
	v_exp_f32_e32 v36, v36
	v_mul_f32_e32 v37, 0x3fb8aa3b, v37
	v_sub_f32_e32 v38, v38, v73
	s_waitcnt vmcnt(0)
	v_mfma_f32_16x16x32_f16 v[40:43], v[84:87], v[40:43], v[48:51]
	v_mul_f32_e32 v32, 0x3fb8aa3b, v32
	v_exp_f32_e32 v37, v37
	v_mul_f32_e32 v38, 0x3fb8aa3b, v38
	v_add_f32_e32 v48, v96, v65
	v_add_f32_e32 v48, v97, v48
	v_sub_f32_e32 v39, v39, v73
	v_exp_f32_e32 v86, v32
	v_sub_f32_e32 v32, v33, v73
	v_add_f32_e32 v48, v98, v48
	v_exp_f32_e32 v38, v38
	v_mul_f32_e32 v39, 0x3fb8aa3b, v39
	v_mul_f32_e32 v32, 0x3fb8aa3b, v32
	v_add_f32_e32 v48, v99, v48
	v_exp_f32_e32 v39, v39
	v_exp_f32_e32 v87, v32
	v_sub_f32_e32 v32, v34, v73
	v_add_f32_e32 v48, v36, v48
	v_mul_f32_e32 v32, 0x3fb8aa3b, v32
	v_add_f32_e32 v48, v37, v48
	v_exp_f32_e32 v90, v32
	v_sub_f32_e32 v32, v35, v73
	v_add_f32_e32 v48, v38, v48
	v_mul_f32_e32 v32, 0x3fb8aa3b, v32
	v_add_f32_e32 v65, v39, v48
	v_exp_f32_e32 v91, v32
	v_cvt_pk_f16_f32 v33, v38, v39
	v_cvt_pk_f16_f32 v32, v36, v37
	global_load_dwordx4 v[36:39], v[78:79], off offset:192
	s_mov_b64 s[8:9], 0xc0
	v_cvt_pk_f16_f32 v35, v90, v91
	v_cvt_pk_f16_f32 v34, v86, v87
	v_lshl_add_u64 v[84:85], v[76:77], 0, s[8:9]
	v_lshl_add_u64 v[48:49], v[84:85], 0, v[68:69]
	s_waitcnt vmcnt(0)
	v_mfma_f32_16x16x32_f16 v[36:39], v[36:39], v[32:35], v[44:47]
	s_nop 2
	v_lshl_add_u64 v[44:45], v[84:85], 0, v[66:67]
	global_load_dwordx4 v[44:47], v[44:45], off
	v_sub_f32_e32 v28, v28, v73
	s_waitcnt vmcnt(0)
	v_mfma_f32_16x16x32_f16 v[44:47], v[44:47], v[32:35], v[52:55]
	s_nop 2
	v_lshl_add_u64 v[52:53], v[84:85], 0, v[70:71]
	global_load_dwordx4 v[48:51], v[48:49], off
	v_mul_f32_e32 v28, 0x3fb8aa3b, v28
	global_load_dwordx4 v[52:55], v[52:53], off
	v_sub_f32_e32 v29, v29, v73
	v_sub_f32_e32 v24, v24, v73
	s_waitcnt vmcnt(1)
	v_mfma_f32_16x16x32_f16 v[48:51], v[48:51], v[32:35], v[56:59]
	v_exp_f32_e32 v28, v28
	v_mul_f32_e32 v29, 0x3fb8aa3b, v29
	v_sub_f32_e32 v30, v30, v73
	s_waitcnt vmcnt(0)
; template <bool CL>
; __device__ __forceinline__ void natten_wave(const Params& p, int l, bool local, int b, int hh, int qrow0  ,
;                             int r, int ct, const f16* lK, const f16* lV) {
;     ...
;   for (int pr = 0; pr < 8; ++pr) {
;     f16x8 pf;
; #pragma unroll
;     for (int blk = 0; blk < 2; ++blk)
; #pragma unroll
;       for (int i = 0; i < 4; ++i) {
;         float e = __expf(sc[pr * 2 + blk][i] - mx);
;         sum += e;
;         pf[blk * 4 + i] = (f16)e;
;       }
;     int tk = pr * 32 + 8 * g;
; #pragma unroll
;     for (int nb = 0; nb < 4; ++nb) {
;       f16x8 vf;
;       if (CL) vf = *(const f16x8*)(lV + (nb * 16 + lq) * 264 + tk);
;       else vf = *(const f16x8*)(vtc + (size_t)(nb * 16 + lq) * CTXL + tk);
;       o[nb] = __builtin_amdgcn_mfma_f32_16x16x32_f16(vf, pf, o[nb], 0, 0, 0);
;     }
	v_mfma_f32_16x16x32_f16 v[32:35], v[52:55], v[32:35], v[40:43]
	v_mul_f32_e32 v24, 0x3fb8aa3b, v24
	v_exp_f32_e32 v29, v29
	v_mul_f32_e32 v30, 0x3fb8aa3b, v30
	v_add_f32_e32 v40, v86, v65
	v_add_f32_e32 v40, v87, v40
	v_sub_f32_e32 v31, v31, v73
	v_exp_f32_e32 v55, v24
	v_sub_f32_e32 v24, v25, v73
	v_add_f32_e32 v40, v90, v40
	v_exp_f32_e32 v30, v30
	v_mul_f32_e32 v31, 0x3fb8aa3b, v31
	v_mul_f32_e32 v24, 0x3fb8aa3b, v24
	v_add_f32_e32 v40, v91, v40
	v_exp_f32_e32 v31, v31
	v_exp_f32_e32 v56, v24
	v_sub_f32_e32 v24, v26, v73
	v_add_f32_e32 v40, v28, v40
	v_mul_f32_e32 v24, 0x3fb8aa3b, v24
	v_add_f32_e32 v40, v29, v40
	v_exp_f32_e32 v57, v24
	v_sub_f32_e32 v24, v27, v73
	v_add_f32_e32 v40, v30, v40
	v_mul_f32_e32 v24, 0x3fb8aa3b, v24
	v_add_f32_e32 v54, v31, v40
	v_exp_f32_e32 v58, v24
	v_cvt_pk_f16_f32 v25, v30, v31
	v_cvt_pk_f16_f32 v24, v28, v29
	global_load_dwordx4 v[28:31], v[78:79], off offset:256
	s_mov_b64 s[8:9], 0x100
	v_cvt_pk_f16_f32 v27, v57, v58
	v_cvt_pk_f16_f32 v26, v55, v56
	v_lshl_add_u64 v[52:53], v[76:77], 0, s[8:9]
	v_lshl_add_u64 v[40:41], v[52:53], 0, v[68:69]
	s_waitcnt vmcnt(0)
	v_mfma_f32_16x16x32_f16 v[28:31], v[28:31], v[24:27], v[36:39]
	s_nop 2
	v_lshl_add_u64 v[36:37], v[52:53], 0, v[66:67]
	global_load_dwordx4 v[36:39], v[36:37], off
	v_sub_f32_e32 v20, v20, v73
	s_waitcnt vmcnt(0)
	v_mfma_f32_16x16x32_f16 v[36:39], v[36:39], v[24:27], v[44:47]
	s_nop 2
	v_lshl_add_u64 v[44:45], v[52:53], 0, v[70:71]
	global_load_dwordx4 v[40:43], v[40:41], off
	v_mul_f32_e32 v20, 0x3fb8aa3b, v20
	global_load_dwordx4 v[44:47], v[44:45], off
	v_sub_f32_e32 v21, v21, v73
	v_sub_f32_e32 v16, v16, v73
	s_waitcnt vmcnt(1)
	v_mfma_f32_16x16x32_f16 v[40:43], v[40:43], v[24:27], v[48:51]
	v_exp_f32_e32 v20, v20
	v_mul_f32_e32 v21, 0x3fb8aa3b, v21
	v_sub_f32_e32 v22, v22, v73
	s_waitcnt vmcnt(0)
	v_mfma_f32_16x16x32_f16 v[24:27], v[44:47], v[24:27], v[32:35]
	v_mul_f32_e32 v16, 0x3fb8aa3b, v16
	v_exp_f32_e32 v21, v21
	v_mul_f32_e32 v22, 0x3fb8aa3b, v22
	v_add_f32_e32 v32, v55, v54
	v_add_f32_e32 v32, v56, v32
	v_sub_f32_e32 v23, v23, v73
	v_exp_f32_e32 v47, v16
	v_sub_f32_e32 v16, v17, v73
	v_add_f32_e32 v32, v57, v32
	v_exp_f32_e32 v22, v22
	v_mul_f32_e32 v23, 0x3fb8aa3b, v23
	v_mul_f32_e32 v16, 0x3fb8aa3b, v16
	v_add_f32_e32 v32, v58, v32
	v_exp_f32_e32 v23, v23
	v_exp_f32_e32 v48, v16
	v_sub_f32_e32 v16, v18, v73
	v_add_f32_e32 v32, v20, v32
	v_mul_f32_e32 v16, 0x3fb8aa3b, v16
	v_add_f32_e32 v32, v21, v32
	v_exp_f32_e32 v49, v16
	v_sub_f32_e32 v16, v19, v73
	v_add_f32_e32 v32, v22, v32
	v_mul_f32_e32 v16, 0x3fb8aa3b, v16
	v_add_f32_e32 v46, v23, v32
	v_exp_f32_e32 v50, v16
	v_cvt_pk_f16_f32 v17, v22, v23
	v_cvt_pk_f16_f32 v16, v20, v21
	global_load_dwordx4 v[20:23], v[78:79], off offset:320
	s_mov_b64 s[8:9], 0x140
	v_cvt_pk_f16_f32 v19, v49, v50
	v_cvt_pk_f16_f32 v18, v47, v48
	v_lshl_add_u64 v[44:45], v[76:77], 0, s[8:9]
	v_lshl_add_u64 v[32:33], v[44:45], 0, v[68:69]
	s_waitcnt vmcnt(0)
	v_mfma_f32_16x16x32_f16 v[20:23], v[20:23], v[16:19], v[28:31]
	s_nop 2
	v_lshl_add_u64 v[28:29], v[44:45], 0, v[66:67]
	global_load_dwordx4 v[28:31], v[28:29], off
	v_sub_f32_e32 v12, v12, v73
	s_waitcnt vmcnt(0)
	v_mfma_f32_16x16x32_f16 v[28:31], v[28:31], v[16:19], v[36:39]
	s_nop 2
	v_lshl_add_u64 v[36:37], v[44:45], 0, v[70:71]
	global_load_dwordx4 v[32:35], v[32:33], off
	v_mul_f32_e32 v12, 0x3fb8aa3b, v12
	global_load_dwordx4 v[36:39], v[36:37], off
	v_sub_f32_e32 v13, v13, v73
	v_sub_f32_e32 v8, v8, v73
	s_waitcnt vmcnt(1)
	v_mfma_f32_16x16x32_f16 v[32:35], v[32:35], v[16:19], v[40:43]
	v_exp_f32_e32 v12, v12
	v_mul_f32_e32 v13, 0x3fb8aa3b, v13
	v_sub_f32_e32 v14, v14, v73
	s_waitcnt vmcnt(0)
	v_mfma_f32_16x16x32_f16 v[16:19], v[36:39], v[16:19], v[24:27]
	v_mul_f32_e32 v8, 0x3fb8aa3b, v8
	v_exp_f32_e32 v13, v13
	v_mul_f32_e32 v14, 0x3fb8aa3b, v14
	v_add_f32_e32 v24, v47, v46
	v_add_f32_e32 v24, v48, v24
	v_sub_f32_e32 v15, v15, v73
	v_exp_f32_e32 v39, v8
	v_sub_f32_e32 v8, v9, v73
	v_add_f32_e32 v24, v49, v24
	v_exp_f32_e32 v14, v14
	v_mul_f32_e32 v15, 0x3fb8aa3b, v15
	v_mul_f32_e32 v8, 0x3fb8aa3b, v8
	v_add_f32_e32 v24, v50, v24
	v_exp_f32_e32 v15, v15
	v_exp_f32_e32 v40, v8
	v_sub_f32_e32 v8, v10, v73
	v_add_f32_e32 v24, v12, v24
	v_mul_f32_e32 v8, 0x3fb8aa3b, v8
	v_add_f32_e32 v24, v13, v24
	v_exp_f32_e32 v41, v8
	v_sub_f32_e32 v8, v11, v73
	v_add_f32_e32 v24, v14, v24
	v_mul_f32_e32 v8, 0x3fb8aa3b, v8
	v_add_f32_e32 v38, v15, v24
	v_exp_f32_e32 v42, v8
	v_cvt_pk_f16_f32 v9, v14, v15
	v_cvt_pk_f16_f32 v8, v12, v13
	global_load_dwordx4 v[12:15], v[78:79], off offset:384
	s_mov_b64 s[8:9], 0x180
	v_cvt_pk_f16_f32 v11, v41, v42
	v_cvt_pk_f16_f32 v10, v39, v40
	v_lshl_add_u64 v[36:37], v[76:77], 0, s[8:9]
	v_lshl_add_u64 v[24:25], v[36:37], 0, v[68:69]
	s_waitcnt vmcnt(0)
; template <bool CL>
; __device__ __forceinline__ void natten_wave(const Params& p, int l, bool local, int b, int hh, int qrow0  ,
;                             int r, int ct, const f16* lK, const f16* lV) {
;     ...
;   for (int pr = 0; pr < 8; ++pr) {
;     f16x8 pf;
; #pragma unroll
;     for (int blk = 0; blk < 2; ++blk)
; #pragma unroll
;       for (int i = 0; i < 4; ++i) {
;         float e = __expf(sc[pr * 2 + blk][i] - mx);
;         sum += e;
;         pf[blk * 4 + i] = (f16)e;
;       }
;     int tk = pr * 32 + 8 * g;
; #pragma unroll
;     for (int nb = 0; nb < 4; ++nb) {
;       f16x8 vf;
;       if (CL) vf = *(const f16x8*)(lV + (nb * 16 + lq) * 264 + tk);
;       else vf = *(const f16x8*)(vtc + (size_t)(nb * 16 + lq) * CTXL + tk);
;       o[nb] = __builtin_amdgcn_mfma_f32_16x16x32_f16(vf, pf, o[nb], 0, 0, 0);
;     }
;     if (CL) __builtin_amdgcn_sched_barrier(0);
;   }
;   sum += __shfl_xor(sum, 16, 64);
;   sum += __shfl_xor(sum, 32, 64);
;   float inv = 1.0f / sum;
; #pragma unroll
;   for (int nb = 0; nb < 4; ++nb) {
;     f16x4 ov;
;     ov[0] = (f16)(o[nb][0] * inv);
;     ov[1] = (f16)(o[nb][1] * inv);
;     ov[2] = (f16)(o[nb][2] * inv);
;     ov[3] = (f16)(o[nb][3] * inv);
;     *(f16x4*)(br + (size_t)(qrow0 + lq) * DM + 640 + hh * HD + nb * 16 + 4 * g) = ov;
;   }
	v_mfma_f32_16x16x32_f16 v[12:15], v[12:15], v[8:11], v[20:23]
	s_nop 2
	v_lshl_add_u64 v[20:21], v[36:37], 0, v[66:67]
	global_load_dwordx4 v[20:23], v[20:21], off
	v_sub_f32_e32 v4, v4, v73
	s_waitcnt vmcnt(0)
	v_mfma_f32_16x16x32_f16 v[20:23], v[20:23], v[8:11], v[28:31]
	s_nop 2
	v_lshl_add_u64 v[28:29], v[36:37], 0, v[70:71]
	global_load_dwordx4 v[24:27], v[24:25], off
	v_mul_f32_e32 v4, 0x3fb8aa3b, v4
	global_load_dwordx4 v[28:31], v[28:29], off
	v_sub_f32_e32 v5, v5, v73
	v_sub_f32_e32 v0, v0, v73
	s_waitcnt vmcnt(1)
	v_mfma_f32_16x16x32_f16 v[24:27], v[24:27], v[8:11], v[32:35]
	v_exp_f32_e32 v4, v4
	v_mul_f32_e32 v5, 0x3fb8aa3b, v5
	v_sub_f32_e32 v6, v6, v73
	s_waitcnt vmcnt(0)
	v_mfma_f32_16x16x32_f16 v[16:19], v[28:31], v[8:11], v[16:19]
	v_add_f32_e32 v8, v39, v38
	v_mul_f32_e32 v0, 0x3fb8aa3b, v0
	v_add_f32_e32 v8, v40, v8
	v_exp_f32_e32 v5, v5
	v_mul_f32_e32 v6, 0x3fb8aa3b, v6
	v_sub_f32_e32 v7, v7, v73
	v_exp_f32_e32 v31, v0
	v_sub_f32_e32 v0, v1, v73
	v_add_f32_e32 v8, v41, v8
	v_exp_f32_e32 v6, v6
	v_mul_f32_e32 v7, 0x3fb8aa3b, v7
	v_mul_f32_e32 v0, 0x3fb8aa3b, v0
	v_add_f32_e32 v8, v42, v8
	v_exp_f32_e32 v7, v7
	v_exp_f32_e32 v32, v0
	v_sub_f32_e32 v0, v2, v73
	v_add_f32_e32 v8, v4, v8
	v_mul_f32_e32 v0, 0x3fb8aa3b, v0
	v_add_f32_e32 v8, v5, v8
	v_exp_f32_e32 v33, v0
	v_sub_f32_e32 v0, v3, v73
	v_add_f32_e32 v8, v6, v8
	v_mul_f32_e32 v0, 0x3fb8aa3b, v0
	v_add_f32_e32 v30, v7, v8
	v_exp_f32_e32 v34, v0
	v_cvt_pk_f16_f32 v1, v6, v7
	v_cvt_pk_f16_f32 v0, v4, v5
	global_load_dwordx4 v[4:7], v[78:79], off offset:448
	s_mov_b64 s[8:9], 0x1c0
	v_cvt_pk_f16_f32 v3, v33, v34
	v_cvt_pk_f16_f32 v2, v31, v32
	v_lshl_add_u64 v[28:29], v[76:77], 0, s[8:9]
	v_mov_b32_e32 v73, v165
	s_waitcnt vmcnt(0)
	v_mfma_f32_16x16x32_f16 v[12:15], v[4:7], v[0:3], v[12:15]
	v_lshl_add_u64 v[4:5], v[28:29], 0, v[66:67]
	global_load_dwordx4 v[4:7], v[4:5], off
	s_waitcnt vmcnt(0)
	v_mfma_f32_16x16x32_f16 v[8:11], v[4:7], v[0:3], v[20:23]
	v_lshl_add_u64 v[4:5], v[28:29], 0, v[68:69]
	s_nop 1
	v_lshl_add_u64 v[20:21], v[28:29], 0, v[70:71]
	global_load_dwordx4 v[4:7], v[4:5], off
	s_waitcnt vmcnt(0)
	v_mfma_f32_16x16x32_f16 v[4:7], v[4:7], v[0:3], v[24:27]
	global_load_dwordx4 v[20:23], v[20:21], off
	s_waitcnt vmcnt(0)
	v_mfma_f32_16x16x32_f16 v[0:3], v[20:23], v[0:3], v[16:19]
	s_nop 2
	v_add_f32_e32 v16, v31, v30
	v_add_f32_e32 v16, v32, v16
	v_add_f32_e32 v16, v33, v16
	v_add_f32_e32 v16, v34, v16
	ds_bpermute_b32 v17, v80, v16
	s_waitcnt lgkmcnt(0)
	v_add_f32_e32 v16, v16, v17
	ds_bpermute_b32 v17, v81, v16
	s_waitcnt lgkmcnt(0)
	v_add_f32_e32 v16, v16, v17
	s_nop 0
	v_rcp_f32_e32 v18, v16
	s_nop 0
	v_mul_f32_e32 v17, 1.0, v18
	v_mov_b32_e32 v16, v17
	v_lshlrev_b64 v[18:19], 11, v[74:75]
	v_lshl_add_u64 v[18:19], v[88:89], 0, v[18:19]
	v_fma_mixlo_f16 v17, v12, v16, 0
	v_mov_b32_e32 v12, v13
	v_mov_b32_e32 v13, v14
	v_lshl_add_u64 v[18:19], v[18:19], 0, s[6:7]
	v_pk_mul_f32 v[12:13], v[12:13], v[16:17] op_sel_hi:[1,0]
	v_lshl_add_u64 v[18:19], v[18:19], 0, v[72:73]
	v_cvt_pk_f16_f32 v13, v12, v13
	v_fma_mixlo_f16 v14, v15, v16, 0
	v_pack_b32_f16 v12, v17, v13
	v_alignbit_b32 v13, v14, v13, 16
	v_add_co_u32_e32 v14, vcc, s70, v18
	v_lshl_add_u64 v[20:21], v[18:19], 0, s[52:53]
	s_nop 0
	v_addc_co_u32_e32 v15, vcc, 0, v19, vcc
	global_store_dwordx2 v[14:15], v[12:13], off offset:1280
	v_fma_mixlo_f16 v12, v8, v16, 0
	v_mov_b32_e32 v8, v9
	v_mov_b32_e32 v9, v10
	v_pk_mul_f32 v[8:9], v[8:9], v[16:17] op_sel_hi:[1,0]
	v_fma_mixlo_f16 v10, v11, v16, 0
	v_cvt_pk_f16_f32 v9, v8, v9
	v_pack_b32_f16 v8, v12, v9
	v_alignbit_b32 v9, v10, v9, 16
	global_store_dwordx2 v[20:21], v[8:9], off offset:32
	v_fma_mixlo_f16 v8, v4, v16, 0
	v_mov_b32_e32 v4, v5
	v_mov_b32_e32 v5, v6
	v_pk_mul_f32 v[4:5], v[4:5], v[16:17] op_sel_hi:[1,0]
	v_fma_mixlo_f16 v6, v7, v16, 0
	v_cvt_pk_f16_f32 v5, v4, v5
	v_pack_b32_f16 v4, v8, v5
	v_alignbit_b32 v5, v6, v5, 16
	global_store_dwordx2 v[20:21], v[4:5], off offset:64
	v_fma_mixlo_f16 v4, v0, v16, 0
	v_mov_b32_e32 v0, v1
	v_mov_b32_e32 v1, v2
	v_pk_mul_f32 v[0:1], v[0:1], v[16:17] op_sel_hi:[1,0]
	v_fma_mixlo_f16 v2, v3, v16, 0
	v_cvt_pk_f16_f32 v1, v0, v1
	v_pack_b32_f16 v0, v4, v1
	v_alignbit_b32 v1, v2, v1, 16
	global_store_dwordx2 v[20:21], v[0:1], off offset:96
	s_cbranch_scc1 .LBB0_688

; __device__ __forceinline__ void phase_prep(const Params& p, int l, float* smem) {
;     ...
;       for (int ks = 0; ks < 2; ++ks) {
;         const int c0 = cb + g * 16 + ks * 8;
;         const f16* pc = proj + (size_t)row * PJ + 768 + c0;
;         f16x8 cur = *(const f16x8*)pc;
;         f16x8 prv, nxt;
; #pragma unroll
;         for (int e = 0; e < 8; ++e) { prv[e] = (f16)0.f; nxt[e] = (f16)0.f; }
;         if (t > 0) prv = *(const f16x8*)(pc - PJ);
;         if (t < len - 1) nxt = *(const f16x8*)(pc + PJ);
;         float4 mp0 = *(const float4*)(mup + c0), mp1 = *(const float4*)(mup + c0 + 4);
;         float4 mn0 = *(const float4*)(mun + c0), mn1 = *(const float4*)(mun + c0 + 4);
;         const float mpa[8] = {mp0.x, mp0.y, mp0.z, mp0.w, mp1.x, mp1.y, mp1.z, mp1.w};
;         const float mna[8] = {mn0.x, mn0.y, mn0.z, mn0.w, mn1.x, mn1.y, mn1.z, mn1.w};
; #pragma unroll
;         for (int e = 0; e < 8; ++e) {
;           float pcv = (float)cur[e];
;           float v = pcv + mpa[e] * ((float)prv[e] - pcv) + mna[e] * ((float)nxt[e] - pcv);
;           if (kind == 0) v = 1.0f - 2.0f / (__expf(2.0f * v) + 1.0f);
;           xf[ks][e] = (f16)v;
;         }
;       }
.LBB0_723:
	s_or_b64 exec, exec, s[8:9]
	global_load_dwordx4 v[24:27], v[30:31], off
	global_load_dwordx4 v[20:23], v[36:37], off
	global_load_dwordx4 v[16:19], v[30:31], off offset:16
	global_load_dwordx4 v[12:15], v[36:37], off offset:16
	s_waitcnt vmcnt(4)
	v_cvt_f32_f16_e32 v48, v0
	v_cvt_f32_f16_e32 v51, v8
	v_cvt_f32_f16_e32 v50, v4
	v_cndmask_b32_e64 v47, 0, 1, s[6:7]
	v_cmp_ne_u32_e64 s[8:9], 1, v47
	s_andn2_b64 vcc, exec, s[6:7]
	v_pk_add_f32 v[50:51], v[50:51], v[48:49] op_sel_hi:[1,0] neg_lo:[0,1] neg_hi:[0,1]
	s_waitcnt vmcnt(3)
	v_mov_b32_e32 v52, v24
	s_waitcnt vmcnt(2)
	v_mov_b32_e32 v53, v20
	v_pk_mul_f32 v[50:51], v[50:51], v[52:53]
	s_nop 0
	v_add_f32_e32 v20, v50, v48
	v_add_f32_e32 v47, v20, v51
	s_cbranch_vccnz .LBB0_725
	v_add_f32_e32 v20, v47, v47
	v_mul_f32_e32 v20, 0x3fb8aa3b, v20
	v_exp_f32_e32 v20, v20
	s_nop 0
	v_add_f32_e32 v20, 1.0, v20
	v_rcp_f32_e32 v47, v20
	s_nop 0
	v_mul_f32_e32 v24, 2.0, v47
	v_mov_b32_e32 v20, v24
	v_sub_f32_e32 v47, 1.0, v20
.LBB0_725:
	v_cvt_f32_f16_sdwa v0, v0 dst_sel:DWORD dst_unused:UNUSED_PAD src0_sel:WORD_1
	v_cvt_f32_f16_sdwa v49, v8 dst_sel:DWORD dst_unused:UNUSED_PAD src0_sel:WORD_1
	v_cvt_f32_f16_sdwa v48, v4 dst_sel:DWORD dst_unused:UNUSED_PAD src0_sel:WORD_1
	v_mov_b32_e32 v20, v25
	s_and_b64 vcc, exec, s[8:9]
	v_pk_add_f32 v[24:25], v[48:49], v[0:1] op_sel_hi:[1,0] neg_lo:[0,1] neg_hi:[0,1]
	s_nop 0
	v_pk_mul_f32 v[20:21], v[24:25], v[20:21]
	s_nop 0
	v_add_f32_e32 v0, v20, v0
	v_add_f32_e32 v48, v0, v21
	s_cbranch_vccnz .LBB0_727
	v_add_f32_e32 v0, v48, v48
	v_mul_f32_e32 v0, 0x3fb8aa3b, v0
	v_exp_f32_e32 v0, v0
	s_nop 0
	v_add_f32_e32 v0, 1.0, v0
	v_rcp_f32_e32 v8, v0
	s_nop 0
	v_mul_f32_e32 v4, 2.0, v8
	v_mov_b32_e32 v0, v4
	v_sub_f32_e32 v48, 1.0, v0
.LBB0_727:
	v_cvt_f32_f16_e32 v0, v1
	v_cvt_f32_f16_e32 v21, v9
	v_cvt_f32_f16_e32 v20, v5
	v_mov_b32_e32 v24, v26
	v_mov_b32_e32 v25, v22
	s_and_b64 vcc, exec, s[8:9]
	v_pk_add_f32 v[20:21], v[20:21], v[0:1] op_sel_hi:[1,0] neg_lo:[0,1] neg_hi:[0,1]
	s_nop 0
	v_pk_mul_f32 v[20:21], v[20:21], v[24:25]
	s_nop 0
	v_add_f32_e32 v0, v20, v0
	v_add_f32_e32 v49, v0, v21
	s_cbranch_vccnz .LBB0_729
	v_add_f32_e32 v0, v49, v49
	v_mul_f32_e32 v0, 0x3fb8aa3b, v0
	v_exp_f32_e32 v0, v0
	s_nop 0
	v_add_f32_e32 v0, 1.0, v0
	v_rcp_f32_e32 v8, v0
	s_nop 0
	v_mul_f32_e32 v4, 2.0, v8
	v_mov_b32_e32 v0, v4
	v_sub_f32_e32 v49, 1.0, v0
.LBB0_729:
	v_cvt_f32_f16_sdwa v0, v1 dst_sel:DWORD dst_unused:UNUSED_PAD src0_sel:WORD_1
	v_cvt_f32_f16_sdwa v9, v9 dst_sel:DWORD dst_unused:UNUSED_PAD src0_sel:WORD_1
	v_cvt_f32_f16_sdwa v8, v5 dst_sel:DWORD dst_unused:UNUSED_PAD src0_sel:WORD_1
	v_mov_b32_e32 v22, v27
	s_and_b64 vcc, exec, s[8:9]
	v_pk_add_f32 v[4:5], v[8:9], v[0:1] op_sel_hi:[1,0] neg_lo:[0,1] neg_hi:[0,1]
	s_nop 0
	v_pk_mul_f32 v[4:5], v[4:5], v[22:23]
	s_nop 0
	v_add_f32_e32 v0, v4, v0
	v_add_f32_e32 v50, v0, v5
	s_cbranch_vccnz .LBB0_731
	v_add_f32_e32 v0, v50, v50
	v_mul_f32_e32 v0, 0x3fb8aa3b, v0
	v_exp_f32_e32 v0, v0
	s_nop 0
	v_add_f32_e32 v0, 1.0, v0
	v_rcp_f32_e32 v4, v0
	s_nop 0
	v_mul_f32_e32 v1, 2.0, v4
	v_mov_b32_e32 v0, v1
	v_sub_f32_e32 v50, 1.0, v0
.LBB0_731:
	v_cvt_f32_f16_e32 v0, v2
	v_cvt_f32_f16_e32 v5, v10
	v_cvt_f32_f16_e32 v4, v6
	s_waitcnt vmcnt(1)
	v_mov_b32_e32 v8, v16
	s_waitcnt vmcnt(0)
	v_mov_b32_e32 v9, v12
	s_and_b64 vcc, exec, s[8:9]
	v_pk_add_f32 v[4:5], v[4:5], v[0:1] op_sel_hi:[1,0] neg_lo:[0,1] neg_hi:[0,1]
	s_nop 0
	v_pk_mul_f32 v[4:5], v[4:5], v[8:9]
	s_nop 0
	v_add_f32_e32 v0, v4, v0
	v_add_f32_e32 v51, v0, v5
	s_cbranch_vccnz .LBB0_733
	v_add_f32_e32 v0, v51, v51
	v_mul_f32_e32 v0, 0x3fb8aa3b, v0
	v_exp_f32_e32 v0, v0
	s_nop 0
	v_add_f32_e32 v0, 1.0, v0
	v_rcp_f32_e32 v4, v0
	s_nop 0
	v_mul_f32_e32 v1, 2.0, v4
	v_mov_b32_e32 v0, v1
	v_sub_f32_e32 v51, 1.0, v0
.LBB0_733:
	v_cvt_f32_f16_sdwa v0, v2 dst_sel:DWORD dst_unused:UNUSED_PAD src0_sel:WORD_1
	v_cvt_f32_f16_sdwa v5, v10 dst_sel:DWORD dst_unused:UNUSED_PAD src0_sel:WORD_1
	v_cvt_f32_f16_sdwa v4, v6 dst_sel:DWORD dst_unused:UNUSED_PAD src0_sel:WORD_1
	v_mov_b32_e32 v12, v17
	s_and_b64 vcc, exec, s[8:9]
	v_pk_add_f32 v[4:5], v[4:5], v[0:1] op_sel_hi:[1,0] neg_lo:[0,1] neg_hi:[0,1]
	s_nop 0
	v_pk_mul_f32 v[4:5], v[4:5], v[12:13]
	s_nop 0
	v_add_f32_e32 v0, v4, v0
	v_add_f32_e32 v52, v0, v5
	s_cbranch_vccnz .LBB0_735
	v_add_f32_e32 v0, v52, v52
	v_mul_f32_e32 v0, 0x3fb8aa3b, v0
	v_exp_f32_e32 v0, v0
	s_nop 0
	v_add_f32_e32 v0, 1.0, v0
	v_rcp_f32_e32 v2, v0
	s_nop 0
	v_mul_f32_e32 v1, 2.0, v2
	v_mov_b32_e32 v0, v1
	v_sub_f32_e32 v52, 1.0, v0
.LBB0_735:
	v_cvt_f32_f16_e32 v0, v3
	v_cvt_f32_f16_e32 v5, v11
	v_cvt_f32_f16_e32 v4, v7
	v_mov_b32_e32 v8, v18
	v_mov_b32_e32 v9, v14
	s_and_b64 vcc, exec, s[8:9]
	v_pk_add_f32 v[4:5], v[4:5], v[0:1] op_sel_hi:[1,0] neg_lo:[0,1] neg_hi:[0,1]
	s_nop 0
	v_pk_mul_f32 v[4:5], v[4:5], v[8:9]
	s_nop 0
	v_add_f32_e32 v0, v4, v0
	v_add_f32_e32 v53, v0, v5
	s_cbranch_vccnz .LBB0_737
	v_add_f32_e32 v0, v53, v53
	v_mul_f32_e32 v0, 0x3fb8aa3b, v0
	v_exp_f32_e32 v0, v0
	s_nop 0
	v_add_f32_e32 v0, 1.0, v0
	v_rcp_f32_e32 v2, v0
	s_nop 0
	v_mul_f32_e32 v1, 2.0, v2
	v_mov_b32_e32 v0, v1
	v_sub_f32_e32 v53, 1.0, v0
.LBB0_737:
	v_cvt_f32_f16_sdwa v0, v3 dst_sel:DWORD dst_unused:UNUSED_PAD src0_sel:WORD_1
	v_cvt_f32_f16_sdwa v3, v11 dst_sel:DWORD dst_unused:UNUSED_PAD src0_sel:WORD_1
	v_cvt_f32_f16_sdwa v2, v7 dst_sel:DWORD dst_unused:UNUSED_PAD src0_sel:WORD_1
	v_mov_b32_e32 v14, v19
	s_and_b64 vcc, exec, s[8:9]
	v_pk_add_f32 v[2:3], v[2:3], v[0:1] op_sel_hi:[1,0] neg_lo:[0,1] neg_hi:[0,1]
	s_nop 0
	v_pk_mul_f32 v[2:3], v[2:3], v[14:15]
	s_nop 0
	v_add_f32_e32 v0, v2, v0
	v_add_f32_e32 v54, v0, v3
	s_cbranch_vccnz .LBB0_739
	v_add_f32_e32 v0, v54, v54
	v_mul_f32_e32 v0, 0x3fb8aa3b, v0
	v_exp_f32_e32 v0, v0
	s_nop 0
	v_add_f32_e32 v0, 1.0, v0
	v_rcp_f32_e32 v2, v0
	s_nop 0
	v_mul_f32_e32 v1, 2.0, v2
	v_mov_b32_e32 v0, v1
	v_sub_f32_e32 v54, 1.0, v0

; __device__ __forceinline__ void phase_prep(const Params& p, int l, float* smem) {
;     ...
;       for (int ks = 0; ks < 2; ++ks) {
;         const int c0 = cb + g * 16 + ks * 8;
;         const f16* pc = proj + (size_t)row * PJ + 768 + c0;
;         f16x8 cur = *(const f16x8*)pc;
;         f16x8 prv, nxt;
; #pragma unroll
;         for (int e = 0; e < 8; ++e) { prv[e] = (f16)0.f; nxt[e] = (f16)0.f; }
;         if (t > 0) prv = *(const f16x8*)(pc - PJ);
;         if (t < len - 1) nxt = *(const f16x8*)(pc + PJ);
;         float4 mp0 = *(const float4*)(mup + c0), mp1 = *(const float4*)(mup + c0 + 4);
;         float4 mn0 = *(const float4*)(mun + c0), mn1 = *(const float4*)(mun + c0 + 4);
;         const float mpa[8] = {mp0.x, mp0.y, mp0.z, mp0.w, mp1.x, mp1.y, mp1.z, mp1.w};
;         const float mna[8] = {mn0.x, mn0.y, mn0.z, mn0.w, mn1.x, mn1.y, mn1.z, mn1.w};
; #pragma unroll
;         for (int e = 0; e < 8; ++e) {
;           float pcv = (float)cur[e];
;           float v = pcv + mpa[e] * ((float)prv[e] - pcv) + mna[e] * ((float)nxt[e] - pcv);
;           if (kind == 0) v = 1.0f - 2.0f / (__expf(2.0f * v) + 1.0f);
;           xf[ks][e] = (f16)v;
;         }
;       }
.LBB0_743:
	s_or_b64 exec, exec, s[10:11]
	global_load_dwordx4 v[24:27], v[30:31], off offset:32
	global_load_dwordx4 v[20:23], v[36:37], off offset:32
	global_load_dwordx4 v[16:19], v[30:31], off offset:48
	global_load_dwordx4 v[12:15], v[36:37], off offset:48
	s_waitcnt vmcnt(4)
	v_cvt_f32_f16_e32 v44, v0
	v_cvt_f32_f16_e32 v57, v8
	v_cvt_f32_f16_e32 v56, v4
	s_and_b64 vcc, exec, s[8:9]
	v_pk_add_f32 v[56:57], v[56:57], v[44:45] op_sel_hi:[1,0] neg_lo:[0,1] neg_hi:[0,1]
	s_waitcnt vmcnt(3)
	v_mov_b32_e32 v58, v24
	s_waitcnt vmcnt(2)
	v_mov_b32_e32 v59, v20
	v_pk_mul_f32 v[56:57], v[56:57], v[58:59]
	s_nop 0
	v_add_f32_e32 v20, v56, v44
	v_add_f32_e32 v24, v20, v57
	s_cbranch_vccnz .LBB0_745
	v_add_f32_e32 v20, v24, v24
	v_mul_f32_e32 v20, 0x3fb8aa3b, v20
	v_exp_f32_e32 v20, v20
	s_nop 0
	v_add_f32_e32 v20, 1.0, v20
	v_rcp_f32_e32 v44, v20
	s_nop 0
	v_mul_f32_e32 v24, 2.0, v44
	v_mov_b32_e32 v20, v24
	v_sub_f32_e32 v24, 1.0, v20
.LBB0_745:
	v_cvt_f32_f16_sdwa v0, v0 dst_sel:DWORD dst_unused:UNUSED_PAD src0_sel:WORD_1
	v_cvt_f32_f16_sdwa v45, v8 dst_sel:DWORD dst_unused:UNUSED_PAD src0_sel:WORD_1
	v_cvt_f32_f16_sdwa v44, v4 dst_sel:DWORD dst_unused:UNUSED_PAD src0_sel:WORD_1
	v_mov_b32_e32 v20, v25
	s_and_b64 vcc, exec, s[8:9]
	v_pk_add_f32 v[44:45], v[44:45], v[0:1] op_sel_hi:[1,0] neg_lo:[0,1] neg_hi:[0,1]
	s_nop 0
	v_pk_mul_f32 v[20:21], v[44:45], v[20:21]
	s_nop 0
	v_add_f32_e32 v0, v20, v0
	v_add_f32_e32 v4, v0, v21
	s_cbranch_vccnz .LBB0_747
	v_add_f32_e32 v0, v4, v4
	v_mul_f32_e32 v0, 0x3fb8aa3b, v0
	v_exp_f32_e32 v0, v0
	s_nop 0
	v_add_f32_e32 v0, 1.0, v0
	v_rcp_f32_e32 v8, v0
	s_nop 0
	v_mul_f32_e32 v4, 2.0, v8
	v_mov_b32_e32 v0, v4
	v_sub_f32_e32 v4, 1.0, v0
.LBB0_747:
	v_cvt_f32_f16_e32 v0, v1
	v_cvt_f32_f16_e32 v21, v9
	v_cvt_f32_f16_e32 v20, v5
	v_mov_b32_e32 v44, v26
	v_mov_b32_e32 v45, v22
	s_and_b64 vcc, exec, s[8:9]
	v_pk_add_f32 v[20:21], v[20:21], v[0:1] op_sel_hi:[1,0] neg_lo:[0,1] neg_hi:[0,1]
	s_nop 0
	v_pk_mul_f32 v[20:21], v[20:21], v[44:45]
	s_nop 0
	v_add_f32_e32 v0, v20, v0
	v_add_f32_e32 v8, v0, v21
	s_cbranch_vccnz .LBB0_749
	v_add_f32_e32 v0, v8, v8
	v_mul_f32_e32 v0, 0x3fb8aa3b, v0
	v_exp_f32_e32 v0, v0
	s_nop 0
	v_add_f32_e32 v0, 1.0, v0
	v_rcp_f32_e32 v20, v0
	s_nop 0
	v_mul_f32_e32 v8, 2.0, v20
	v_mov_b32_e32 v0, v8
	v_sub_f32_e32 v8, 1.0, v0
.LBB0_749:
	v_cvt_f32_f16_sdwa v0, v1 dst_sel:DWORD dst_unused:UNUSED_PAD src0_sel:WORD_1
	v_cvt_f32_f16_sdwa v21, v9 dst_sel:DWORD dst_unused:UNUSED_PAD src0_sel:WORD_1
	v_cvt_f32_f16_sdwa v20, v5 dst_sel:DWORD dst_unused:UNUSED_PAD src0_sel:WORD_1
	v_mov_b32_e32 v22, v27
	s_and_b64 vcc, exec, s[8:9]
	v_pk_add_f32 v[20:21], v[20:21], v[0:1] op_sel_hi:[1,0] neg_lo:[0,1] neg_hi:[0,1]
	s_nop 0
	v_pk_mul_f32 v[20:21], v[20:21], v[22:23]
	s_nop 0
	v_add_f32_e32 v0, v20, v0
	v_add_f32_e32 v5, v0, v21
	s_cbranch_vccnz .LBB0_751
	v_add_f32_e32 v0, v5, v5
	v_mul_f32_e32 v0, 0x3fb8aa3b, v0
	v_exp_f32_e32 v0, v0
	s_nop 0
	v_add_f32_e32 v0, 1.0, v0
	v_rcp_f32_e32 v5, v0
	s_nop 0
	v_mul_f32_e32 v1, 2.0, v5
	v_mov_b32_e32 v0, v1
	v_sub_f32_e32 v5, 1.0, v0
.LBB0_751:
	v_cvt_f32_f16_e32 v0, v2
	v_cvt_f32_f16_e32 v21, v10
	v_cvt_f32_f16_e32 v20, v6
	s_waitcnt vmcnt(1)
	v_mov_b32_e32 v22, v16
	s_waitcnt vmcnt(0)
	v_mov_b32_e32 v23, v12
	s_and_b64 vcc, exec, s[8:9]
	v_pk_add_f32 v[20:21], v[20:21], v[0:1] op_sel_hi:[1,0] neg_lo:[0,1] neg_hi:[0,1]
	s_nop 0
	v_pk_mul_f32 v[20:21], v[20:21], v[22:23]
	s_nop 0
	v_add_f32_e32 v0, v20, v0
	v_add_f32_e32 v9, v0, v21
	s_cbranch_vccnz .LBB0_753
	v_add_f32_e32 v0, v9, v9
	v_mul_f32_e32 v0, 0x3fb8aa3b, v0
	v_exp_f32_e32 v0, v0
	s_nop 0
	v_add_f32_e32 v0, 1.0, v0
	v_rcp_f32_e32 v9, v0
	s_nop 0
	v_mul_f32_e32 v1, 2.0, v9
	v_mov_b32_e32 v0, v1
	v_sub_f32_e32 v9, 1.0, v0
.LBB0_753:
	v_cvt_f32_f16_sdwa v0, v2 dst_sel:DWORD dst_unused:UNUSED_PAD src0_sel:WORD_1
	v_cvt_f32_f16_sdwa v21, v10 dst_sel:DWORD dst_unused:UNUSED_PAD src0_sel:WORD_1
	v_cvt_f32_f16_sdwa v20, v6 dst_sel:DWORD dst_unused:UNUSED_PAD src0_sel:WORD_1
	v_mov_b32_e32 v12, v17
	s_and_b64 vcc, exec, s[8:9]
	v_pk_add_f32 v[16:17], v[20:21], v[0:1] op_sel_hi:[1,0] neg_lo:[0,1] neg_hi:[0,1]
	s_nop 0
	v_pk_mul_f32 v[12:13], v[16:17], v[12:13]
	s_nop 0
	v_add_f32_e32 v0, v12, v0
	v_add_f32_e32 v6, v0, v13
	s_cbranch_vccnz .LBB0_755
	v_add_f32_e32 v0, v6, v6
	v_mul_f32_e32 v0, 0x3fb8aa3b, v0
	v_exp_f32_e32 v0, v0
	s_nop 0
	v_add_f32_e32 v0, 1.0, v0
	v_rcp_f32_e32 v2, v0
	s_nop 0
	v_mul_f32_e32 v1, 2.0, v2
	v_mov_b32_e32 v0, v1
	v_sub_f32_e32 v6, 1.0, v0
.LBB0_755:
	v_cvt_f32_f16_e32 v0, v3
	v_cvt_f32_f16_e32 v13, v11
	v_cvt_f32_f16_e32 v12, v7
	v_mov_b32_e32 v16, v18
	v_mov_b32_e32 v17, v14
	s_and_b64 vcc, exec, s[8:9]
	v_pk_add_f32 v[12:13], v[12:13], v[0:1] op_sel_hi:[1,0] neg_lo:[0,1] neg_hi:[0,1]
	s_nop 0
	v_pk_mul_f32 v[12:13], v[12:13], v[16:17]
	s_nop 0
	v_add_f32_e32 v0, v12, v0
	v_add_f32_e32 v12, v0, v13
	s_cbranch_vccnz .LBB0_757
	v_add_f32_e32 v0, v12, v12
	v_mul_f32_e32 v0, 0x3fb8aa3b, v0
	v_exp_f32_e32 v0, v0
	s_nop 0
	v_add_f32_e32 v0, 1.0, v0
	v_rcp_f32_e32 v2, v0
	s_nop 0
	v_mul_f32_e32 v1, 2.0, v2
	v_mov_b32_e32 v0, v1
	v_sub_f32_e32 v12, 1.0, v0
.LBB0_757:
	v_cvt_f32_f16_sdwa v0, v3 dst_sel:DWORD dst_unused:UNUSED_PAD src0_sel:WORD_1
	v_cvt_f32_f16_sdwa v3, v11 dst_sel:DWORD dst_unused:UNUSED_PAD src0_sel:WORD_1
	v_cvt_f32_f16_sdwa v2, v7 dst_sel:DWORD dst_unused:UNUSED_PAD src0_sel:WORD_1
	v_mov_b32_e32 v14, v19
	s_and_b64 vcc, exec, s[8:9]
	s_mov_b64 s[8:9], 0x1b2c0000
	v_pk_add_f32 v[2:3], v[2:3], v[0:1] op_sel_hi:[1,0] neg_lo:[0,1] neg_hi:[0,1]
	s_nop 0
	v_pk_mul_f32 v[2:3], v[2:3], v[14:15]
	s_nop 0
	v_add_f32_e32 v0, v2, v0
	v_add_f32_e32 v7, v0, v3
	s_cbranch_vccnz .LBB0_759
	v_add_f32_e32 v0, v7, v7
	v_mul_f32_e32 v0, 0x3fb8aa3b, v0
	v_exp_f32_e32 v0, v0
	s_nop 0
	v_add_f32_e32 v0, 1.0, v0
	s_mov_b64 s[8:9], 0x18200000
	v_rcp_f32_e32 v2, v0
	s_nop 0
	v_mul_f32_e32 v1, 2.0, v2
	v_mov_b32_e32 v0, v1
	v_sub_f32_e32 v7, 1.0, v0
	v_mov_b64_e32 v[10:11], v[34:35]
	s_branch .LBB0_760

; __device__ __forceinline__ float sigmoidf_(float x) { return 1.0f / (1.0f + __expf(-x)); }
; __device__ __forceinline__ void phase_prep(const Params& p, int l, float* smem) {
;     ...
;       const f16* wbase = lwt + (size_t)m * RD * 64;
;       const float* bias = (kind == 0 ? p.in[I_DW0] : p.in[I_A0]) + ((size_t)l * 2 + z) * RD;
;       f16* dst = (kind == 0 ? dE : dA) + ((size_t)z * NTOK + row) * RD;
; #pragma unroll 4
;       for (int nb = 0; nb < 24; ++nb) {
;         const f16* wp = wbase + (size_t)(nb * 16 + lq) * 64 + g * 16;
;         f16x8 w0 = *(const f16x8*)wp, w1 = *(const f16x8*)(wp + 8);
;         f32x4 a = f32x4{0.f, 0.f, 0.f, 0.f};
;         a = __builtin_amdgcn_mfma_f32_16x16x32_f16(w0, xf[0], a, 0, 0, 0);
;         a = __builtin_amdgcn_mfma_f32_16x16x32_f16(w1, xf[1], a, 0, 0, 0);
;         const int c = nb * 16 + 4 * g;
;         float4 b4 = *(const float4*)(bias + c);
;         const float ba[4] = {b4.x, b4.y, b4.z, b4.w};
;         f16x4 o4;
; #pragma unroll
;         for (int i = 0; i < 4; ++i) {
;           float xv = ba[i] + a[i];
;           if (kind == 0) {
;             o4[i] = (f16)(0.60653065971f * sigmoidf_(xv));
;           } else {
;             o4[i] = (f16)sigmoidf_(xv);
;           }
;         }
;         *(f16x4*)(dst + c) = o4;
;       }
.LBB0_761:
	v_lshl_add_u64 v[18:19], v[28:29], 0, v[12:13]
	v_add_co_u32_e32 v20, vcc, 0x1eda8000, v18
	s_nop 1
	v_addc_co_u32_e32 v21, vcc, 0, v19, vcc
	global_load_dwordx4 v[14:17], v[20:21], off
	global_load_dwordx4 v[22:25], v[20:21], off offset:16
	s_waitcnt vmcnt(1)
	v_mfma_f32_16x16x32_f16 v[14:17], v[14:17], v[0:3], 0
	s_waitcnt vmcnt(0)
	v_mfma_f32_16x16x32_f16 v[22:25], v[22:25], v[4:7], v[14:17]
	s_nop 5
	v_lshl_add_u64 v[14:15], v[10:11], 0, s[8:9]
	global_load_dwordx4 v[48:51], v[14:15], off
	s_add_u32 s8, s8, 0x100
	s_addc_u32 s9, s9, 0
	s_cmpk_eq_i32 s8, 0x600
	s_waitcnt vmcnt(0)
	v_add_f32_e32 v16, v22, v48
	v_mul_f32_e32 v16, 0xbfb8aa3b, v16
	v_exp_f32_e32 v16, v16
	s_nop 0
	v_add_f32_e32 v16, 1.0, v16
	s_nop 0
	v_rcp_f32_e32 v22, v16
	s_nop 0
	v_mul_f32_e32 v17, 1.0, v22
	v_mov_b32_e32 v16, v17
	v_mul_f32_e32 v17, 0x3f1b4598, v16
	v_cndmask_b32_e64 v16, v16, v17, s[6:7]
	v_add_f32_e32 v17, v23, v49
	v_mul_f32_e32 v17, 0xbfb8aa3b, v17
	v_exp_f32_e32 v17, v17
	s_nop 0
	v_add_f32_e32 v17, 1.0, v17
	s_nop 0
	v_rcp_f32_e32 v23, v17
	s_nop 0
	v_mul_f32_e32 v22, 1.0, v23
	v_mov_b32_e32 v17, v22
	v_mul_f32_e32 v22, 0x3f1b4598, v17
	v_cndmask_b32_e64 v17, v17, v22, s[6:7]
	v_add_f32_e32 v22, v24, v50
	v_mul_f32_e32 v22, 0xbfb8aa3b, v22
	v_exp_f32_e32 v22, v22
	s_nop 0
	v_add_f32_e32 v22, 1.0, v22
	s_nop 0
	v_rcp_f32_e32 v24, v22
	s_nop 0
	v_mul_f32_e32 v23, 1.0, v24
	v_mov_b32_e32 v22, v23
	v_mul_f32_e32 v23, 0x3f1b4598, v22
	v_cndmask_b32_e64 v22, v22, v23, s[6:7]
	v_add_f32_e32 v23, v25, v51
	v_mul_f32_e32 v23, 0xbfb8aa3b, v23
	v_exp_f32_e32 v23, v23
	s_nop 0
	v_add_f32_e32 v23, 1.0, v23
	s_nop 0
	v_rcp_f32_e32 v25, v23
	s_nop 0
	v_mul_f32_e32 v24, 1.0, v25
	v_mov_b32_e32 v23, v24
	v_mul_f32_e32 v24, 0x3f1b4598, v23
	v_cndmask_b32_e64 v23, v23, v24, s[6:7]
	v_cvt_pk_f16_f32 v23, v22, v23
	v_cvt_pk_f16_f32 v22, v16, v17
	v_lshl_add_u64 v[16:17], v[28:29], 0, v[8:9]
	global_store_dwordx2 v[16:17], v[22:23], off
	global_load_dwordx4 v[22:25], v[20:21], off offset:2048
	s_nop 0
	global_load_dwordx4 v[48:51], v[20:21], off offset:2064
	v_lshl_add_u64 v[8:9], v[8:9], 0, s[84:85]
	s_waitcnt vmcnt(1)
	v_mfma_f32_16x16x32_f16 v[20:23], v[22:25], v[0:3], 0
	global_load_dwordx4 v[24:27], v[14:15], off offset:64
	s_waitcnt vmcnt(1)
	v_mfma_f32_16x16x32_f16 v[20:23], v[48:51], v[4:7], v[20:23]
	s_waitcnt vmcnt(0)
	s_nop 6
	v_add_f32_e32 v20, v20, v24
	v_mul_f32_e32 v20, 0xbfb8aa3b, v20
	v_exp_f32_e32 v20, v20
	v_add_f32_e32 v21, v21, v25
	v_mul_f32_e32 v21, 0xbfb8aa3b, v21
	v_exp_f32_e32 v21, v21
	v_add_f32_e32 v20, 1.0, v20
	v_add_f32_e32 v21, 1.0, v21
	v_rcp_f32_e32 v44, v20
	s_nop 0
	v_mul_f32_e32 v24, 1.0, v44
	v_mov_b32_e32 v20, v24
	v_mul_f32_e32 v24, 0x3f1b4598, v20
	v_cndmask_b32_e64 v20, v20, v24, s[6:7]
	s_nop 0
	v_rcp_f32_e32 v25, v21
	s_nop 0
	v_mul_f32_e32 v24, 1.0, v25
	v_mov_b32_e32 v21, v24
	v_mul_f32_e32 v24, 0x3f1b4598, v21
	v_cndmask_b32_e64 v24, v21, v24, s[6:7]
	v_add_f32_e32 v21, v22, v26
	v_mul_f32_e32 v21, 0xbfb8aa3b, v21
	v_exp_f32_e32 v21, v21
	v_cvt_pk_f16_f32 v20, v20, v24
	v_add_f32_e32 v21, 1.0, v21
	s_nop 0
	v_rcp_f32_e32 v25, v21
	s_nop 0
	v_mul_f32_e32 v22, 1.0, v25
	v_mov_b32_e32 v21, v22
	v_mul_f32_e32 v22, 0x3f1b4598, v21
	v_cndmask_b32_e64 v21, v21, v22, s[6:7]
	v_add_f32_e32 v22, v23, v27
	v_mul_f32_e32 v22, 0xbfb8aa3b, v22
	v_exp_f32_e32 v22, v22
	s_nop 0
	v_add_f32_e32 v22, 1.0, v22
	s_mov_b32 s10, 0x1eda9000
	v_rcp_f32_e32 v25, v22
	s_nop 0
	v_mul_f32_e32 v23, 1.0, v25
	v_mov_b32_e32 v22, v23
	v_mul_f32_e32 v23, 0x3f1b4598, v22
	v_cndmask_b32_e64 v22, v22, v23, s[6:7]
	v_cvt_pk_f16_f32 v21, v21, v22
	v_add_co_u32_e32 v18, vcc, s10, v18
	global_store_dwordx2 v[16:17], v[20:21], off offset:32
	s_nop 0
	v_addc_co_u32_e32 v19, vcc, 0, v19, vcc
	global_load_dwordx4 v[20:23], v[18:19], off
	global_load_dwordx4 v[24:27], v[18:19], off offset:16
	s_waitcnt vmcnt(1)
; __device__ __forceinline__ float sigmoidf_(float x) { return 1.0f / (1.0f + __expf(-x)); }
; __device__ __forceinline__ void phase_prep(const Params& p, int l, float* smem) {
;     ...
;     for (int it = gw; it < (NTOK / 16) * 4; it += nw) {
;     ...
;       const f16* wbase = lwt + (size_t)m * RD * 64;
;       const float* bias = (kind == 0 ? p.in[I_DW0] : p.in[I_A0]) + ((size_t)l * 2 + z) * RD;
;       f16* dst = (kind == 0 ? dE : dA) + ((size_t)z * NTOK + row) * RD;
; #pragma unroll 4
;       for (int nb = 0; nb < 24; ++nb) {
;         const f16* wp = wbase + (size_t)(nb * 16 + lq) * 64 + g * 16;
;         f16x8 w0 = *(const f16x8*)wp, w1 = *(const f16x8*)(wp + 8);
;         f32x4 a = f32x4{0.f, 0.f, 0.f, 0.f};
;         a = __builtin_amdgcn_mfma_f32_16x16x32_f16(w0, xf[0], a, 0, 0, 0);
;         a = __builtin_amdgcn_mfma_f32_16x16x32_f16(w1, xf[1], a, 0, 0, 0);
;         const int c = nb * 16 + 4 * g;
;         float4 b4 = *(const float4*)(bias + c);
;         const float ba[4] = {b4.x, b4.y, b4.z, b4.w};
;         f16x4 o4;
; #pragma unroll
;         for (int i = 0; i < 4; ++i) {
;           float xv = ba[i] + a[i];
;           if (kind == 0) {
;             o4[i] = (f16)(0.60653065971f * sigmoidf_(xv));
;           } else {
;             o4[i] = (f16)sigmoidf_(xv);
;           }
;         }
;         *(f16x4*)(dst + c) = o4;
;       }
	v_mfma_f32_16x16x32_f16 v[20:23], v[20:23], v[0:3], 0
	s_waitcnt vmcnt(0)
	v_mfma_f32_16x16x32_f16 v[20:23], v[24:27], v[4:7], v[20:23]
	global_load_dwordx4 v[24:27], v[14:15], off offset:128
	s_waitcnt vmcnt(0)
	s_nop 5
	v_add_f32_e32 v20, v20, v24
	v_mul_f32_e32 v20, 0xbfb8aa3b, v20
	v_exp_f32_e32 v20, v20
	v_add_f32_e32 v21, v21, v25
	v_mul_f32_e32 v21, 0xbfb8aa3b, v21
	v_exp_f32_e32 v21, v21
	v_add_f32_e32 v20, 1.0, v20
	v_add_f32_e32 v21, 1.0, v21
	v_rcp_f32_e32 v44, v20
	s_nop 0
	v_mul_f32_e32 v24, 1.0, v44
	v_mov_b32_e32 v20, v24
	v_mul_f32_e32 v24, 0x3f1b4598, v20
	v_cndmask_b32_e64 v20, v20, v24, s[6:7]
	s_nop 0
	v_rcp_f32_e32 v25, v21
	s_nop 0
	v_mul_f32_e32 v24, 1.0, v25
	v_mov_b32_e32 v21, v24
	v_mul_f32_e32 v24, 0x3f1b4598, v21
	v_cndmask_b32_e64 v24, v21, v24, s[6:7]
	v_add_f32_e32 v21, v22, v26
	v_mul_f32_e32 v21, 0xbfb8aa3b, v21
	v_exp_f32_e32 v21, v21
	v_cvt_pk_f16_f32 v20, v20, v24
	v_add_f32_e32 v21, 1.0, v21
	s_nop 0
	v_rcp_f32_e32 v25, v21
	s_nop 0
	v_mul_f32_e32 v22, 1.0, v25
	v_mov_b32_e32 v21, v22
	v_mul_f32_e32 v22, 0x3f1b4598, v21
	v_cndmask_b32_e64 v21, v21, v22, s[6:7]
	v_add_f32_e32 v22, v23, v27
	v_mul_f32_e32 v22, 0xbfb8aa3b, v22
	v_exp_f32_e32 v22, v22
	s_nop 0
	v_add_f32_e32 v22, 1.0, v22
	s_nop 0
	v_rcp_f32_e32 v25, v22
	s_nop 0
	v_mul_f32_e32 v23, 1.0, v25
	v_mov_b32_e32 v22, v23
	v_mul_f32_e32 v23, 0x3f1b4598, v22
	v_cndmask_b32_e64 v22, v22, v23, s[6:7]
	v_cvt_pk_f16_f32 v21, v21, v22
	global_store_dwordx2 v[16:17], v[20:21], off offset:64
	global_load_dwordx4 v[20:23], v[18:19], off offset:2048
	s_nop 0
	global_load_dwordx4 v[24:27], v[18:19], off offset:2064
	s_waitcnt vmcnt(1)
	v_mfma_f32_16x16x32_f16 v[18:21], v[20:23], v[0:3], 0
	s_waitcnt vmcnt(0)
	v_mfma_f32_16x16x32_f16 v[18:21], v[24:27], v[4:7], v[18:21]
	global_load_dwordx4 v[22:25], v[14:15], off offset:192
	s_waitcnt vmcnt(0)
	s_nop 5
	v_add_f32_e32 v14, v18, v22
	v_mul_f32_e32 v14, 0xbfb8aa3b, v14
	v_exp_f32_e32 v14, v14
	s_nop 0
	v_add_f32_e32 v14, 1.0, v14
	s_nop 0
	v_rcp_f32_e32 v18, v14
	s_nop 0
	v_mul_f32_e32 v15, 1.0, v18
	v_mov_b32_e32 v14, v15
	v_mul_f32_e32 v15, 0x3f1b4598, v14
	v_cndmask_b32_e64 v14, v14, v15, s[6:7]
	v_add_f32_e32 v15, v19, v23
	v_mul_f32_e32 v15, 0xbfb8aa3b, v15
	v_exp_f32_e32 v15, v15
	s_nop 0
	v_add_f32_e32 v15, 1.0, v15
	s_nop 0
	v_rcp_f32_e32 v19, v15
	s_nop 0
	v_mul_f32_e32 v18, 1.0, v19
	v_mov_b32_e32 v15, v18
	v_mul_f32_e32 v18, 0x3f1b4598, v15
	v_cndmask_b32_e64 v18, v15, v18, s[6:7]
	v_add_f32_e32 v15, v20, v24
	v_mul_f32_e32 v15, 0xbfb8aa3b, v15
	v_exp_f32_e32 v15, v15
	v_cvt_pk_f16_f32 v14, v14, v18
	v_add_f32_e32 v15, 1.0, v15
	s_nop 0
	v_rcp_f32_e32 v20, v15
	s_nop 0
	v_mul_f32_e32 v19, 1.0, v20
	v_mov_b32_e32 v15, v19
	v_mul_f32_e32 v19, 0x3f1b4598, v15
	v_cndmask_b32_e64 v15, v15, v19, s[6:7]
	v_add_f32_e32 v19, v21, v25
	v_mul_f32_e32 v19, 0xbfb8aa3b, v19
	v_exp_f32_e32 v19, v19
	s_nop 0
	v_add_f32_e32 v19, 1.0, v19
	s_mov_b64 s[10:11], 0x2000
	v_lshl_add_u64 v[12:13], v[12:13], 0, s[10:11]
	v_rcp_f32_e32 v21, v19
	s_nop 0
	v_mul_f32_e32 v20, 1.0, v21
	v_mov_b32_e32 v19, v20
	v_mul_f32_e32 v20, 0x3f1b4598, v19
	v_cndmask_b32_e64 v19, v19, v20, s[6:7]
	v_cvt_pk_f16_f32 v15, v15, v19
	global_store_dwordx2 v[16:17], v[14:15], off offset:96
	s_cbranch_scc0 .LBB0_761
	s_add_i32 s16, s16, s17
	s_add_i32 s18, s18, s19
	s_cmpk_gt_i32 s16, 0x207f
	s_cbranch_scc0 .LBB0_715

; __device__ __forceinline__ void phase_pool(const Params& p, int l, float* smem) {
;     ...
;     f16x8 xf[2];
;     {
;       f16x8 s0 = *(const f16x8*)(base + (size_t)t * PJ), s1 = *(const f16x8*)(base + (size_t)t * PJ + 8);
;       const float inv = 1.0f / (float)(hi - lo + 1);
; #pragma unroll
;       for (int e = 0; e < 8; ++e) {
;         xf[0][e] = (f16)(acc[e] * inv - (float)s0[e]);
;         xf[1][e] = (f16)(acc[8 + e] * inv - (float)s1[e]);
;       }
;     }
;     const f16* wb = pwt + (size_t)g * 4096;
; #pragma unroll
;     for (int nb = 0; nb < 4; ++nb) {
;       const f16* wp = wb + (size_t)(nb * 16 + lq) * 64 + gq * 16;
;       f16x8 w0 = *(const f16x8*)wp, w1 = *(const f16x8*)(wp + 8);
;       f32x4 a = f32x4{0.f, 0.f, 0.f, 0.f};
;       a = __builtin_amdgcn_mfma_f32_16x16x32_f16(w0, xf[0], a, 0, 0, 0);
;       a = __builtin_amdgcn_mfma_f32_16x16x32_f16(w1, xf[1], a, 0, 0, 0);
;       const int d = g * 64 + nb * 16 + 4 * gq;
;       float4 sc = *(const float4*)(p.in[I_POOLS] + (size_t)l * 256 + d);
;       f16x4 o4;
;       o4[0] = (f16)(a[0] * sc.x); o4[1] = (f16)(a[1] * sc.y); o4[2] = (f16)(a[2] * sc.z); o4[3] = (f16)(a[3] * sc.w);
;       *(f16x4*)(br + (size_t)row * DM + RD + d) = o4;
;     }
.LBB0_765:
	v_mul_i32_i24_e32 v44, 0xa20, v23
	v_ashrrev_i32_e32 v45, 31, v44
	v_lshl_add_u64 v[40:41], v[44:45], 1, v[40:41]
	global_load_dwordx4 v[44:47], v[40:41], off
	global_load_dwordx4 v[48:51], v[40:41], off offset:16
	v_add_u32_e32 v29, s10, v23
	v_max_i32_e32 v27, 0, v27
	v_min_i32_e32 v25, v29, v25
	v_sub_u32_e32 v23, v25, v27
	v_cvt_f32_i32_e32 v23, v23
	v_lshlrev_b64 v[30:31], 11, v[30:31]
	v_lshl_add_u64 v[30:31], v[8:9], 0, v[30:31]
	s_add_i32 s8, s8, s28
	s_mov_b64 s[6:7], 0x2298300
	v_lshl_add_u64 v[30:31], v[30:31], 0, s[6:7]
	s_cmpk_gt_i32 s8, 0x207f
	v_rcp_f32_e32 v27, v23
	s_nop 0
	v_mul_f32_e32 v25, 1.0, v27
	v_mov_b32_e32 v40, v25
	v_mov_b32_e32 v23, v165
	v_mov_b32_e32 v25, v165
	v_mov_b32_e32 v27, v165
	v_mov_b32_e32 v29, v165
	s_waitcnt vmcnt(1)
	v_cvt_f32_f16_e32 v52, v44
	v_cvt_f32_f16_sdwa v53, v44 dst_sel:DWORD dst_unused:UNUSED_PAD src0_sel:WORD_1
	v_cvt_f32_f16_e32 v44, v45
	v_cvt_f32_f16_sdwa v45, v45 dst_sel:DWORD dst_unused:UNUSED_PAD src0_sel:WORD_1
	v_pk_fma_f32 v[0:1], v[40:41], v[0:1], v[52:53] op_sel_hi:[0,1,1] neg_lo:[0,0,1] neg_hi:[0,0,1]
	v_cvt_pk_f16_f32 v0, v0, v1
	v_pk_fma_f32 v[36:37], v[40:41], v[36:37], v[44:45] op_sel_hi:[0,1,1] neg_lo:[0,0,1] neg_hi:[0,0,1]
	s_waitcnt vmcnt(0)
	v_cvt_f32_f16_e32 v52, v48
	v_cvt_f32_f16_sdwa v53, v48 dst_sel:DWORD dst_unused:UNUSED_PAD src0_sel:WORD_1
	v_cvt_pk_f16_f32 v1, v36, v37
	v_cvt_f32_f16_e32 v36, v49
	v_cvt_f32_f16_sdwa v37, v49 dst_sel:DWORD dst_unused:UNUSED_PAD src0_sel:WORD_1
	v_pk_fma_f32 v[4:5], v[40:41], v[4:5], v[52:53] op_sel_hi:[0,1,1] neg_lo:[0,0,1] neg_hi:[0,0,1]
	v_cvt_pk_f16_f32 v4, v4, v5
	v_pk_fma_f32 v[36:37], v[40:41], v[38:39], v[36:37] op_sel_hi:[0,1,1] neg_lo:[0,0,1] neg_hi:[0,0,1]
	v_cvt_pk_f16_f32 v5, v36, v37
	v_cvt_f32_f16_e32 v36, v46
	v_cvt_f32_f16_sdwa v37, v46 dst_sel:DWORD dst_unused:UNUSED_PAD src0_sel:WORD_1
	v_pk_fma_f32 v[2:3], v[40:41], v[2:3], v[36:37] op_sel_hi:[0,1,1] neg_lo:[0,0,1] neg_hi:[0,0,1]
	v_cvt_f32_f16_e32 v36, v50
	v_cvt_f32_f16_sdwa v37, v50 dst_sel:DWORD dst_unused:UNUSED_PAD src0_sel:WORD_1
	v_cvt_pk_f16_f32 v2, v2, v3
	v_pk_fma_f32 v[6:7], v[40:41], v[6:7], v[36:37] op_sel_hi:[0,1,1] neg_lo:[0,0,1] neg_hi:[0,0,1]
	v_cvt_f32_f16_e32 v36, v47
	v_cvt_f32_f16_sdwa v37, v47 dst_sel:DWORD dst_unused:UNUSED_PAD src0_sel:WORD_1
	v_cvt_pk_f16_f32 v6, v6, v7
	v_pk_fma_f32 v[32:33], v[40:41], v[32:33], v[36:37] op_sel_hi:[0,1,1] neg_lo:[0,0,1] neg_hi:[0,0,1]
	v_cvt_pk_f16_f32 v3, v32, v33
	v_cvt_f32_f16_e32 v32, v51
	v_cvt_f32_f16_sdwa v33, v51 dst_sel:DWORD dst_unused:UNUSED_PAD src0_sel:WORD_1
	v_pk_fma_f32 v[32:33], v[40:41], v[34:35], v[32:33] op_sel_hi:[0,1,1] neg_lo:[0,0,1] neg_hi:[0,0,1]
	v_cvt_pk_f16_f32 v7, v32, v33
	global_load_dwordx4 v[32:35], v[10:11], off
	global_load_dwordx4 v[36:39], v[10:11], off offset:16
	s_waitcnt vmcnt(1)
	v_mfma_f32_16x16x32_f16 v[32:35], v[32:35], v[0:3], 0
	s_waitcnt vmcnt(0)
	v_mfma_f32_16x16x32_f16 v[32:35], v[36:39], v[4:7], v[32:35]
	global_load_dwordx4 v[36:39], v[20:21], off
	s_waitcnt vmcnt(0)
	s_nop 5
	v_pk_mul_f32 v[32:33], v[32:33], v[36:37]
	v_pk_mul_f32 v[34:35], v[34:35], v[38:39]
	v_cvt_pk_f16_f32 v32, v32, v33
	v_cvt_pk_f16_f32 v33, v34, v35
	v_lshl_add_u64 v[34:35], v[30:31], 0, v[22:23]
	global_store_dwordx2 v[34:35], v[32:33], off
	global_load_dwordx4 v[32:35], v[10:11], off offset:2048
	s_nop 0
	global_load_dwordx4 v[36:39], v[10:11], off offset:2064
	s_waitcnt vmcnt(1)
	v_mfma_f32_16x16x32_f16 v[32:35], v[32:35], v[0:3], 0
	s_waitcnt vmcnt(0)
	v_mfma_f32_16x16x32_f16 v[32:35], v[36:39], v[4:7], v[32:35]
	global_load_dwordx4 v[36:39], v[20:21], off offset:64
	s_waitcnt vmcnt(0)
	s_nop 5
	v_pk_mul_f32 v[32:33], v[32:33], v[36:37]
	v_pk_mul_f32 v[34:35], v[34:35], v[38:39]
	v_cvt_pk_f16_f32 v32, v32, v33
	v_cvt_pk_f16_f32 v33, v34, v35
	v_lshl_add_u64 v[34:35], v[30:31], 0, v[24:25]
	global_store_dwordx2 v[34:35], v[32:33], off
	global_load_dwordx4 v[32:35], v[12:13], off
	s_nop 0
	global_load_dwordx4 v[36:39], v[14:15], off
	s_waitcnt vmcnt(1)
	v_mfma_f32_16x16x32_f16 v[32:35], v[32:35], v[0:3], 0
	s_waitcnt vmcnt(0)
	v_mfma_f32_16x16x32_f16 v[32:35], v[36:39], v[4:7], v[32:35]
	global_load_dwordx4 v[36:39], v[20:21], off offset:128
	s_waitcnt vmcnt(0)
	s_nop 5
	v_pk_mul_f32 v[32:33], v[32:33], v[36:37]
	v_pk_mul_f32 v[34:35], v[34:35], v[38:39]
	v_cvt_pk_f16_f32 v32, v32, v33
	v_cvt_pk_f16_f32 v33, v34, v35
	v_lshl_add_u64 v[34:35], v[30:31], 0, v[26:27]
	global_store_dwordx2 v[34:35], v[32:33], off
	global_load_dwordx4 v[32:35], v[16:17], off
	s_nop 0
	global_load_dwordx4 v[36:39], v[18:19], off
	s_waitcnt vmcnt(1)
	v_mfma_f32_16x16x32_f16 v[0:3], v[32:35], v[0:3], 0
	s_waitcnt vmcnt(0)
	v_mfma_f32_16x16x32_f16 v[0:3], v[36:39], v[4:7], v[0:3]
	global_load_dwordx4 v[4:7], v[20:21], off offset:192
	s_waitcnt vmcnt(0)
	s_nop 5
	v_pk_mul_f32 v[0:1], v[0:1], v[4:5]
	v_pk_mul_f32 v[2:3], v[2:3], v[6:7]
	v_cvt_pk_f16_f32 v0, v0, v1
	v_cvt_pk_f16_f32 v1, v2, v3
	v_lshl_add_u64 v[2:3], v[30:31], 0, v[28:29]
	global_store_dwordx2 v[2:3], v[0:1], off
	s_cbranch_scc1 .LBB0_774

; __device__ __forceinline__ float sigmoidf_(float x) { return 1.0f / (1.0f + __expf(-x)); }
; __device__ __forceinline__ void phase_readout(const Params& p, int l, float* smem) {
;     ...
;   for (int it = gw; it < (NTOK / 16) * NH; it += nw) {
;     const int hh = it % NH, row = (it / NH) * 16 + lq;
;     f32x4 ga[4];
; #pragma unroll
;     for (int nb = 0; nb < 4; ++nb) ga[nb] = f32x4{0.f, 0.f, 0.f, 0.f};
; #pragma unroll
;     for (int ks = 0; ks < 5; ++ks) {
;       f16x8 xf = *(const f16x8*)(dGD + (size_t)row * 160 + ks * 32 + g * 8);
; #pragma unroll
;       for (int e = 0; e < 8; ++e) xf[e] = (f16)sigmoidf_((float)xf[e]);
; #pragma unroll
;       for (int nb = 0; nb < 4; ++nb) {
;         f16x8 wf = *(const f16x8*)(gwt + (size_t)(hh * HD + nb * 16 + lq) * 160 + ks * 32 + g * 8);
;         ga[nb] = __builtin_amdgcn_mfma_f32_16x16x32_f16(wf, xf, ga[nb], 0, 0, 0);
;       }
;     }
.LBB0_1056:
	s_mul_hi_i32 s8, s5, 0x2aaaaaab
	s_lshr_b32 s9, s8, 31
	s_add_i32 s10, s8, s9
	v_lshl_or_b32 v16, s10, 4, v45
	v_mad_i64_i32 v[18:19], s[8:9], v16, s49, v[40:41]
	global_load_dwordx4 v[0:3], v[18:19], off
	s_mul_i32 s8, s10, 0xfffffe80
	s_mul_i32 s10, s10, 0xffff1000
	v_add_u32_e32 v4, s10, v107
	v_ashrrev_i32_e32 v5, 31, v4
	v_lshl_add_u64 v[20:21], v[4:5], 1, v[42:43]
	s_movk_i32 s9, 0x1000
	s_add_i32 s8, s6, s8
	v_add_u32_e32 v100, s8, v44
	v_ashrrev_i32_e32 v101, 31, v100
	v_ashrrev_i32_e32 v17, 31, v16
	s_add_i32 s5, s5, s28
	s_add_i32 s6, s6, s7
	s_waitcnt vmcnt(0)
	v_cvt_f32_f16_e32 v6, v0
	v_cvt_f32_f16_sdwa v0, v0 dst_sel:DWORD dst_unused:UNUSED_PAD src0_sel:WORD_1
	v_mul_f32_e32 v6, 0xbfb8aa3b, v6
	v_exp_f32_e32 v6, v6
	v_mul_f32_e32 v0, 0xbfb8aa3b, v0
	v_add_f32_e32 v6, 1.0, v6
	s_nop 0
	v_rcp_f32_e32 v8, v6
	s_nop 0
	v_mul_f32_e32 v7, 1.0, v8
	v_mov_b32_e32 v6, v7
	v_cvt_f16_f32_e32 v8, v6
	v_exp_f32_e32 v6, v0
	v_cvt_f32_f16_e32 v0, v1
	v_mul_f32_e32 v0, 0xbfb8aa3b, v0
	v_exp_f32_e32 v7, v0
	s_nop 0
	v_pk_add_f32 v[6:7], v[6:7], 1.0 op_sel_hi:[1,0]
	s_nop 0
	s_nop 0
	v_rcp_f32_e32 v9, v7
	s_nop 0
	v_mul_f32_e32 v0, 1.0, v9
	s_nop 0
	v_rcp_f32_e32 v9, v6
	s_nop 0
	v_mul_f32_e32 v7, 1.0, v9
	v_mov_b32_e32 v6, v7
	v_cvt_pk_f16_f32 v6, v6, v0
	v_cvt_f32_f16_sdwa v0, v1 dst_sel:DWORD dst_unused:UNUSED_PAD src0_sel:WORD_1
	v_cvt_f32_f16_e32 v1, v2
	v_pack_b32_f16 v12, v8, v6
	v_mul_f32_e32 v0, 0xbfb8aa3b, v0
	v_mul_f32_e32 v1, 0xbfb8aa3b, v1
	v_exp_f32_e32 v0, v0
	v_exp_f32_e32 v1, v1
	s_nop 0
	v_pk_add_f32 v[0:1], v[0:1], 1.0 op_sel_hi:[1,0]
	s_nop 0
	s_nop 0
	v_rcp_f32_e32 v8, v1
	s_nop 0
	v_mul_f32_e32 v7, 1.0, v8
	v_mov_b32_e32 v1, v7
	s_nop 0
	v_rcp_f32_e32 v8, v0
	s_nop 0
	v_mul_f32_e32 v7, 1.0, v8
	v_mov_b32_e32 v0, v7
	v_cvt_pk_f16_f32 v7, v0, v1
	v_cvt_f32_f16_sdwa v0, v2 dst_sel:DWORD dst_unused:UNUSED_PAD src0_sel:WORD_1
	v_cvt_f32_f16_e32 v1, v3
	v_alignbit_b32 v13, v7, v6, 16
	v_mul_f32_e32 v0, 0xbfb8aa3b, v0
	v_mul_f32_e32 v1, 0xbfb8aa3b, v1
	v_exp_f32_e32 v0, v0
	v_exp_f32_e32 v1, v1
	s_nop 0
	v_pk_add_f32 v[0:1], v[0:1], 1.0 op_sel_hi:[1,0]
	s_nop 0
	s_nop 0
	v_rcp_f32_e32 v6, v1
	s_nop 0
	v_mul_f32_e32 v2, 1.0, v6
	v_mov_b32_e32 v1, v2
	s_nop 0
	v_rcp_f32_e32 v6, v0
	s_nop 0
	v_mul_f32_e32 v2, 1.0, v6
	v_mov_b32_e32 v0, v2
	v_cvt_pk_f16_f32 v0, v0, v1
	v_cvt_f32_f16_sdwa v1, v3 dst_sel:DWORD dst_unused:UNUSED_PAD src0_sel:WORD_1
	v_alignbit_b32 v14, v0, v7, 16
	v_mul_f32_e32 v1, 0xbfb8aa3b, v1
	v_exp_f32_e32 v1, v1
	s_nop 0
	v_add_f32_e32 v1, 1.0, v1
	s_nop 0
	v_rcp_f32_e32 v3, v1
	s_nop 0
	v_mul_f32_e32 v2, 1.0, v3
	v_add_co_u32_e32 v22, vcc, s9, v20
	v_mov_b32_e32 v1, v2
	s_nop 0
	v_addc_co_u32_e32 v23, vcc, 0, v21, vcc
	s_movk_i32 s9, 0x2000
	v_cvt_f16_f32_e32 v1, v1
	v_add_co_u32_e32 v54, vcc, s9, v20
	s_movk_i32 s9, 0x3000
	s_nop 0
	v_addc_co_u32_e32 v55, vcc, 0, v21, vcc
	v_add_co_u32_e32 v56, vcc, s9, v20
	v_alignbit_b32 v15, v1, v0, 16
	s_nop 0
	v_addc_co_u32_e32 v57, vcc, 0, v21, vcc
	global_load_dwordx4 v[0:3], v[20:21], off
	global_load_dwordx4 v[4:7], v[22:23], off offset:1024
	global_load_dwordx4 v[8:11], v[54:55], off offset:2048
	global_load_dwordx4 v[58:61], v[56:57], off offset:3072
	s_ashr_i32 s9, s8, 31
	s_cmpk_lt_i32 s5, 0x30c0
	s_waitcnt vmcnt(2)
	v_mfma_f32_16x16x32_f16 v[4:7], v[4:7], v[12:15], 0
	v_mfma_f32_16x16x32_f16 v[0:3], v[0:3], v[12:15], 0
	s_waitcnt vmcnt(1)
	v_mfma_f32_16x16x32_f16 v[8:11], v[8:11], v[12:15], 0
	s_waitcnt vmcnt(0)
	v_mfma_f32_16x16x32_f16 v[12:15], v[58:61], v[12:15], 0
	global_load_dwordx4 v[58:61], v[18:19], off offset:64
	s_waitcnt vmcnt(0)
	v_cvt_f32_f16_e32 v62, v58
	v_cvt_f32_f16_sdwa v58, v58 dst_sel:DWORD dst_unused:UNUSED_PAD src0_sel:WORD_1
	v_mul_f32_e32 v62, 0xbfb8aa3b, v62
	v_exp_f32_e32 v62, v62
	v_mul_f32_e32 v58, 0xbfb8aa3b, v58
	v_add_f32_e32 v62, 1.0, v62
	s_nop 0
	v_rcp_f32_e32 v64, v62
	s_nop 0
	v_mul_f32_e32 v63, 1.0, v64
	v_mov_b32_e32 v62, v63
	v_cvt_f16_f32_e32 v64, v62
	v_exp_f32_e32 v62, v58
	v_cvt_f32_f16_e32 v58, v59
	v_cvt_f32_f16_sdwa v59, v59 dst_sel:DWORD dst_unused:UNUSED_PAD src0_sel:WORD_1
	v_mul_f32_e32 v58, 0xbfb8aa3b, v58
	v_exp_f32_e32 v63, v58
	v_mul_f32_e32 v59, 0xbfb8aa3b, v59
	v_pk_add_f32 v[62:63], v[62:63], 1.0 op_sel_hi:[1,0]
	s_nop 0
	s_nop 0
	v_rcp_f32_e32 v65, v63
	s_nop 0
	v_mul_f32_e32 v58, 1.0, v65
	s_nop 0
	v_rcp_f32_e32 v65, v62
	s_nop 0
	v_mul_f32_e32 v63, 1.0, v65
	v_mov_b32_e32 v62, v63
	v_cvt_pk_f16_f32 v65, v62, v58
	v_exp_f32_e32 v62, v59
	v_cvt_f32_f16_e32 v59, v60
	v_pack_b32_f16 v58, v64, v65
	v_cvt_f32_f16_sdwa v60, v60 dst_sel:DWORD dst_unused:UNUSED_PAD src0_sel:WORD_1
	v_mul_f32_e32 v59, 0xbfb8aa3b, v59
	v_exp_f32_e32 v63, v59
	v_mul_f32_e32 v60, 0xbfb8aa3b, v60
	v_pk_add_f32 v[62:63], v[62:63], 1.0 op_sel_hi:[1,0]
	s_nop 0
	s_nop 0
	v_rcp_f32_e32 v64, v63
	s_nop 0
	v_mul_f32_e32 v59, 1.0, v64
	s_nop 0
	v_rcp_f32_e32 v64, v62
	s_nop 0
	v_mul_f32_e32 v63, 1.0, v64
	v_mov_b32_e32 v62, v63
	v_cvt_pk_f16_f32 v64, v62, v59
	v_exp_f32_e32 v62, v60
	v_cvt_f32_f16_e32 v60, v61
	v_alignbit_b32 v59, v64, v65, 16
	v_cvt_f32_f16_sdwa v61, v61 dst_sel:DWORD dst_unused:UNUSED_PAD src0_sel:WORD_1
	v_mul_f32_e32 v60, 0xbfb8aa3b, v60
	v_exp_f32_e32 v63, v60
	v_mul_f32_e32 v61, 0xbfb8aa3b, v61
	v_exp_f32_e32 v61, v61
	v_pk_add_f32 v[62:63], v[62:63], 1.0 op_sel_hi:[1,0]
	s_nop 0
	v_add_f32_e32 v61, 1.0, v61
	v_rcp_f32_e32 v65, v63
	s_nop 0
	v_mul_f32_e32 v60, 1.0, v65
	s_nop 0
	v_rcp_f32_e32 v65, v62
	s_nop 0
	v_mul_f32_e32 v63, 1.0, v65
	v_mov_b32_e32 v62, v63
	v_cvt_pk_f16_f32 v62, v62, v60
	v_alignbit_b32 v60, v62, v64, 16
	s_nop 0
	v_rcp_f32_e32 v64, v61
	s_nop 0
	v_mul_f32_e32 v63, 1.0, v64
	v_mov_b32_e32 v61, v63
	v_cvt_f16_f32_e32 v61, v61
	v_alignbit_b32 v61, v61, v62, 16
	global_load_dwordx4 v[62:65], v[20:21], off offset:64
	s_waitcnt vmcnt(0)
; __device__ __forceinline__ float sigmoidf_(float x) { return 1.0f / (1.0f + __expf(-x)); }
; __device__ __forceinline__ void phase_readout(const Params& p, int l, float* smem) {
;     ...
;     for (int ks = 0; ks < 5; ++ks) {
;       f16x8 xf = *(const f16x8*)(dGD + (size_t)row * 160 + ks * 32 + g * 8);
; #pragma unroll
;       for (int e = 0; e < 8; ++e) xf[e] = (f16)sigmoidf_((float)xf[e]);
; #pragma unroll
;       for (int nb = 0; nb < 4; ++nb) {
;         f16x8 wf = *(const f16x8*)(gwt + (size_t)(hh * HD + nb * 16 + lq) * 160 + ks * 32 + g * 8);
;         ga[nb] = __builtin_amdgcn_mfma_f32_16x16x32_f16(wf, xf, ga[nb], 0, 0, 0);
;       }
;     }
	v_mfma_f32_16x16x32_f16 v[0:3], v[62:65], v[58:61], v[0:3]
	global_load_dwordx4 v[62:65], v[22:23], off offset:1088
	s_waitcnt vmcnt(0)
	v_mfma_f32_16x16x32_f16 v[4:7], v[62:65], v[58:61], v[4:7]
	global_load_dwordx4 v[62:65], v[54:55], off offset:2112
	s_waitcnt vmcnt(0)
	v_mfma_f32_16x16x32_f16 v[8:11], v[62:65], v[58:61], v[8:11]
	global_load_dwordx4 v[62:65], v[56:57], off offset:3136
	s_waitcnt vmcnt(0)
	v_mfma_f32_16x16x32_f16 v[12:15], v[62:65], v[58:61], v[12:15]
	global_load_dwordx4 v[58:61], v[18:19], off offset:128
	s_waitcnt vmcnt(0)
	v_cvt_f32_f16_e32 v62, v58
	v_cvt_f32_f16_sdwa v58, v58 dst_sel:DWORD dst_unused:UNUSED_PAD src0_sel:WORD_1
	v_mul_f32_e32 v62, 0xbfb8aa3b, v62
	v_exp_f32_e32 v62, v62
	v_mul_f32_e32 v58, 0xbfb8aa3b, v58
	v_add_f32_e32 v62, 1.0, v62
	s_nop 0
	v_rcp_f32_e32 v64, v62
	s_nop 0
	v_mul_f32_e32 v63, 1.0, v64
	v_mov_b32_e32 v62, v63
	v_cvt_f16_f32_e32 v64, v62
	v_exp_f32_e32 v62, v58
	v_cvt_f32_f16_e32 v58, v59
	v_cvt_f32_f16_sdwa v59, v59 dst_sel:DWORD dst_unused:UNUSED_PAD src0_sel:WORD_1
	v_mul_f32_e32 v58, 0xbfb8aa3b, v58
	v_exp_f32_e32 v63, v58
	v_mul_f32_e32 v59, 0xbfb8aa3b, v59
	v_pk_add_f32 v[62:63], v[62:63], 1.0 op_sel_hi:[1,0]
	s_nop 0
	s_nop 0
	v_rcp_f32_e32 v65, v63
	s_nop 0
	v_mul_f32_e32 v58, 1.0, v65
	s_nop 0
	v_rcp_f32_e32 v65, v62
	s_nop 0
	v_mul_f32_e32 v63, 1.0, v65
	v_mov_b32_e32 v62, v63
	v_cvt_pk_f16_f32 v65, v62, v58
	v_exp_f32_e32 v62, v59
	v_cvt_f32_f16_e32 v59, v60
	v_pack_b32_f16 v58, v64, v65
	v_cvt_f32_f16_sdwa v60, v60 dst_sel:DWORD dst_unused:UNUSED_PAD src0_sel:WORD_1
	v_mul_f32_e32 v59, 0xbfb8aa3b, v59
	v_exp_f32_e32 v63, v59
	v_mul_f32_e32 v60, 0xbfb8aa3b, v60
	v_pk_add_f32 v[62:63], v[62:63], 1.0 op_sel_hi:[1,0]
	s_nop 0
	s_nop 0
	v_rcp_f32_e32 v64, v63
	s_nop 0
	v_mul_f32_e32 v59, 1.0, v64
	s_nop 0
	v_rcp_f32_e32 v64, v62
	s_nop 0
	v_mul_f32_e32 v63, 1.0, v64
	v_mov_b32_e32 v62, v63
	v_cvt_pk_f16_f32 v64, v62, v59
	v_exp_f32_e32 v62, v60
	v_cvt_f32_f16_e32 v60, v61
	v_alignbit_b32 v59, v64, v65, 16
	v_cvt_f32_f16_sdwa v61, v61 dst_sel:DWORD dst_unused:UNUSED_PAD src0_sel:WORD_1
	v_mul_f32_e32 v60, 0xbfb8aa3b, v60
	v_exp_f32_e32 v63, v60
	v_mul_f32_e32 v61, 0xbfb8aa3b, v61
	v_exp_f32_e32 v61, v61
	v_pk_add_f32 v[62:63], v[62:63], 1.0 op_sel_hi:[1,0]
	s_nop 0
	v_add_f32_e32 v61, 1.0, v61
	v_rcp_f32_e32 v65, v63
	s_nop 0
	v_mul_f32_e32 v60, 1.0, v65
	s_nop 0
	v_rcp_f32_e32 v65, v62
	s_nop 0
	v_mul_f32_e32 v63, 1.0, v65
	v_mov_b32_e32 v62, v63
	v_cvt_pk_f16_f32 v62, v62, v60
	v_alignbit_b32 v60, v62, v64, 16
	s_nop 0
	v_rcp_f32_e32 v64, v61
	s_nop 0
	v_mul_f32_e32 v63, 1.0, v64
	v_mov_b32_e32 v61, v63
	v_cvt_f16_f32_e32 v61, v61
	v_alignbit_b32 v61, v61, v62, 16
	global_load_dwordx4 v[62:65], v[20:21], off offset:128
	s_waitcnt vmcnt(0)
	v_mfma_f32_16x16x32_f16 v[0:3], v[62:65], v[58:61], v[0:3]
	global_load_dwordx4 v[62:65], v[22:23], off offset:1152
	s_waitcnt vmcnt(0)
	v_mfma_f32_16x16x32_f16 v[4:7], v[62:65], v[58:61], v[4:7]
	global_load_dwordx4 v[62:65], v[54:55], off offset:2176
	s_waitcnt vmcnt(0)
	v_mfma_f32_16x16x32_f16 v[8:11], v[62:65], v[58:61], v[8:11]
	global_load_dwordx4 v[62:65], v[56:57], off offset:3200
	s_waitcnt vmcnt(0)
	v_mfma_f32_16x16x32_f16 v[12:15], v[62:65], v[58:61], v[12:15]
	global_load_dwordx4 v[58:61], v[18:19], off offset:192
	s_waitcnt vmcnt(0)
	v_cvt_f32_f16_e32 v62, v58
	v_cvt_f32_f16_sdwa v58, v58 dst_sel:DWORD dst_unused:UNUSED_PAD src0_sel:WORD_1
	v_mul_f32_e32 v62, 0xbfb8aa3b, v62
	v_exp_f32_e32 v62, v62
	v_mul_f32_e32 v58, 0xbfb8aa3b, v58
	v_add_f32_e32 v62, 1.0, v62
	s_nop 0
	v_rcp_f32_e32 v64, v62
	s_nop 0
	v_mul_f32_e32 v63, 1.0, v64
	v_mov_b32_e32 v62, v63
	v_cvt_f16_f32_e32 v64, v62
	v_exp_f32_e32 v62, v58
	v_cvt_f32_f16_e32 v58, v59
	v_cvt_f32_f16_sdwa v59, v59 dst_sel:DWORD dst_unused:UNUSED_PAD src0_sel:WORD_1
	v_mul_f32_e32 v58, 0xbfb8aa3b, v58
	v_exp_f32_e32 v63, v58
	v_mul_f32_e32 v59, 0xbfb8aa3b, v59
	v_pk_add_f32 v[62:63], v[62:63], 1.0 op_sel_hi:[1,0]
	s_nop 0
	s_nop 0
	v_rcp_f32_e32 v65, v63
	s_nop 0
	v_mul_f32_e32 v58, 1.0, v65
	s_nop 0
	v_rcp_f32_e32 v65, v62
	s_nop 0
	v_mul_f32_e32 v63, 1.0, v65
	v_mov_b32_e32 v62, v63
	v_cvt_pk_f16_f32 v65, v62, v58
	v_exp_f32_e32 v62, v59
	v_cvt_f32_f16_e32 v59, v60
	v_pack_b32_f16 v58, v64, v65
	v_cvt_f32_f16_sdwa v60, v60 dst_sel:DWORD dst_unused:UNUSED_PAD src0_sel:WORD_1
	v_mul_f32_e32 v59, 0xbfb8aa3b, v59
	v_exp_f32_e32 v63, v59
	v_mul_f32_e32 v60, 0xbfb8aa3b, v60
	v_pk_add_f32 v[62:63], v[62:63], 1.0 op_sel_hi:[1,0]
	s_nop 0
	s_nop 0
	v_rcp_f32_e32 v64, v63
	s_nop 0
	v_mul_f32_e32 v59, 1.0, v64
	s_nop 0
	v_rcp_f32_e32 v64, v62
	s_nop 0
	v_mul_f32_e32 v63, 1.0, v64
	v_mov_b32_e32 v62, v63
	v_cvt_pk_f16_f32 v64, v62, v59
	v_exp_f32_e32 v62, v60
	v_cvt_f32_f16_e32 v60, v61
	v_alignbit_b32 v59, v64, v65, 16
	v_cvt_f32_f16_sdwa v61, v61 dst_sel:DWORD dst_unused:UNUSED_PAD src0_sel:WORD_1
	v_mul_f32_e32 v60, 0xbfb8aa3b, v60
	v_exp_f32_e32 v63, v60
	v_mul_f32_e32 v61, 0xbfb8aa3b, v61
	v_exp_f32_e32 v61, v61
	v_pk_add_f32 v[62:63], v[62:63], 1.0 op_sel_hi:[1,0]
	s_nop 0
	v_add_f32_e32 v61, 1.0, v61
	v_rcp_f32_e32 v65, v63
	s_nop 0
	v_mul_f32_e32 v60, 1.0, v65
	s_nop 0
	v_rcp_f32_e32 v65, v62
	s_nop 0
	v_mul_f32_e32 v63, 1.0, v65
	v_mov_b32_e32 v62, v63
	v_cvt_pk_f16_f32 v62, v62, v60
	v_alignbit_b32 v60, v62, v64, 16
	s_nop 0
	v_rcp_f32_e32 v64, v61
	s_nop 0
	v_mul_f32_e32 v63, 1.0, v64
	v_mov_b32_e32 v61, v63
	v_cvt_f16_f32_e32 v61, v61
	v_alignbit_b32 v61, v61, v62, 16
	global_load_dwordx4 v[62:65], v[20:21], off offset:192
	s_waitcnt vmcnt(0)
	v_mfma_f32_16x16x32_f16 v[0:3], v[62:65], v[58:61], v[0:3]
	global_load_dwordx4 v[62:65], v[22:23], off offset:1216
	s_waitcnt vmcnt(0)
; __device__ __forceinline__ float sigmoidf_(float x) { return 1.0f / (1.0f + __expf(-x)); }
; __device__ __forceinline__ void phase_readout(const Params& p, int l, float* smem) {
;     ...
;     for (int ks = 0; ks < 5; ++ks) {
;       f16x8 xf = *(const f16x8*)(dGD + (size_t)row * 160 + ks * 32 + g * 8);
; #pragma unroll
;       for (int e = 0; e < 8; ++e) xf[e] = (f16)sigmoidf_((float)xf[e]);
; #pragma unroll
;       for (int nb = 0; nb < 4; ++nb) {
;         f16x8 wf = *(const f16x8*)(gwt + (size_t)(hh * HD + nb * 16 + lq) * 160 + ks * 32 + g * 8);
;         ga[nb] = __builtin_amdgcn_mfma_f32_16x16x32_f16(wf, xf, ga[nb], 0, 0, 0);
;       }
;     }
;     float y[4][4];
;     float sum = 0.f;
; #pragma unroll
;     for (int nb = 0; nb < 4; ++nb) {
;       size_t o = (size_t)row * RD + hh * HD + nb * 16 + 4 * g;
;       uint2 ya = *(const uint2*)(Y0 + o), yb = *(const uint2*)(Y1 + o);
;       y[nb][0] = bf2f((unsigned short)(ya.x & 0xFFFFu)) + bf2f((unsigned short)(yb.x & 0xFFFFu));
;       y[nb][1] = bf2f((unsigned short)(ya.x >> 16)) + bf2f((unsigned short)(yb.x >> 16));
;       y[nb][2] = bf2f((unsigned short)(ya.y & 0xFFFFu)) + bf2f((unsigned short)(yb.y & 0xFFFFu));
;       y[nb][3] = bf2f((unsigned short)(ya.y >> 16)) + bf2f((unsigned short)(yb.y >> 16));
;       sum += (y[nb][0] + y[nb][1]) + (y[nb][2] + y[nb][3]);
;     }
	v_mfma_f32_16x16x32_f16 v[4:7], v[62:65], v[58:61], v[4:7]
	global_load_dwordx4 v[62:65], v[54:55], off offset:2240
	s_waitcnt vmcnt(0)
	v_mfma_f32_16x16x32_f16 v[62:65], v[62:65], v[58:61], v[8:11]
	s_nop 2
	global_load_dwordx4 v[8:11], v[56:57], off offset:3264
	s_waitcnt vmcnt(0)
	v_mfma_f32_16x16x32_f16 v[58:61], v[8:11], v[58:61], v[12:15]
	global_load_dwordx4 v[8:11], v[18:19], off offset:256
	s_waitcnt vmcnt(0)
	s_nop 0
	v_cvt_f32_f16_e32 v12, v8
	v_cvt_f32_f16_sdwa v8, v8 dst_sel:DWORD dst_unused:UNUSED_PAD src0_sel:WORD_1
	v_mul_f32_e32 v12, 0xbfb8aa3b, v12
	v_exp_f32_e32 v12, v12
	v_mul_f32_e32 v8, 0xbfb8aa3b, v8
	v_add_f32_e32 v12, 1.0, v12
	s_nop 0
	v_rcp_f32_e32 v14, v12
	s_nop 0
	v_mul_f32_e32 v13, 1.0, v14
	v_mov_b32_e32 v12, v13
	v_cvt_f16_f32_e32 v14, v12
	v_exp_f32_e32 v12, v8
	v_cvt_f32_f16_e32 v8, v9
	v_mul_f32_e32 v8, 0xbfb8aa3b, v8
	v_exp_f32_e32 v13, v8
	s_nop 0
	v_pk_add_f32 v[12:13], v[12:13], 1.0 op_sel_hi:[1,0]
	s_nop 0
	s_nop 0
	v_rcp_f32_e32 v15, v13
	s_nop 0
	v_mul_f32_e32 v8, 1.0, v15
	s_nop 0
	v_rcp_f32_e32 v15, v12
	s_nop 0
	v_mul_f32_e32 v13, 1.0, v15
	v_mov_b32_e32 v12, v13
	v_cvt_pk_f16_f32 v12, v12, v8
	v_cvt_f32_f16_sdwa v8, v9 dst_sel:DWORD dst_unused:UNUSED_PAD src0_sel:WORD_1
	v_cvt_f32_f16_e32 v9, v10
	v_pack_b32_f16 v66, v14, v12
	v_mul_f32_e32 v8, 0xbfb8aa3b, v8
	v_mul_f32_e32 v9, 0xbfb8aa3b, v9
	v_exp_f32_e32 v8, v8
	v_exp_f32_e32 v9, v9
	s_nop 0
	v_pk_add_f32 v[8:9], v[8:9], 1.0 op_sel_hi:[1,0]
	s_nop 0
	s_nop 0
	v_rcp_f32_e32 v14, v9
	s_nop 0
	v_mul_f32_e32 v13, 1.0, v14
	v_mov_b32_e32 v9, v13
	s_nop 0
	v_rcp_f32_e32 v14, v8
	s_nop 0
	v_mul_f32_e32 v13, 1.0, v14
	v_mov_b32_e32 v8, v13
	v_cvt_pk_f16_f32 v13, v8, v9
	v_cvt_f32_f16_sdwa v8, v10 dst_sel:DWORD dst_unused:UNUSED_PAD src0_sel:WORD_1
	v_cvt_f32_f16_e32 v9, v11
	v_alignbit_b32 v67, v13, v12, 16
	v_mov_b32_e32 v19, s9
	v_mul_f32_e32 v8, 0xbfb8aa3b, v8
	v_mul_f32_e32 v9, 0xbfb8aa3b, v9
	v_exp_f32_e32 v8, v8
	v_exp_f32_e32 v9, v9
	s_nop 0
	v_pk_add_f32 v[8:9], v[8:9], 1.0 op_sel_hi:[1,0]
	s_nop 0
	s_nop 0
	v_rcp_f32_e32 v12, v9
	s_nop 0
	v_mul_f32_e32 v10, 1.0, v12
	v_mov_b32_e32 v9, v10
	s_nop 0
	v_rcp_f32_e32 v12, v8
	s_nop 0
	v_mul_f32_e32 v10, 1.0, v12
	v_mov_b32_e32 v8, v10
	v_cvt_pk_f16_f32 v8, v8, v9
	v_cvt_f32_f16_sdwa v9, v11 dst_sel:DWORD dst_unused:UNUSED_PAD src0_sel:WORD_1
	v_alignbit_b32 v68, v8, v13, 16
	v_mov_b32_e32 v18, s8
	v_mad_i64_i32 v[18:19], s[10:11], v16, s60, v[18:19]
	v_mul_f32_e32 v9, 0xbfb8aa3b, v9
	v_exp_f32_e32 v9, v9
	v_or_b32_e32 v18, v18, v44
	v_add_f32_e32 v9, 1.0, v9
	s_nop 0
	v_rcp_f32_e32 v11, v9
	s_nop 0
	v_mul_f32_e32 v10, 1.0, v11
	v_mov_b32_e32 v9, v10
	v_cvt_f16_f32_e32 v9, v9
	v_alignbit_b32 v69, v9, v8, 16
	global_load_dwordx4 v[8:11], v[20:21], off offset:256
	s_waitcnt vmcnt(0)
	v_mfma_f32_16x16x32_f16 v[12:15], v[8:11], v[66:69], v[0:3]
	s_nop 2
	global_load_dwordx4 v[0:3], v[22:23], off offset:1280
	v_lshlrev_b64 v[22:23], 1, v[18:19]
	v_lshl_add_u64 v[18:19], v[34:35], 0, v[22:23]
	s_waitcnt vmcnt(0)
	v_mfma_f32_16x16x32_f16 v[8:11], v[0:3], v[66:69], v[4:7]
	global_load_dwordx4 v[0:3], v[54:55], off offset:2304
	s_nop 0
	global_load_dwordx2 v[54:55], v[18:19], off
	v_lshl_add_u64 v[18:19], v[36:37], 0, v[22:23]
	s_waitcnt vmcnt(1)
	v_mfma_f32_16x16x32_f16 v[4:7], v[0:3], v[66:69], v[62:65]
	global_load_dwordx4 v[0:3], v[56:57], off offset:3328
	s_waitcnt vmcnt(1)
	v_lshlrev_b32_e32 v70, 16, v55
	global_load_dwordx2 v[56:57], v[18:19], off
	v_lshlrev_b32_e32 v18, 16, v54
	v_and_b32_e32 v19, 0xffff0000, v54
	v_and_b32_e32 v71, 0xffff0000, v55
	v_or_b32_e32 v54, 32, v22
	v_mov_b32_e32 v55, v23
	s_waitcnt vmcnt(1)
	v_mfma_f32_16x16x32_f16 v[0:3], v[0:3], v[66:69], v[58:61]
	s_waitcnt vmcnt(0)
	v_lshlrev_b32_e32 v20, 16, v56
	v_and_b32_e32 v21, 0xffff0000, v56
	v_lshlrev_b32_e32 v72, 16, v57
	v_and_b32_e32 v73, 0xffff0000, v57
	v_lshl_add_u64 v[56:57], v[34:35], 0, v[54:55]
	v_lshl_add_u64 v[54:55], v[36:37], 0, v[54:55]
	global_load_dwordx2 v[56:57], v[56:57], off
	s_nop 0
	global_load_dwordx2 v[54:55], v[54:55], off
	v_pk_add_f32 v[70:71], v[70:71], v[72:73]
	s_waitcnt vmcnt(1)
	v_lshlrev_b32_e32 v59, 16, v57
	v_lshlrev_b32_e32 v58, 16, v56
	s_waitcnt vmcnt(0)
	v_lshlrev_b32_e32 v61, 16, v55
	v_lshlrev_b32_e32 v60, 16, v54
	v_and_b32_e32 v57, 0xffff0000, v57
	v_and_b32_e32 v56, 0xffff0000, v56
	v_and_b32_e32 v55, 0xffff0000, v55
	v_and_b32_e32 v54, 0xffff0000, v54
	v_pk_add_f32 v[96:97], v[58:59], v[60:61]
	v_pk_add_f32 v[62:63], v[56:57], v[54:55]
	v_mov_b32_e32 v73, v70
	v_pk_add_f32 v[54:55], v[96:97], v[62:63]
	s_nop 0
	v_pk_add_f32 v[78:79], v[54:55], v[54:55] op_sel:[0,1] op_sel_hi:[1,0]
	v_or_b32_e32 v54, 64, v22
	v_mov_b32_e32 v55, v23
	v_lshl_add_u64 v[56:57], v[34:35], 0, v[54:55]
	v_lshl_add_u64 v[54:55], v[36:37], 0, v[54:55]
	global_load_dwordx2 v[56:57], v[56:57], off
	v_or_b32_e32 v22, 0x60, v22
	global_load_dwordx2 v[54:55], v[54:55], off
	s_waitcnt vmcnt(1)
	v_lshlrev_b32_e32 v58, 16, v56
	v_and_b32_e32 v59, 0xffff0000, v56
	s_waitcnt vmcnt(0)
	v_lshlrev_b32_e32 v60, 16, v54
	v_and_b32_e32 v61, 0xffff0000, v54
	v_lshlrev_b32_e32 v56, 16, v57
	v_lshlrev_b32_e32 v54, 16, v55
	v_and_b32_e32 v57, 0xffff0000, v57
	v_and_b32_e32 v55, 0xffff0000, v55
	v_pk_add_f32 v[60:61], v[58:59], v[60:61]
	v_pk_add_f32 v[58:59], v[56:57], v[54:55]
	v_lshl_add_u64 v[54:55], v[34:35], 0, v[22:23]
	v_lshl_add_u64 v[22:23], v[36:37], 0, v[22:23]
	global_load_dwordx2 v[22:23], v[22:23], off
	v_pk_add_f32 v[80:81], v[60:61], v[60:61] op_sel:[0,1] op_sel_hi:[1,0]
	global_load_dwordx2 v[54:55], v[54:55], off
	v_pk_add_f32 v[82:83], v[58:59], v[58:59] op_sel:[0,1] op_sel_hi:[1,0]
	s_waitcnt vmcnt(1)
; __device__ __forceinline__ void phase_readout(const Params& p, int l, float* smem) {
;     ...
;     float vv[4][4];
;     float bs = 0.f;
; #pragma unroll
;     for (int nb = 0; nb < 4; ++nb) {
;       const int c = hh * HD + nb * 16 + 4 * g;
;       size_t o = (size_t)row * RD + c;
;       f16x4 r4 = *(const f16x4*)(dR + o), k4 = *(const f16x4*)(dK + o), v4 = *(const f16x4*)(dV + o);
;       f16x4 a04 = *(const f16x4*)(dA0 + o), a14 = *(const f16x4*)(dA1 + o);
;       float4 rk = *(const float4*)(p.in[I_RK] + (size_t)l * RD + c);
;       float4 ka = *(const float4*)(p.in[I_KA] + (size_t)l * RD + c);
;       const float rkv[4] = {rk.x, rk.y, rk.z, rk.w}, kav[4] = {ka.x, ka.y, ka.z, ka.w};
; #pragma unroll
;       for (int i = 0; i < 4; ++i) {
;         float kds = (float)k4[i] * (2.0f + ((float)a04[i] + (float)a14[i] - 2.0f) * kav[i]);
;         bs += (float)r4[i] * rkv[i] * kds;
;         vv[nb][i] = (float)v4[i];
;       }
;     }
	v_lshlrev_b32_e32 v87, 16, v22
	v_and_b32_e32 v86, 0xffff0000, v22
	v_lshlrev_b32_e32 v91, 16, v23
	v_and_b32_e32 v90, 0xffff0000, v23
	v_mad_i64_i32 v[22:23], s[8:9], v16, s60, v[100:101]
	v_lshlrev_b64 v[22:23], 1, v[22:23]
	s_waitcnt vmcnt(0)
	v_lshlrev_b32_e32 v85, 16, v54
	v_and_b32_e32 v84, 0xffff0000, v54
	v_lshlrev_b32_e32 v89, 16, v55
	v_and_b32_e32 v88, 0xffff0000, v55
	v_lshl_add_u64 v[54:55], v[24:25], 0, v[22:23]
	global_load_dwordx2 v[68:69], v[54:55], off
	v_lshl_add_u64 v[54:55], v[26:27], 0, v[22:23]
	global_load_dwordx2 v[76:77], v[54:55], off
	v_lshl_add_u64 v[54:55], v[28:29], 0, v[22:23]
	global_load_dwordx2 v[74:75], v[54:55], off
	v_lshl_add_u64 v[54:55], v[30:31], 0, v[22:23]
	v_lshl_add_u64 v[22:23], v[32:33], 0, v[22:23]
	global_load_dwordx2 v[92:93], v[54:55], off
	global_load_dwordx2 v[98:99], v[22:23], off
	v_lshlrev_b64 v[22:23], 2, v[100:101]
	v_lshl_add_u64 v[104:105], v[48:49], 0, v[22:23]
	global_load_dwordx4 v[64:67], v[104:105], off
	v_lshl_add_u64 v[102:103], v[46:47], 0, v[22:23]
	global_load_dwordx4 v[54:57], v[102:103], off
	v_pk_add_f32 v[84:85], v[84:85], v[86:87]
	s_waitcnt vmcnt(5)
	v_cvt_f32_f16_e32 v79, v76
	s_waitcnt vmcnt(3)
	v_cvt_f32_f16_e32 v81, v92
	s_waitcnt vmcnt(2)
	v_cvt_f32_f16_e32 v83, v98
	v_add_f32_e32 v81, v81, v83
	v_add_f32_e32 v81, -2.0, v81
	s_waitcnt vmcnt(1)
	v_fma_f32 v64, v81, v64, 2.0
	v_mul_f32_e32 v64, v64, v79
	v_cvt_f32_f16_e32 v79, v68
	s_waitcnt vmcnt(0)
	v_mul_f32_e32 v54, v54, v79
	v_fma_f32 v79, v54, v64, 0
	v_cvt_f32_f16_sdwa v54, v76 dst_sel:DWORD dst_unused:UNUSED_PAD src0_sel:WORD_1
	v_cvt_f32_f16_sdwa v64, v92 dst_sel:DWORD dst_unused:UNUSED_PAD src0_sel:WORD_1
	v_cvt_f32_f16_sdwa v76, v98 dst_sel:DWORD dst_unused:UNUSED_PAD src0_sel:WORD_1
	v_add_f32_e32 v64, v64, v76
	v_add_f32_e32 v64, -2.0, v64
	v_fma_f32 v64, v64, v65, 2.0
	v_mul_f32_e32 v54, v64, v54
	v_cvt_f32_f16_sdwa v64, v68 dst_sel:DWORD dst_unused:UNUSED_PAD src0_sel:WORD_1
	v_mul_f32_e32 v55, v55, v64
	v_fmac_f32_e32 v79, v55, v54
	v_cvt_f32_f16_e32 v55, v93
	v_cvt_f32_f16_e32 v64, v99
	v_cvt_f32_f16_e32 v54, v77
	v_add_f32_e32 v55, v55, v64
	v_add_f32_e32 v55, -2.0, v55
	v_fma_f32 v55, v55, v66, 2.0
	v_mul_f32_e32 v54, v55, v54
	v_cvt_f32_f16_e32 v55, v69
	v_mul_f32_e32 v55, v56, v55
	v_fmac_f32_e32 v79, v55, v54
	v_cvt_f32_f16_sdwa v55, v93 dst_sel:DWORD dst_unused:UNUSED_PAD src0_sel:WORD_1
	v_cvt_f32_f16_sdwa v56, v99 dst_sel:DWORD dst_unused:UNUSED_PAD src0_sel:WORD_1
	v_cvt_f32_f16_sdwa v54, v77 dst_sel:DWORD dst_unused:UNUSED_PAD src0_sel:WORD_1
	v_add_f32_e32 v55, v55, v56
	v_add_f32_e32 v55, -2.0, v55
	v_fma_f32 v55, v55, v67, 2.0
	v_mul_f32_e32 v54, v55, v54
	v_cvt_f32_f16_sdwa v55, v69 dst_sel:DWORD dst_unused:UNUSED_PAD src0_sel:WORD_1
	v_mul_f32_e32 v55, v57, v55
	v_fmac_f32_e32 v79, v55, v54
	v_add_u32_e32 v54, 16, v100
	v_ashrrev_i32_e32 v55, 31, v54
	v_mad_i64_i32 v[54:55], s[8:9], v16, s60, v[54:55]
	v_lshlrev_b64 v[54:55], 1, v[54:55]
	v_lshl_add_u64 v[56:57], v[24:25], 0, v[54:55]
	global_load_dwordx2 v[68:69], v[56:57], off
	v_lshl_add_u64 v[56:57], v[26:27], 0, v[54:55]
	global_load_dwordx2 v[76:77], v[56:57], off
	v_lshl_add_u64 v[56:57], v[28:29], 0, v[54:55]
	global_load_dwordx2 v[98:99], v[56:57], off
	v_lshl_add_u64 v[56:57], v[30:31], 0, v[54:55]
	global_load_dwordx2 v[92:93], v[56:57], off
	v_lshl_add_u64 v[54:55], v[32:33], 0, v[54:55]
	global_load_dwordx2 v[108:109], v[54:55], off
	s_nop 0
	global_load_dwordx4 v[54:57], v[102:103], off offset:64
	global_load_dwordx4 v[64:67], v[104:105], off offset:64
	s_waitcnt vmcnt(5)
	v_cvt_f32_f16_e32 v81, v76
	s_waitcnt vmcnt(3)
	v_cvt_f32_f16_e32 v83, v92
	s_waitcnt vmcnt(2)
	v_cvt_f32_f16_e32 v94, v108
	v_add_f32_e32 v83, v83, v94
	v_add_f32_e32 v83, -2.0, v83
	s_waitcnt vmcnt(0)
	v_fma_f32 v64, v83, v64, 2.0
	v_mul_f32_e32 v64, v64, v81
	v_cvt_f32_f16_e32 v81, v68
	v_mul_f32_e32 v54, v54, v81
	v_fmac_f32_e32 v79, v54, v64
	v_cvt_f32_f16_sdwa v54, v76 dst_sel:DWORD dst_unused:UNUSED_PAD src0_sel:WORD_1
	v_cvt_f32_f16_sdwa v64, v92 dst_sel:DWORD dst_unused:UNUSED_PAD src0_sel:WORD_1
	v_cvt_f32_f16_sdwa v76, v108 dst_sel:DWORD dst_unused:UNUSED_PAD src0_sel:WORD_1
	v_add_f32_e32 v64, v64, v76
	v_add_f32_e32 v64, -2.0, v64
	v_fma_f32 v64, v64, v65, 2.0
	v_mul_f32_e32 v54, v64, v54
	v_cvt_f32_f16_sdwa v64, v68 dst_sel:DWORD dst_unused:UNUSED_PAD src0_sel:WORD_1
	v_cvt_f32_f16_sdwa v65, v93 dst_sel:DWORD dst_unused:UNUSED_PAD src0_sel:WORD_1
	v_cvt_f32_f16_e32 v76, v109
	v_mul_f32_e32 v55, v55, v64
	v_fmac_f32_e32 v79, v55, v54
	v_cvt_f32_f16_e32 v54, v77
	v_cvt_f32_f16_sdwa v55, v77 dst_sel:DWORD dst_unused:UNUSED_PAD src0_sel:WORD_1
	v_cvt_f32_f16_e32 v64, v93
	v_cvt_f32_f16_sdwa v77, v109 dst_sel:DWORD dst_unused:UNUSED_PAD src0_sel:WORD_1
	v_pk_add_f32 v[64:65], v[64:65], v[76:77]
	s_nop 0
	v_pk_add_f32 v[64:65], v[64:65], -2.0 op_sel_hi:[1,0]
	s_nop 0
	v_pk_fma_f32 v[64:65], v[64:65], v[66:67], 2.0 op_sel_hi:[1,1,0]
	s_nop 0
	v_pk_mul_f32 v[54:55], v[64:65], v[54:55]
	v_cvt_f32_f16_e32 v64, v69
	v_cvt_f32_f16_sdwa v65, v69 dst_sel:DWORD dst_unused:UNUSED_PAD src0_sel:WORD_1
	v_pk_mul_f32 v[56:57], v[56:57], v[64:65]
	s_nop 0
	v_pk_mul_f32 v[54:55], v[56:57], v[54:55]
	s_nop 0
	v_add_f32_e32 v54, v79, v54
	v_add_f32_e32 v79, v54, v55
	v_add_u32_e32 v54, 32, v100
	v_ashrrev_i32_e32 v55, 31, v54
	v_mad_i64_i32 v[54:55], s[8:9], v16, s60, v[54:55]
	v_lshlrev_b64 v[54:55], 1, v[54:55]
	v_lshl_add_u64 v[56:57], v[24:25], 0, v[54:55]
	global_load_dwordx2 v[76:77], v[56:57], off
	v_lshl_add_u64 v[56:57], v[26:27], 0, v[54:55]
	global_load_dwordx2 v[92:93], v[56:57], off
	v_lshl_add_u64 v[56:57], v[28:29], 0, v[54:55]
	global_load_dwordx2 v[64:65], v[56:57], off
	v_lshl_add_u64 v[56:57], v[30:31], 0, v[54:55]
	global_load_dwordx2 v[108:109], v[56:57], off
	v_lshl_add_u64 v[54:55], v[32:33], 0, v[54:55]
	global_load_dwordx2 v[110:111], v[54:55], off
	s_nop 0
	global_load_dwordx4 v[54:57], v[102:103], off offset:128
	global_load_dwordx4 v[66:69], v[104:105], off offset:128
	s_waitcnt vmcnt(5)
; __device__ __forceinline__ void phase_readout(const Params& p, int l, float* smem) {
;     ...
;     sum += __shfl_xor(sum, 16, 64);
;     sum += __shfl_xor(sum, 32, 64);
;     const float mean = sum * (1.0f / 64.f);
;     float vs = 0.f;
; #pragma unroll
;     for (int nb = 0; nb < 4; ++nb)
; #pragma unroll
;       for (int i = 0; i < 4; ++i) { y[nb][i] -= mean; vs += y[nb][i] * y[nb][i]; }
;     vs += __shfl_xor(vs, 16, 64);
;     vs += __shfl_xor(vs, 32, 64);
;     const float rstd = rsqrtf(vs * (1.0f / 64.f) + 64e-5f);
;     float vv[4][4];
;     float bs = 0.f;
; #pragma unroll
;     for (int nb = 0; nb < 4; ++nb) {
;       const int c = hh * HD + nb * 16 + 4 * g;
;       size_t o = (size_t)row * RD + c;
;       f16x4 r4 = *(const f16x4*)(dR + o), k4 = *(const f16x4*)(dK + o), v4 = *(const f16x4*)(dV + o);
;       f16x4 a04 = *(const f16x4*)(dA0 + o), a14 = *(const f16x4*)(dA1 + o);
;       float4 rk = *(const float4*)(p.in[I_RK] + (size_t)l * RD + c);
;       float4 ka = *(const float4*)(p.in[I_KA] + (size_t)l * RD + c);
;       const float rkv[4] = {rk.x, rk.y, rk.z, rk.w}, kav[4] = {ka.x, ka.y, ka.z, ka.w};
; #pragma unroll
;       for (int i = 0; i < 4; ++i) {
;         float kds = (float)k4[i] * (2.0f + ((float)a04[i] + (float)a14[i] - 2.0f) * kav[i]);
;         bs += (float)r4[i] * rkv[i] * kds;
;         vv[nb][i] = (float)v4[i];
;       }
;     }
;     bs += __shfl_xor(bs, 16, 64);
;     bs += __shfl_xor(bs, 32, 64);
; #pragma unroll
;     for (int nb = 0; nb < 4; ++nb) {
;       const int c = hh * HD + nb * 16 + 4 * g;
;       float4 gwv = *(const float4*)(p.in[I_GNW] + (size_t)l * RD + c);
;       float4 gbv = *(const float4*)(p.in[I_GNB] + (size_t)l * RD + c);
	v_cvt_f32_f16_e32 v112, v92
	v_cvt_f32_f16_sdwa v113, v92 dst_sel:DWORD dst_unused:UNUSED_PAD src0_sel:WORD_1
	s_waitcnt vmcnt(3)
	v_cvt_f32_f16_e32 v114, v108
	v_cvt_f32_f16_sdwa v115, v108 dst_sel:DWORD dst_unused:UNUSED_PAD src0_sel:WORD_1
	s_waitcnt vmcnt(2)
	v_cvt_f32_f16_e32 v116, v110
	v_cvt_f32_f16_sdwa v117, v110 dst_sel:DWORD dst_unused:UNUSED_PAD src0_sel:WORD_1
	v_cvt_f32_f16_e32 v92, v111
	v_pk_add_f32 v[114:115], v[114:115], v[116:117]
	s_nop 0
	v_pk_add_f32 v[114:115], v[114:115], -2.0 op_sel_hi:[1,0]
	s_waitcnt vmcnt(0)
	v_pk_fma_f32 v[66:67], v[114:115], v[66:67], 2.0 op_sel_hi:[1,1,0]
	s_nop 0
	v_pk_mul_f32 v[66:67], v[66:67], v[112:113]
	v_cvt_f32_f16_e32 v112, v76
	v_cvt_f32_f16_sdwa v113, v76 dst_sel:DWORD dst_unused:UNUSED_PAD src0_sel:WORD_1
	v_pk_mul_f32 v[54:55], v[54:55], v[112:113]
	s_nop 0
	v_pk_mul_f32 v[54:55], v[54:55], v[66:67]
	v_cvt_f32_f16_e32 v66, v109
	v_add_f32_e32 v54, v79, v54
	v_add_f32_e32 v76, v54, v55
	v_cvt_f32_f16_e32 v54, v93
	v_cvt_f32_f16_sdwa v55, v93 dst_sel:DWORD dst_unused:UNUSED_PAD src0_sel:WORD_1
	v_cvt_f32_f16_sdwa v67, v109 dst_sel:DWORD dst_unused:UNUSED_PAD src0_sel:WORD_1
	v_cvt_f32_f16_sdwa v93, v111 dst_sel:DWORD dst_unused:UNUSED_PAD src0_sel:WORD_1
	v_pk_add_f32 v[66:67], v[66:67], v[92:93]
	s_nop 0
	v_pk_add_f32 v[66:67], v[66:67], -2.0 op_sel_hi:[1,0]
	s_nop 0
	v_pk_fma_f32 v[66:67], v[66:67], v[68:69], 2.0 op_sel_hi:[1,1,0]
	s_nop 0
	v_pk_mul_f32 v[54:55], v[66:67], v[54:55]
	v_cvt_f32_f16_e32 v66, v77
	v_cvt_f32_f16_sdwa v67, v77 dst_sel:DWORD dst_unused:UNUSED_PAD src0_sel:WORD_1
	v_pk_mul_f32 v[56:57], v[56:57], v[66:67]
	s_nop 0
	v_pk_mul_f32 v[54:55], v[56:57], v[54:55]
	s_nop 0
	v_add_f32_e32 v54, v76, v54
	v_add_f32_e32 v79, v54, v55
	v_add_u32_e32 v54, 48, v100
	v_ashrrev_i32_e32 v55, 31, v54
	v_mad_i64_i32 v[54:55], s[8:9], v16, s60, v[54:55]
	v_lshlrev_b64 v[56:57], 1, v[54:55]
	v_lshl_add_u64 v[54:55], v[24:25], 0, v[56:57]
	v_lshl_add_u64 v[66:67], v[30:31], 0, v[56:57]
	global_load_dwordx2 v[76:77], v[54:55], off
	v_lshl_add_u64 v[54:55], v[26:27], 0, v[56:57]
	global_load_dwordx2 v[108:109], v[66:67], off
	global_load_dwordx2 v[92:93], v[54:55], off
	v_lshl_add_u64 v[54:55], v[28:29], 0, v[56:57]
	v_lshl_add_u64 v[56:57], v[32:33], 0, v[56:57]
	global_load_dwordx2 v[54:55], v[54:55], off
	s_nop 0
	global_load_dwordx2 v[56:57], v[56:57], off
	s_nop 0
	global_load_dwordx4 v[66:69], v[102:103], off offset:192
	s_nop 0
	global_load_dwordx4 v[102:105], v[104:105], off offset:192
	v_lshlrev_b64 v[16:17], 11, v[16:17]
	s_mul_i32 s8, s28, 0x2800
	v_add_u32_e32 v107, s8, v107
	s_waitcnt vmcnt(5)
	v_cvt_f32_f16_e32 v112, v108
	v_cvt_f32_f16_sdwa v113, v108 dst_sel:DWORD dst_unused:UNUSED_PAD src0_sel:WORD_1
	s_waitcnt vmcnt(4)
	v_cvt_f32_f16_e32 v110, v92
	s_waitcnt vmcnt(2)
	v_cvt_f32_f16_e32 v114, v56
	v_cvt_f32_f16_sdwa v115, v56 dst_sel:DWORD dst_unused:UNUSED_PAD src0_sel:WORD_1
	v_cvt_f32_f16_sdwa v111, v92 dst_sel:DWORD dst_unused:UNUSED_PAD src0_sel:WORD_1
	v_cvt_f32_f16_e32 v92, v109
	v_pk_add_f32 v[112:113], v[112:113], v[114:115]
	s_nop 0
	v_pk_add_f32 v[112:113], v[112:113], -2.0 op_sel_hi:[1,0]
	s_waitcnt vmcnt(0)
	v_pk_fma_f32 v[102:103], v[112:113], v[102:103], 2.0 op_sel_hi:[1,1,0]
	s_nop 0
	v_pk_mul_f32 v[102:103], v[102:103], v[110:111]
	v_cvt_f32_f16_e32 v110, v76
	v_cvt_f32_f16_sdwa v111, v76 dst_sel:DWORD dst_unused:UNUSED_PAD src0_sel:WORD_1
	v_pk_mul_f32 v[66:67], v[66:67], v[110:111]
	s_nop 0
	v_pk_mul_f32 v[66:67], v[66:67], v[102:103]
	v_lshl_add_u64 v[102:103], v[38:39], 0, v[16:17]
	v_add_f32_e32 v56, v79, v66
	v_add_f32_e32 v76, v56, v67
	v_cvt_f32_f16_e32 v66, v93
	v_cvt_f32_f16_sdwa v67, v93 dst_sel:DWORD dst_unused:UNUSED_PAD src0_sel:WORD_1
	v_cvt_f32_f16_sdwa v93, v109 dst_sel:DWORD dst_unused:UNUSED_PAD src0_sel:WORD_1
	v_cvt_f32_f16_e32 v56, v57
	v_cvt_f32_f16_sdwa v57, v57 dst_sel:DWORD dst_unused:UNUSED_PAD src0_sel:WORD_1
	v_mov_b32_e32 v79, v84
	v_pk_add_f32 v[56:57], v[92:93], v[56:57]
	s_nop 0
	v_pk_add_f32 v[56:57], v[56:57], -2.0 op_sel_hi:[1,0]
	v_pk_add_f32 v[92:93], v[18:19], v[20:21]
	v_pk_fma_f32 v[56:57], v[56:57], v[104:105], 2.0 op_sel_hi:[1,1,0]
	v_mov_b32_e32 v72, v92
	v_pk_mul_f32 v[56:57], v[56:57], v[66:67]
	v_cvt_f32_f16_e32 v66, v77
	v_cvt_f32_f16_sdwa v67, v77 dst_sel:DWORD dst_unused:UNUSED_PAD src0_sel:WORD_1
	v_mov_b32_e32 v104, v93
	v_mov_b32_e32 v105, v71
	v_pk_add_f32 v[72:73], v[72:73], v[104:105]
	v_pk_mul_f32 v[66:67], v[68:69], v[66:67]
	v_lshl_add_u64 v[68:69], v[50:51], 0, v[22:23]
	v_pk_mul_f32 v[56:57], v[66:67], v[56:57]
	v_lshl_add_u64 v[66:67], v[52:53], 0, v[22:23]
	global_load_dwordx4 v[16:19], v[68:69], off
	global_load_dwordx4 v[20:23], v[66:67], off
	v_add_f32_e32 v56, v76, v56
	v_add_f32_e32 v56, v56, v57
	ds_bpermute_b32 v57, v95, v56
	v_pk_add_f32 v[104:105], v[88:89], v[90:91]
	v_cvt_f32_f16_e32 v76, v74
	v_mov_b32_e32 v81, v105
	v_mov_b32_e32 v83, v104
	s_waitcnt lgkmcnt(0)
	v_add_f32_e32 v56, v56, v57
	ds_bpermute_b32 v57, v106, v56
	v_pk_add_f32 v[80:81], v[80:81], v[82:83]
	v_cvt_f32_f16_sdwa v77, v74 dst_sel:DWORD dst_unused:UNUSED_PAD src0_sel:WORD_1
	v_cvt_f32_f16_e32 v74, v75
	v_cvt_f32_f16_sdwa v75, v75 dst_sel:DWORD dst_unused:UNUSED_PAD src0_sel:WORD_1
	s_waitcnt lgkmcnt(0)
	v_add_f32_e32 v56, v56, v57
	v_add_f32_e32 v57, v72, v73
	v_add_f32_e32 v72, 0, v57
	v_mov_b32_e32 v73, v85
	v_pk_add_f32 v[72:73], v[72:73], v[78:79]
	s_nop 0
	v_pk_add_f32 v[72:73], v[72:73], v[80:81]
	v_lshl_add_u64 v[80:81], v[100:101], 1, v[102:103]
	v_add_f32_e32 v57, v72, v73
	ds_bpermute_b32 v72, v95, v57
	v_mov_b32_e32 v100, v96
	v_mov_b32_e32 v101, v62
	v_mov_b32_e32 v62, v97
	s_waitcnt lgkmcnt(0)
; __device__ __forceinline__ void phase_readout(const Params& p, int l, float* smem) {
;     ...
;     const float mean = sum * (1.0f / 64.f);
;     float vs = 0.f;
; #pragma unroll
;     for (int nb = 0; nb < 4; ++nb)
; #pragma unroll
;       for (int i = 0; i < 4; ++i) { y[nb][i] -= mean; vs += y[nb][i] * y[nb][i]; }
;     vs += __shfl_xor(vs, 16, 64);
;     vs += __shfl_xor(vs, 32, 64);
;     const float rstd = rsqrtf(vs * (1.0f / 64.f) + 64e-5f);
;     float vv[4][4];
;     float bs = 0.f;
; #pragma unroll
;     for (int nb = 0; nb < 4; ++nb) {
;       const int c = hh * HD + nb * 16 + 4 * g;
;       size_t o = (size_t)row * RD + c;
;       f16x4 r4 = *(const f16x4*)(dR + o), k4 = *(const f16x4*)(dK + o), v4 = *(const f16x4*)(dV + o);
;       f16x4 a04 = *(const f16x4*)(dA0 + o), a14 = *(const f16x4*)(dA1 + o);
;       float4 rk = *(const float4*)(p.in[I_RK] + (size_t)l * RD + c);
;       float4 ka = *(const float4*)(p.in[I_KA] + (size_t)l * RD + c);
;       const float rkv[4] = {rk.x, rk.y, rk.z, rk.w}, kav[4] = {ka.x, ka.y, ka.z, ka.w};
; #pragma unroll
;       for (int i = 0; i < 4; ++i) {
;         float kds = (float)k4[i] * (2.0f + ((float)a04[i] + (float)a14[i] - 2.0f) * kav[i]);
;         bs += (float)r4[i] * rkv[i] * kds;
;         vv[nb][i] = (float)v4[i];
;       }
;     }
;     bs += __shfl_xor(bs, 16, 64);
;     bs += __shfl_xor(bs, 32, 64);
; #pragma unroll
;     for (int nb = 0; nb < 4; ++nb) {
;       const int c = hh * HD + nb * 16 + 4 * g;
;       float4 gwv = *(const float4*)(p.in[I_GNW] + (size_t)l * RD + c);
;       float4 gbv = *(const float4*)(p.in[I_GNB] + (size_t)l * RD + c);
;       const float gwa[4] = {gwv.x, gwv.y, gwv.z, gwv.w}, gba[4] = {gbv.x, gbv.y, gbv.z, gbv.w};
;       f16x4 o4;
; #pragma unroll
;       for (int i = 0; i < 4; ++i) o4[i] = (f16)((y[nb][i] * rstd * gwa[i] + gba[i] + bs * vv[nb][i]) * ga[nb][i]);
;       *(f16x4*)(br + (size_t)row * DM + c) = o4;
;     }
;   }
	v_add_f32_e32 v57, v57, v72
	ds_bpermute_b32 v72, v106, v57
	s_waitcnt lgkmcnt(0)
	v_add_f32_e32 v57, v57, v72
	v_mul_f32_e32 v94, 0x3c800000, v57
	v_pk_add_f32 v[82:83], v[92:93], v[94:95] op_sel_hi:[1,0] neg_lo:[0,1] neg_hi:[0,1]
	v_pk_add_f32 v[78:79], v[70:71], v[94:95] op_sel_hi:[1,0] neg_lo:[0,1] neg_hi:[0,1]
	v_pk_mul_f32 v[92:93], v[82:83], v[82:83]
	v_pk_mul_f32 v[90:91], v[78:79], v[78:79]
	v_add_f32_e32 v57, v92, v93
	v_pk_add_f32 v[100:101], v[100:101], v[94:95] op_sel_hi:[1,0] neg_lo:[0,1] neg_hi:[0,1]
	v_add_f32_e32 v57, v90, v57
	v_pk_mul_f32 v[102:103], v[100:101], v[100:101]
	v_add_f32_e32 v57, v91, v57
	v_pk_add_f32 v[70:71], v[104:105], v[94:95] op_sel_hi:[1,0] neg_lo:[0,1] neg_hi:[0,1]
	v_pk_add_f32 v[104:105], v[62:63], v[94:95] op_sel_hi:[1,0] neg_lo:[0,1] neg_hi:[0,1]
	v_add_f32_e32 v57, v102, v57
	v_pk_mul_f32 v[108:109], v[104:105], v[104:105]
	v_add_f32_e32 v57, v103, v57
	v_pk_add_f32 v[96:97], v[60:61], v[94:95] op_sel_hi:[1,0] neg_lo:[0,1] neg_hi:[0,1]
	v_add_f32_e32 v57, v108, v57
	v_pk_mul_f32 v[110:111], v[96:97], v[96:97]
	v_add_f32_e32 v57, v109, v57
	v_pk_add_f32 v[58:59], v[58:59], v[94:95] op_sel_hi:[1,0] neg_lo:[0,1] neg_hi:[0,1]
	v_add_f32_e32 v57, v110, v57
	v_cvt_f32_f16_e32 v62, v64
	v_cvt_f32_f16_sdwa v63, v64 dst_sel:DWORD dst_unused:UNUSED_PAD src0_sel:WORD_1
	v_cvt_f32_f16_e32 v60, v65
	v_cvt_f32_f16_sdwa v61, v65 dst_sel:DWORD dst_unused:UNUSED_PAD src0_sel:WORD_1
	v_pk_mul_f32 v[64:65], v[58:59], v[58:59]
	v_add_f32_e32 v57, v111, v57
	v_pk_add_f32 v[72:73], v[84:85], v[94:95] op_sel_hi:[1,0] neg_lo:[0,1] neg_hi:[0,1]
	v_add_f32_e32 v57, v64, v57
	v_pk_mul_f32 v[88:89], v[72:73], v[72:73]
	v_add_f32_e32 v57, v65, v57
	v_add_f32_e32 v57, v89, v57
	v_pk_mul_f32 v[86:87], v[70:71], v[70:71]
	v_add_f32_e32 v57, v88, v57
	v_add_f32_e32 v57, v87, v57
	v_add_f32_e32 v57, v86, v57
	ds_bpermute_b32 v64, v95, v57
	v_cvt_f32_f16_e32 v84, v98
	v_cvt_f32_f16_sdwa v85, v98 dst_sel:DWORD dst_unused:UNUSED_PAD src0_sel:WORD_1
	v_cvt_f32_f16_e32 v98, v99
	v_cvt_f32_f16_sdwa v99, v99 dst_sel:DWORD dst_unused:UNUSED_PAD src0_sel:WORD_1
	s_waitcnt lgkmcnt(0)
	v_add_f32_e32 v57, v57, v64
	ds_bpermute_b32 v64, v106, v57
	s_waitcnt lgkmcnt(0)
	v_add_f32_e32 v57, v57, v64
	v_fmamk_f32 v57, v57, 0x3c800000, v178
	v_cmp_gt_f32_e32 vcc, s83, v57
	v_mul_f32_e32 v64, 0x4b800000, v57
	s_nop 0
	v_cndmask_b32_e32 v57, v57, v64, vcc
	v_rsq_f32_e32 v57, v57
	s_nop 0
	v_mul_f32_e32 v64, 0x45800000, v57
	v_cndmask_b32_e32 v64, v57, v64, vcc
	v_pk_mul_f32 v[82:83], v[82:83], v[64:65] op_sel_hi:[1,0]
	s_waitcnt vmcnt(0)
	v_pk_fma_f32 v[16:17], v[82:83], v[16:17], v[20:21]
	v_pk_mul_f32 v[20:21], v[100:101], v[64:65] op_sel_hi:[1,0]
	v_pk_fma_f32 v[16:17], v[56:57], v[76:77], v[16:17] op_sel_hi:[0,1,1]
	v_pk_mul_f32 v[12:13], v[12:13], v[16:17]
	v_pk_mul_f32 v[16:17], v[78:79], v[64:65] op_sel_hi:[1,0]
	v_cvt_pk_f16_f32 v12, v12, v13
	v_pk_fma_f32 v[16:17], v[16:17], v[18:19], v[22:23]
	s_nop 0
	v_pk_fma_f32 v[16:17], v[56:57], v[74:75], v[16:17] op_sel_hi:[0,1,1]
	v_pk_mul_f32 v[14:15], v[14:15], v[16:17]
	s_nop 0
	v_cvt_pk_f16_f32 v13, v14, v15
	global_store_dwordx2 v[80:81], v[12:13], off
	global_load_dwordx4 v[12:15], v[68:69], off offset:64
	s_nop 0
	global_load_dwordx4 v[16:19], v[66:67], off offset:64
	s_waitcnt vmcnt(0)
	v_pk_fma_f32 v[12:13], v[20:21], v[12:13], v[16:17]
	s_nop 0
	v_pk_fma_f32 v[12:13], v[56:57], v[84:85], v[12:13] op_sel_hi:[0,1,1]
	v_pk_mul_f32 v[8:9], v[8:9], v[12:13]
	v_pk_mul_f32 v[12:13], v[104:105], v[64:65] op_sel_hi:[1,0]
	v_cvt_pk_f16_f32 v8, v8, v9
	v_pk_fma_f32 v[12:13], v[12:13], v[14:15], v[18:19]
	v_pk_mul_f32 v[16:17], v[96:97], v[64:65] op_sel_hi:[1,0]
	v_pk_fma_f32 v[12:13], v[56:57], v[98:99], v[12:13] op_sel_hi:[0,1,1]
	v_pk_mul_f32 v[10:11], v[10:11], v[12:13]
	s_nop 0
	v_cvt_pk_f16_f32 v9, v10, v11
	global_store_dwordx2 v[80:81], v[8:9], off offset:32
	global_load_dwordx4 v[8:11], v[68:69], off offset:128
	s_nop 0
	global_load_dwordx4 v[12:15], v[66:67], off offset:128
	s_waitcnt vmcnt(0)
	v_pk_fma_f32 v[8:9], v[16:17], v[8:9], v[12:13]
	s_nop 0
	v_pk_fma_f32 v[8:9], v[56:57], v[62:63], v[8:9] op_sel_hi:[0,1,1]
	v_pk_mul_f32 v[4:5], v[4:5], v[8:9]
	v_pk_mul_f32 v[8:9], v[58:59], v[64:65] op_sel_hi:[1,0]
	v_cvt_pk_f16_f32 v4, v4, v5
	v_pk_fma_f32 v[8:9], v[8:9], v[10:11], v[14:15]
	v_cvt_f32_f16_e32 v12, v54
	v_pk_fma_f32 v[8:9], v[56:57], v[60:61], v[8:9] op_sel_hi:[0,1,1]
	v_pk_mul_f32 v[6:7], v[6:7], v[8:9]
	v_cvt_f32_f16_sdwa v13, v54 dst_sel:DWORD dst_unused:UNUSED_PAD src0_sel:WORD_1
	v_cvt_pk_f16_f32 v5, v6, v7
	global_store_dwordx2 v[80:81], v[4:5], off offset:64
	global_load_dwordx4 v[4:7], v[68:69], off offset:192
	s_nop 0
	global_load_dwordx4 v[8:11], v[66:67], off offset:192
	v_pk_mul_f32 v[14:15], v[72:73], v[64:65] op_sel_hi:[1,0]
	s_waitcnt vmcnt(0)
	v_pk_fma_f32 v[4:5], v[14:15], v[4:5], v[8:9] op_sel:[1,0,0] op_sel_hi:[0,1,1]
	v_pk_fma_f32 v[4:5], v[56:57], v[12:13], v[4:5] op_sel_hi:[0,1,1]
	v_pk_mul_f32 v[0:1], v[0:1], v[4:5]
	v_cvt_f32_f16_e32 v4, v55
	v_cvt_f32_f16_sdwa v5, v55 dst_sel:DWORD dst_unused:UNUSED_PAD src0_sel:WORD_1
	v_pk_mul_f32 v[8:9], v[70:71], v[64:65] op_sel_hi:[1,0]
	v_cvt_pk_f16_f32 v0, v0, v1
	v_pk_fma_f32 v[6:7], v[8:9], v[6:7], v[10:11] op_sel:[1,0,0] op_sel_hi:[0,1,1]
	v_pk_fma_f32 v[4:5], v[56:57], v[4:5], v[6:7] op_sel_hi:[0,1,1]
	v_pk_mul_f32 v[2:3], v[2:3], v[4:5]
	s_nop 0
	v_cvt_pk_f16_f32 v1, v2, v3
	global_store_dwordx2 v[80:81], v[0:1], off offset:96
	s_cbranch_scc1 .LBB0_1056

; __device__ __forceinline__ float sigmoidf_(float x) { return 1.0f / (1.0f + __expf(-x)); }
; __device__ __forceinline__ void phase_g2(const Params& p, int l, f16* smem) {
;     ...
; #pragma unroll
;         for (int i = 0; i < 4; ++i)
; #pragma unroll
;           for (int j = 0; j < 4; ++j)
; #pragma unroll
;             for (int r = 0; r < 4; ++r) sg[i][j][r] = (f16)sigmoidf_(ag[i][j][r]);
;       }
;       __builtin_amdgcn_sched_barrier(0);
;       const f16* wo = (const f16*)(p.ws + (x == 0 ? WT_RO_OFF : (x == 1 ? WT_PO_OFF : WT_NO_OFF)));
;       const int kx = x == 1 ? 256 : RD;
;       const int aoff = x == 0 ? 0 : (x == 1 ? RD : 640);
; #pragma unroll
;       for (int h = 0; h < 2; ++h) {
;         f32x4 ab[4][2];
;         zero_acc<2>(ab);
;         gemm_tile_dma<2, true>(BR + (size_t)m0 * DM + aoff, DM, wo + (size_t)(n0 + h * 32) * kx, kx, kx, ab, sA, TIDX(p));
; #pragma unroll
;         for (int i = 0; i < 4; ++i)
; #pragma unroll
;           for (int j = 0; j < 2; ++j)
; #pragma unroll
;             for (int r = 0; r < 4; ++r) am[i][h * 2 + j][r] = (f16)((float)am[i][h * 2 + j][r] + (float)sg[i][h * 2 + j][r] * ab[i][j][r]);
.LBB0_1114:
	v_pk_add_f32 v[150:151], v[148:149], 1.0 op_sel_hi:[1,0]
	v_add_f32_e32 v215, 1.0, v215
	v_add_f32_e32 v214, 1.0, v214
	v_pk_add_f32 v[132:133], v[132:133], 1.0 op_sel_hi:[1,0]
	v_pk_add_f32 v[130:131], v[130:131], 1.0 op_sel_hi:[1,0]
	v_rcp_f32_e32 v149, v151
	s_nop 0
	v_mul_f32_e32 v148, 1.0, v149
	v_pk_add_f32 v[128:129], v[128:129], 1.0 op_sel_hi:[1,0]
	v_pk_add_f32 v[126:127], v[126:127], 1.0 op_sel_hi:[1,0]
	v_pk_add_f32 v[124:125], v[124:125], 1.0 op_sel_hi:[1,0]
	v_rcp_f32_e32 v151, v150
	s_nop 0
	v_mul_f32_e32 v149, 1.0, v151
	v_pk_add_f32 v[150:151], v[146:147], 1.0 op_sel_hi:[1,0]
	v_pk_add_f32 v[122:123], v[122:123], 1.0 op_sel_hi:[1,0]
	v_pk_add_f32 v[120:121], v[120:121], 1.0 op_sel_hi:[1,0]
	v_cvt_pk_f16_f32 v148, v149, v148
	v_pk_add_f32 v[118:119], v[118:119], 1.0 op_sel_hi:[1,0]
	v_rcp_f32_e32 v147, v151
	s_nop 0
	v_mul_f32_e32 v146, 1.0, v147
	s_add_i32 s9, s9, 1
	s_addk_i32 s14, 0x400
	s_cmp_eq_u32 s9, 3
	v_rcp_f32_e32 v151, v150
	s_nop 0
	v_mul_f32_e32 v147, 1.0, v151
	v_pk_add_f32 v[150:151], v[144:145], 1.0 op_sel_hi:[1,0]
	v_cvt_pk_f16_f32 v146, v147, v146
	s_nop 0
	v_rcp_f32_e32 v145, v151
	s_nop 0
	v_mul_f32_e32 v144, 1.0, v145
	s_nop 0
	v_rcp_f32_e32 v151, v150
	s_nop 0
	v_mul_f32_e32 v145, 1.0, v151
	v_pk_add_f32 v[150:151], v[142:143], 1.0 op_sel_hi:[1,0]
	v_cvt_pk_f16_f32 v144, v145, v144
	s_nop 0
	v_rcp_f32_e32 v143, v151
	s_nop 0
	v_mul_f32_e32 v142, 1.0, v143
	s_nop 0
	v_rcp_f32_e32 v151, v150
	s_nop 0
	v_mul_f32_e32 v143, 1.0, v151
	v_add_f32_e32 v150, 1.0, v221
	v_cvt_pk_f16_f32 v142, v143, v142
	v_rcp_f32_e32 v152, v150
	s_nop 0
	v_mul_f32_e32 v151, 1.0, v152
	v_mov_b32_e32 v150, v151
	v_add_f32_e32 v151, 1.0, v220
	s_nop 0
	v_rcp_f32_e32 v153, v151
	s_nop 0
	v_mul_f32_e32 v152, 1.0, v153
	v_mov_b32_e32 v151, v152
	v_add_f32_e32 v152, 1.0, v219
	s_nop 0
	v_rcp_f32_e32 v154, v152
	s_nop 0
	v_mul_f32_e32 v153, 1.0, v154
	v_mov_b32_e32 v152, v153
	v_add_f32_e32 v153, 1.0, v218
	s_nop 0
	v_rcp_f32_e32 v155, v153
	s_nop 0
	v_mul_f32_e32 v154, 1.0, v155
	v_mov_b32_e32 v153, v154
	v_pk_add_f32 v[154:155], v[140:141], 1.0 op_sel_hi:[1,0]
	s_nop 0
	s_nop 0
	v_rcp_f32_e32 v141, v155
	s_nop 0
	v_mul_f32_e32 v140, 1.0, v141
	s_nop 0
	v_rcp_f32_e32 v155, v154
	s_nop 0
	v_mul_f32_e32 v141, 1.0, v155
	v_pk_add_f32 v[154:155], v[138:139], 1.0 op_sel_hi:[1,0]
	v_cvt_pk_f16_f32 v140, v141, v140
	s_nop 0
	v_rcp_f32_e32 v139, v155
	s_nop 0
	v_mul_f32_e32 v138, 1.0, v139
	s_nop 0
	v_rcp_f32_e32 v155, v154
	s_nop 0
	v_mul_f32_e32 v139, 1.0, v155
	v_pk_add_f32 v[154:155], v[136:137], 1.0 op_sel_hi:[1,0]
	v_cvt_pk_f16_f32 v138, v139, v138
	s_nop 0
	v_rcp_f32_e32 v137, v155
	s_nop 0
	v_mul_f32_e32 v136, 1.0, v137
	s_nop 0
	v_rcp_f32_e32 v155, v154
	s_nop 0
	v_mul_f32_e32 v137, 1.0, v155
	v_pk_add_f32 v[154:155], v[134:135], 1.0 op_sel_hi:[1,0]
	v_cvt_pk_f16_f32 v139, v137, v136
	v_cvt_f32_f16_e32 v136, v148
	v_cvt_f32_f16_sdwa v137, v148 dst_sel:DWORD dst_unused:UNUSED_PAD src0_sel:WORD_1
	v_rcp_f32_e32 v135, v155
	s_nop 0
	v_mul_f32_e32 v134, 1.0, v135
	s_nop 0
	v_rcp_f32_e32 v155, v154
	s_nop 0
	v_mul_f32_e32 v135, 1.0, v155
	v_add_f32_e32 v154, 1.0, v217
	v_cvt_pk_f16_f32 v141, v135, v134
	v_cvt_f32_f16_sdwa v135, v112 dst_sel:DWORD dst_unused:UNUSED_PAD src0_sel:WORD_1
	v_cvt_f32_f16_e32 v134, v112
	v_rcp_f32_e32 v217, v154
	s_nop 0
	v_mul_f32_e32 v155, 1.0, v217
	v_mov_b32_e32 v154, v155
	v_add_f32_e32 v155, 1.0, v216
	v_pk_fma_f32 v[60:61], v[60:61], v[136:137], v[134:135]
	v_cvt_f32_f16_e32 v134, v146
	v_cvt_pk_f16_f32 v112, v60, v61
	v_rcp_f32_e32 v217, v155
	s_nop 0
	v_mul_f32_e32 v216, 1.0, v217
	v_mov_b32_e32 v155, v216
	v_cvt_f32_f16_sdwa v61, v113 dst_sel:DWORD dst_unused:UNUSED_PAD src0_sel:WORD_1
	v_cvt_f32_f16_e32 v60, v113
	v_cvt_f32_f16_sdwa v135, v146 dst_sel:DWORD dst_unused:UNUSED_PAD src0_sel:WORD_1
	v_rcp_f32_e32 v217, v215
	s_nop 0
	v_mul_f32_e32 v216, 1.0, v217
	v_mov_b32_e32 v215, v216
	v_pk_fma_f32 v[60:61], v[62:63], v[134:135], v[60:61]
	v_cvt_f32_f16_e32 v62, v144
	v_cvt_pk_f16_f32 v113, v60, v61
	v_rcp_f32_e32 v217, v214
	s_nop 0
	v_mul_f32_e32 v216, 1.0, v217
	v_mov_b32_e32 v214, v216
	v_cvt_f32_f16_sdwa v61, v108 dst_sel:DWORD dst_unused:UNUSED_PAD src0_sel:WORD_1
	v_cvt_f32_f16_e32 v60, v108
	v_cvt_f32_f16_sdwa v63, v144 dst_sel:DWORD dst_unused:UNUSED_PAD src0_sel:WORD_1
	v_rcp_f32_e32 v217, v133
	s_nop 0
	v_mul_f32_e32 v216, 1.0, v217
	v_pk_fma_f32 v[56:57], v[56:57], v[62:63], v[60:61]
	v_cvt_f32_f16_e32 v60, v142
	v_cvt_pk_f16_f32 v108, v56, v57
	v_rcp_f32_e32 v217, v132
	s_nop 0
	v_mul_f32_e32 v133, 1.0, v217
	v_mov_b32_e32 v217, v133
	v_cvt_f32_f16_sdwa v57, v109 dst_sel:DWORD dst_unused:UNUSED_PAD src0_sel:WORD_1
	v_cvt_f32_f16_e32 v56, v109
	v_cvt_f32_f16_sdwa v61, v142 dst_sel:DWORD dst_unused:UNUSED_PAD src0_sel:WORD_1
	v_rcp_f32_e32 v133, v131
	s_nop 0
	v_mul_f32_e32 v132, 1.0, v133
	v_mov_b32_e32 v218, v132
	v_pk_fma_f32 v[56:57], v[58:59], v[60:61], v[56:57]
	v_cvt_f32_f16_e32 v58, v140
	v_cvt_pk_f16_f32 v109, v56, v57
	v_rcp_f32_e32 v132, v130
	s_nop 0
	v_mul_f32_e32 v131, 1.0, v132
	v_mov_b32_e32 v219, v131
	v_cvt_f32_f16_sdwa v57, v102 dst_sel:DWORD dst_unused:UNUSED_PAD src0_sel:WORD_1
	v_cvt_f32_f16_e32 v56, v102
	v_cvt_f32_f16_sdwa v59, v140 dst_sel:DWORD dst_unused:UNUSED_PAD src0_sel:WORD_1
	v_rcp_f32_e32 v131, v129
	s_nop 0
	v_mul_f32_e32 v130, 1.0, v131
	v_mov_b32_e32 v220, v130
	v_pk_fma_f32 v[52:53], v[52:53], v[58:59], v[56:57]
	v_cvt_f32_f16_e32 v56, v138
	v_cvt_pk_f16_f32 v102, v52, v53
	v_rcp_f32_e32 v130, v128
	s_nop 0
	v_mul_f32_e32 v129, 1.0, v130
	v_mov_b32_e32 v221, v129
	v_cvt_f32_f16_sdwa v53, v103 dst_sel:DWORD dst_unused:UNUSED_PAD src0_sel:WORD_1
; __device__ __forceinline__ float sigmoidf_(float x) { return 1.0f / (1.0f + __expf(-x)); }
; __device__ __forceinline__ void phase_g2(const Params& p, int l, f16* smem) {
;     ...
; #pragma unroll
;         for (int i = 0; i < 4; ++i)
; #pragma unroll
;           for (int j = 0; j < 4; ++j)
; #pragma unroll
;             for (int r = 0; r < 4; ++r) sg[i][j][r] = (f16)sigmoidf_(ag[i][j][r]);
;       }
;       __builtin_amdgcn_sched_barrier(0);
;       const f16* wo = (const f16*)(p.ws + (x == 0 ? WT_RO_OFF : (x == 1 ? WT_PO_OFF : WT_NO_OFF)));
;       const int kx = x == 1 ? 256 : RD;
;       const int aoff = x == 0 ? 0 : (x == 1 ? RD : 640);
; #pragma unroll
;       for (int h = 0; h < 2; ++h) {
;         f32x4 ab[4][2];
;         zero_acc<2>(ab);
;         gemm_tile_dma<2, true>(BR + (size_t)m0 * DM + aoff, DM, wo + (size_t)(n0 + h * 32) * kx, kx, kx, ab, sA, TIDX(p));
; #pragma unroll
;         for (int i = 0; i < 4; ++i)
; #pragma unroll
;           for (int j = 0; j < 2; ++j)
; #pragma unroll
;             for (int r = 0; r < 4; ++r) am[i][h * 2 + j][r] = (f16)((float)am[i][h * 2 + j][r] + (float)sg[i][h * 2 + j][r] * ab[i][j][r]);
	v_cvt_f32_f16_e32 v52, v103
	v_cvt_f32_f16_sdwa v57, v138 dst_sel:DWORD dst_unused:UNUSED_PAD src0_sel:WORD_1
	v_rcp_f32_e32 v129, v127
	s_nop 0
	v_mul_f32_e32 v128, 1.0, v129
	v_mov_b32_e32 v222, v128
	v_pk_fma_f32 v[52:53], v[54:55], v[56:57], v[52:53]
	v_cvt_f32_f16_e32 v54, v139
	v_cvt_pk_f16_f32 v103, v52, v53
	v_rcp_f32_e32 v128, v126
	s_nop 0
	v_mul_f32_e32 v127, 1.0, v128
	v_mov_b32_e32 v223, v127
	v_add_f32_e32 v126, 1.0, v213
	v_cvt_f32_f16_sdwa v53, v100 dst_sel:DWORD dst_unused:UNUSED_PAD src0_sel:WORD_1
	v_cvt_f32_f16_e32 v52, v100
	v_cvt_f32_f16_sdwa v55, v139 dst_sel:DWORD dst_unused:UNUSED_PAD src0_sel:WORD_1
	v_rcp_f32_e32 v128, v126
	s_nop 0
	v_mul_f32_e32 v127, 1.0, v128
	v_mov_b32_e32 v213, v127
	v_add_f32_e32 v126, 1.0, v212
	v_pk_fma_f32 v[48:49], v[48:49], v[54:55], v[52:53]
	v_cvt_f32_f16_e32 v52, v141
	v_cvt_pk_f16_f32 v100, v48, v49
	v_rcp_f32_e32 v128, v126
	s_nop 0
	v_mul_f32_e32 v127, 1.0, v128
	v_mov_b32_e32 v212, v127
	v_add_f32_e32 v126, 1.0, v211
	v_cvt_f32_f16_sdwa v49, v101 dst_sel:DWORD dst_unused:UNUSED_PAD src0_sel:WORD_1
	v_cvt_f32_f16_e32 v48, v101
	v_cvt_f32_f16_sdwa v53, v141 dst_sel:DWORD dst_unused:UNUSED_PAD src0_sel:WORD_1
	v_rcp_f32_e32 v128, v126
	s_nop 0
	v_mul_f32_e32 v127, 1.0, v128
	v_mov_b32_e32 v211, v127
	v_add_f32_e32 v126, 1.0, v210
	v_cvt_pk_f16_f32 v143, v217, v216
	v_pk_fma_f32 v[48:49], v[50:51], v[52:53], v[48:49]
	v_cvt_f32_f16_e32 v50, v143
	v_rcp_f32_e32 v128, v126
	s_nop 0
	v_mul_f32_e32 v127, 1.0, v128
	v_mov_b32_e32 v210, v127
	v_cvt_pk_f16_f32 v101, v48, v49
	v_cvt_f32_f16_sdwa v49, v94 dst_sel:DWORD dst_unused:UNUSED_PAD src0_sel:WORD_1
	v_cvt_f32_f16_e32 v48, v94
	v_rcp_f32_e32 v127, v125
	s_nop 0
	v_mul_f32_e32 v126, 1.0, v127
	v_mov_b32_e32 v224, v126
	v_cvt_f32_f16_sdwa v51, v143 dst_sel:DWORD dst_unused:UNUSED_PAD src0_sel:WORD_1
	v_cvt_pk_f16_f32 v145, v219, v218
	v_cvt_pk_f16_f32 v147, v221, v220
	v_rcp_f32_e32 v126, v124
	s_nop 0
	v_mul_f32_e32 v125, 1.0, v126
	v_mov_b32_e32 v225, v125
	v_pk_fma_f32 v[44:45], v[44:45], v[50:51], v[48:49]
	v_cvt_f32_f16_e32 v48, v145
	v_cvt_pk_f16_f32 v94, v44, v45
	v_rcp_f32_e32 v125, v123
	s_nop 0
	v_mul_f32_e32 v124, 1.0, v125
	v_mov_b32_e32 v226, v124
	v_cvt_f32_f16_sdwa v45, v95 dst_sel:DWORD dst_unused:UNUSED_PAD src0_sel:WORD_1
	v_cvt_f32_f16_e32 v44, v95
	v_cvt_f32_f16_sdwa v49, v145 dst_sel:DWORD dst_unused:UNUSED_PAD src0_sel:WORD_1
	v_rcp_f32_e32 v124, v122
	s_nop 0
	v_mul_f32_e32 v123, 1.0, v124
	v_mov_b32_e32 v227, v123
	v_pk_fma_f32 v[44:45], v[46:47], v[48:49], v[44:45]
	v_cvt_f32_f16_e32 v46, v147
	v_cvt_pk_f16_f32 v95, v44, v45
	v_rcp_f32_e32 v123, v121
	s_nop 0
	v_mul_f32_e32 v122, 1.0, v123
	v_mov_b32_e32 v121, v122
	v_cvt_f32_f16_sdwa v45, v92 dst_sel:DWORD dst_unused:UNUSED_PAD src0_sel:WORD_1
	v_cvt_f32_f16_e32 v44, v92
	v_cvt_f32_f16_sdwa v47, v147 dst_sel:DWORD dst_unused:UNUSED_PAD src0_sel:WORD_1
	v_rcp_f32_e32 v123, v120
	s_nop 0
	v_mul_f32_e32 v122, 1.0, v123
	v_mov_b32_e32 v120, v122
	v_cvt_pk_f16_f32 v149, v223, v222
	v_pk_fma_f32 v[40:41], v[40:41], v[46:47], v[44:45]
	v_cvt_f32_f16_e32 v44, v149
	v_rcp_f32_e32 v123, v119
	s_nop 0
	v_mul_f32_e32 v122, 1.0, v123
	v_mov_b32_e32 v119, v122
	v_cvt_pk_f16_f32 v92, v40, v41
	v_cvt_f32_f16_sdwa v41, v93 dst_sel:DWORD dst_unused:UNUSED_PAD src0_sel:WORD_1
	v_cvt_f32_f16_e32 v40, v93
	v_rcp_f32_e32 v123, v118
	s_nop 0
	v_mul_f32_e32 v122, 1.0, v123
	v_mov_b32_e32 v118, v122
	v_add_f32_e32 v122, 1.0, v209
	v_cvt_f32_f16_sdwa v45, v149 dst_sel:DWORD dst_unused:UNUSED_PAD src0_sel:WORD_1
	v_cvt_f16_f32_e32 v133, v150
	v_cvt_pk_f16_f32 v150, v225, v224
	v_rcp_f32_e32 v124, v122
	s_nop 0
	v_mul_f32_e32 v123, 1.0, v124
	v_mov_b32_e32 v209, v123
	v_add_f32_e32 v122, 1.0, v208
	v_pk_fma_f32 v[40:41], v[42:43], v[44:45], v[40:41]
	v_cvt_f32_f16_e32 v42, v150
	v_cvt_pk_f16_f32 v93, v40, v41
	v_rcp_f32_e32 v124, v122
	v_cvt_f32_f16_sdwa v41, v86 dst_sel:DWORD dst_unused:UNUSED_PAD src0_sel:WORD_1
	v_cvt_f32_f16_e32 v40, v86
	v_cvt_f32_f16_sdwa v43, v150 dst_sel:DWORD dst_unused:UNUSED_PAD src0_sel:WORD_1
	s_nop 0
	v_mul_f32_e32 v123, 1.0, v124
	v_mov_b32_e32 v208, v123
	v_add_f32_e32 v122, 1.0, v207
	v_cvt_f16_f32_e32 v132, v151
	v_cvt_pk_f16_f32 v151, v227, v226
	v_pk_fma_f32 v[36:37], v[36:37], v[42:43], v[40:41]
	v_cvt_f32_f16_e32 v40, v151
	v_cvt_pk_f16_f32 v86, v36, v37
	v_cvt_f32_f16_sdwa v37, v87 dst_sel:DWORD dst_unused:UNUSED_PAD src0_sel:WORD_1
	v_cvt_f32_f16_e32 v36, v87
	v_cvt_f32_f16_sdwa v41, v151 dst_sel:DWORD dst_unused:UNUSED_PAD src0_sel:WORD_1
	v_rcp_f32_e32 v124, v122
	v_cvt_f16_f32_e32 v131, v152
	v_cvt_pk_f16_f32 v152, v120, v121
	v_pk_fma_f32 v[36:37], v[38:39], v[40:41], v[36:37]
	v_cvt_pk_f16_f32 v87, v36, v37
	v_cvt_f32_f16_sdwa v37, v84 dst_sel:DWORD dst_unused:UNUSED_PAD src0_sel:WORD_1
	v_cvt_f32_f16_e32 v36, v84
	v_cvt_f32_f16_e32 v38, v152
	v_cvt_f32_f16_sdwa v39, v152 dst_sel:DWORD dst_unused:UNUSED_PAD src0_sel:WORD_1
	s_nop 0
	v_mul_f32_e32 v123, 1.0, v124
	v_cvt_f16_f32_e32 v130, v153
	v_cvt_pk_f16_f32 v153, v118, v119
	v_pk_fma_f32 v[32:33], v[32:33], v[38:39], v[36:37]
	v_mov_b32_e32 v207, v123
	v_add_f32_e32 v122, 1.0, v206
	v_cvt_pk_f16_f32 v84, v32, v33
	v_cvt_f32_f16_sdwa v33, v85 dst_sel:DWORD dst_unused:UNUSED_PAD src0_sel:WORD_1
	v_cvt_f32_f16_e32 v32, v85
	v_cvt_f32_f16_e32 v36, v153
	v_cvt_f32_f16_sdwa v37, v153 dst_sel:DWORD dst_unused:UNUSED_PAD src0_sel:WORD_1
	v_pk_fma_f32 v[32:33], v[34:35], v[36:37], v[32:33]
	v_cvt_f16_f32_e32 v129, v154
	v_cvt_pk_f16_f32 v85, v32, v33
	v_add_f32_e32 v32, 1.0, v205
	v_rcp_f32_e32 v124, v122
	s_nop 0
	v_mul_f32_e32 v123, 1.0, v124
	v_rcp_f32_e32 v34, v32
	s_nop 0
	v_mul_f32_e32 v33, 1.0, v34
; __device__ __forceinline__ float sigmoidf_(float x) { return 1.0f / (1.0f + __expf(-x)); }
; __device__ __forceinline__ void phase_g2(const Params& p, int l, f16* smem) {
;     ...
; #pragma unroll
;         for (int i = 0; i < 4; ++i)
; #pragma unroll
;           for (int j = 0; j < 4; ++j)
; #pragma unroll
;             for (int r = 0; r < 4; ++r) sg[i][j][r] = (f16)sigmoidf_(ag[i][j][r]);
;       }
;       __builtin_amdgcn_sched_barrier(0);
;       const f16* wo = (const f16*)(p.ws + (x == 0 ? WT_RO_OFF : (x == 1 ? WT_PO_OFF : WT_NO_OFF)));
;       const int kx = x == 1 ? 256 : RD;
;       const int aoff = x == 0 ? 0 : (x == 1 ? RD : 640);
; #pragma unroll
;       for (int h = 0; h < 2; ++h) {
;         f32x4 ab[4][2];
;         zero_acc<2>(ab);
;         gemm_tile_dma<2, true>(BR + (size_t)m0 * DM + aoff, DM, wo + (size_t)(n0 + h * 32) * kx, kx, kx, ab, sA, TIDX(p));
; #pragma unroll
;         for (int i = 0; i < 4; ++i)
; #pragma unroll
;           for (int j = 0; j < 2; ++j)
; #pragma unroll
;             for (int r = 0; r < 4; ++r) am[i][h * 2 + j][r] = (f16)((float)am[i][h * 2 + j][r] + (float)sg[i][h * 2 + j][r] * ab[i][j][r]);
	v_mov_b32_e32 v32, v33
	v_add_f32_e32 v33, 1.0, v204
	v_cvt_f16_f32_e32 v128, v155
	v_cvt_f16_f32_e32 v127, v215
	v_cvt_f16_f32_e32 v126, v214
	v_rcp_f32_e32 v35, v33
	s_nop 0
	v_mul_f32_e32 v34, 1.0, v35
	v_mov_b32_e32 v33, v34
	v_add_f32_e32 v34, 1.0, v203
	v_cvt_f16_f32_e32 v125, v213
	v_cvt_f16_f32_e32 v124, v212
	v_mov_b32_e32 v206, v123
	v_rcp_f32_e32 v36, v34
	s_nop 0
	v_mul_f32_e32 v35, 1.0, v36
	v_mov_b32_e32 v34, v35
	v_add_f32_e32 v35, 1.0, v202
	v_cvt_f16_f32_e32 v123, v211
	v_cvt_f16_f32_e32 v122, v210
	v_cvt_f16_f32_e32 v121, v209
	v_rcp_f32_e32 v37, v35
	s_nop 0
	v_mul_f32_e32 v36, 1.0, v37
	v_mov_b32_e32 v35, v36
	v_add_f32_e32 v36, 1.0, v201
	v_cvt_f16_f32_e32 v120, v208
	v_cvt_f16_f32_e32 v119, v207
	v_cvt_f16_f32_e32 v118, v206
	v_rcp_f32_e32 v38, v36
	s_nop 0
	v_mul_f32_e32 v37, 1.0, v38
	v_mov_b32_e32 v36, v37
	v_add_f32_e32 v37, 1.0, v200
	v_cvt_f16_f32_e32 v36, v36
	v_rcp_f32_e32 v39, v37
	s_nop 0
	v_mul_f32_e32 v38, 1.0, v39
	v_mov_b32_e32 v37, v38
	v_add_f32_e32 v38, 1.0, v199
	v_cvt_f16_f32_e32 v37, v37
	v_rcp_f32_e32 v40, v38
	s_nop 0
	v_mul_f32_e32 v39, 1.0, v40
	v_mov_b32_e32 v38, v39
	v_add_f32_e32 v39, 1.0, v198
	v_cvt_f16_f32_e32 v38, v38
	v_rcp_f32_e32 v41, v39
	s_nop 0
	v_mul_f32_e32 v40, 1.0, v41
	v_mov_b32_e32 v39, v40
	v_add_f32_e32 v40, 1.0, v197
	v_cvt_f16_f32_e32 v39, v39
	v_rcp_f32_e32 v42, v40
	s_nop 0
	v_mul_f32_e32 v41, 1.0, v42
	v_mov_b32_e32 v40, v41
	v_add_f32_e32 v41, 1.0, v196
	v_cvt_f16_f32_e32 v40, v40
	v_rcp_f32_e32 v43, v41
	s_nop 0
	v_mul_f32_e32 v42, 1.0, v43
	v_mov_b32_e32 v41, v42
	v_add_f32_e32 v42, 1.0, v195
	v_cvt_f16_f32_e32 v41, v41
	v_rcp_f32_e32 v44, v42
	s_nop 0
	v_mul_f32_e32 v43, 1.0, v44
	v_mov_b32_e32 v42, v43
	v_add_f32_e32 v43, 1.0, v194
	v_cvt_f16_f32_e32 v42, v42
	v_rcp_f32_e32 v45, v43
	s_nop 0
	v_mul_f32_e32 v44, 1.0, v45
	v_mov_b32_e32 v43, v44
	v_add_f32_e32 v44, 1.0, v193
	v_cvt_f16_f32_e32 v43, v43
	v_rcp_f32_e32 v46, v44
	s_nop 0
	v_mul_f32_e32 v45, 1.0, v46
	v_mov_b32_e32 v44, v45
	v_add_f32_e32 v45, 1.0, v192
	v_cvt_f16_f32_e32 v44, v44
	v_rcp_f32_e32 v47, v45
	s_nop 0
	v_mul_f32_e32 v46, 1.0, v47
	v_mov_b32_e32 v45, v46
	v_add_f32_e32 v46, 1.0, v170
	v_cvt_f16_f32_e32 v45, v45
	v_rcp_f32_e32 v48, v46
	s_nop 0
	v_mul_f32_e32 v47, 1.0, v48
	v_mov_b32_e32 v46, v47
	v_add_f32_e32 v47, 1.0, v169
	v_cvt_f16_f32_e32 v46, v46
	v_rcp_f32_e32 v49, v47
	s_nop 0
	v_mul_f32_e32 v48, 1.0, v49
	v_mov_b32_e32 v47, v48
	v_cvt_f16_f32_e32 v48, v32
	v_cvt_f16_f32_e32 v49, v33
	v_cvt_f16_f32_e32 v50, v34
	v_cvt_f16_f32_e32 v51, v35
	v_cvt_f32_f16_sdwa v33, v106 dst_sel:DWORD dst_unused:UNUSED_PAD src0_sel:WORD_1
	v_cvt_f32_f16_e32 v32, v106
	v_cvt_f32_f16_e32 v35, v48
	v_cvt_f32_f16_e32 v34, v133
	v_cvt_f16_f32_e32 v47, v47
	v_pk_fma_f32 v[28:29], v[28:29], v[34:35], v[32:33]
	s_nop 0
	v_cvt_pk_f16_f32 v106, v28, v29
	v_cvt_f32_f16_sdwa v29, v107 dst_sel:DWORD dst_unused:UNUSED_PAD src0_sel:WORD_1
	v_cvt_f32_f16_e32 v28, v107
	v_cvt_f32_f16_e32 v33, v49
	v_cvt_f32_f16_e32 v32, v132
	v_pk_fma_f32 v[28:29], v[30:31], v[32:33], v[28:29]
	s_nop 0
	v_cvt_pk_f16_f32 v107, v28, v29
	v_cvt_f32_f16_sdwa v29, v104 dst_sel:DWORD dst_unused:UNUSED_PAD src0_sel:WORD_1
	v_cvt_f32_f16_e32 v28, v104
	v_cvt_f32_f16_e32 v31, v50
	v_cvt_f32_f16_e32 v30, v131
	v_pk_fma_f32 v[24:25], v[24:25], v[30:31], v[28:29]
	s_nop 0
	v_cvt_pk_f16_f32 v104, v24, v25
	v_cvt_f32_f16_sdwa v25, v105 dst_sel:DWORD dst_unused:UNUSED_PAD src0_sel:WORD_1
	v_cvt_f32_f16_e32 v24, v105
	v_cvt_f32_f16_e32 v29, v51
	v_cvt_f32_f16_e32 v28, v130
	v_pk_fma_f32 v[24:25], v[26:27], v[28:29], v[24:25]
	s_nop 0
	v_cvt_pk_f16_f32 v105, v24, v25
	v_cvt_f32_f16_sdwa v25, v98 dst_sel:DWORD dst_unused:UNUSED_PAD src0_sel:WORD_1
	v_cvt_f32_f16_e32 v24, v98
	v_cvt_f32_f16_e32 v27, v36
	v_cvt_f32_f16_e32 v26, v129
	v_pk_fma_f32 v[20:21], v[20:21], v[26:27], v[24:25]
	s_nop 0
	v_cvt_pk_f16_f32 v98, v20, v21
	v_cvt_f32_f16_sdwa v21, v99 dst_sel:DWORD dst_unused:UNUSED_PAD src0_sel:WORD_1
	v_cvt_f32_f16_e32 v20, v99
	v_cvt_f32_f16_e32 v25, v37
	v_cvt_f32_f16_e32 v24, v128
	v_pk_fma_f32 v[20:21], v[22:23], v[24:25], v[20:21]
	s_nop 0
	v_cvt_pk_f16_f32 v99, v20, v21
	v_cvt_f32_f16_sdwa v21, v96 dst_sel:DWORD dst_unused:UNUSED_PAD src0_sel:WORD_1
	v_cvt_f32_f16_e32 v20, v96
	v_cvt_f32_f16_e32 v23, v38
	v_cvt_f32_f16_e32 v22, v127
	v_pk_fma_f32 v[16:17], v[16:17], v[22:23], v[20:21]
	s_nop 0
	v_cvt_pk_f16_f32 v96, v16, v17
	v_cvt_f32_f16_sdwa v17, v97 dst_sel:DWORD dst_unused:UNUSED_PAD src0_sel:WORD_1
	v_cvt_f32_f16_e32 v16, v97
	v_cvt_f32_f16_e32 v21, v39
	v_cvt_f32_f16_e32 v20, v126
	v_pk_fma_f32 v[16:17], v[18:19], v[20:21], v[16:17]
	s_nop 0
	v_cvt_pk_f16_f32 v97, v16, v17
	v_cvt_f32_f16_sdwa v17, v90 dst_sel:DWORD dst_unused:UNUSED_PAD src0_sel:WORD_1
	v_cvt_f32_f16_e32 v16, v90
	v_cvt_f32_f16_e32 v19, v40
	v_cvt_f32_f16_e32 v18, v125
	v_pk_fma_f32 v[12:13], v[12:13], v[18:19], v[16:17]
	s_nop 0
	v_cvt_pk_f16_f32 v90, v12, v13
	v_cvt_f32_f16_sdwa v13, v91 dst_sel:DWORD dst_unused:UNUSED_PAD src0_sel:WORD_1
	v_cvt_f32_f16_e32 v12, v91
	v_cvt_f32_f16_e32 v17, v41
	v_cvt_f32_f16_e32 v16, v124
	v_pk_fma_f32 v[12:13], v[14:15], v[16:17], v[12:13]
	s_nop 0
	v_cvt_pk_f16_f32 v91, v12, v13
	v_cvt_f32_f16_sdwa v13, v88 dst_sel:DWORD dst_unused:UNUSED_PAD src0_sel:WORD_1
	v_cvt_f32_f16_e32 v12, v88
	v_cvt_f32_f16_e32 v15, v42
	v_cvt_f32_f16_e32 v14, v123
	v_pk_fma_f32 v[8:9], v[8:9], v[14:15], v[12:13]
	s_nop 0
	v_cvt_pk_f16_f32 v88, v8, v9
	v_cvt_f32_f16_sdwa v9, v89 dst_sel:DWORD dst_unused:UNUSED_PAD src0_sel:WORD_1
	v_cvt_f32_f16_e32 v8, v89
	v_cvt_f32_f16_e32 v13, v43
	v_cvt_f32_f16_e32 v12, v122
	v_pk_fma_f32 v[8:9], v[10:11], v[12:13], v[8:9]
	s_nop 0
	v_cvt_pk_f16_f32 v89, v8, v9
	v_cvt_f32_f16_sdwa v9, v82 dst_sel:DWORD dst_unused:UNUSED_PAD src0_sel:WORD_1
	v_cvt_f32_f16_e32 v8, v82
	v_cvt_f32_f16_e32 v11, v44
	v_cvt_f32_f16_e32 v10, v121
	v_pk_fma_f32 v[4:5], v[4:5], v[10:11], v[8:9]
	s_nop 0
	v_cvt_pk_f16_f32 v82, v4, v5
	v_cvt_f32_f16_sdwa v5, v83 dst_sel:DWORD dst_unused:UNUSED_PAD src0_sel:WORD_1
	v_cvt_f32_f16_e32 v4, v83
	v_cvt_f32_f16_e32 v9, v45
	v_cvt_f32_f16_e32 v8, v120
	v_pk_fma_f32 v[4:5], v[6:7], v[8:9], v[4:5]
	s_nop 0
	v_cvt_pk_f16_f32 v83, v4, v5
	v_cvt_f32_f16_sdwa v5, v80 dst_sel:DWORD dst_unused:UNUSED_PAD src0_sel:WORD_1
	v_cvt_f32_f16_e32 v4, v80
	v_cvt_f32_f16_e32 v7, v46
	v_cvt_f32_f16_e32 v6, v119
	v_pk_fma_f32 v[0:1], v[0:1], v[6:7], v[4:5]
	s_nop 0
	v_cvt_pk_f16_f32 v80, v0, v1
	v_cvt_f32_f16_sdwa v1, v81 dst_sel:DWORD dst_unused:UNUSED_PAD src0_sel:WORD_1
	v_cvt_f32_f16_e32 v0, v81
	v_cvt_f32_f16_e32 v5, v47
	v_cvt_f32_f16_e32 v4, v118
	v_pk_fma_f32 v[0:1], v[2:3], v[4:5], v[0:1]
	s_nop 0
	v_cvt_pk_f16_f32 v81, v0, v1
	s_cbranch_scc1 .LBB0_1112

; template <int NJ>
; __device__ __forceinline__ void gemm_tile(const f16* __restrict__ A, int lda, const f16* __restrict__ Bt, int ldb,
;                                           int K, f32x4 (&acc)[4][NJ], f16* sA, f16* sB, const int tid) {
;     ...
; #pragma unroll 1
;   for (int k0 = 0; k0 < K; k0 += 128) {
;     {
;       const int kof = (k0 + 192 < K) ? k0 + 192 : K - 64;
;       G_STEP(0, ra1, rb1, true, true, kof)
;     }
;     __syncthreads();
;     if (k0 + 64 >= K) break;
;     {
;       const int kof = (k0 + 256 < K) ? k0 + 256 : K - 64;
;       G_STEP(1, ra0, rb0, true, true, kof)
.LBB0_1398:
	ds_read_b128 v[166:169], v148 offset:16384
	ds_read_b128 v[192:195], v148 offset:18432
	ds_read_b128 v[196:199], v148 offset:20480
	ds_read_b128 v[200:203], v148 offset:22528
	s_add_i32 s13, s11, 0xc0
	ds_read_b128 v[152:155], v150
	ds_read_b128 v[156:159], v150 offset:2048
	s_cmpk_lt_u32 s11, 0x340
	s_cselect_b32 s42, s13, 0x3c0
	ds_read_b128 v[160:163], v150 offset:4096
	s_lshl_b64 s[14:15], s[42:43], 1
	v_lshl_add_u64 v[144:145], v[138:139], 0, s[14:15]
	ds_read_b128 v[128:131], v150 offset:6144
	ds_read_b128 v[244:247], v243 offset:16384
	ds_read_b128 v[248:251], v243 offset:18432
	ds_read_b128 v[252:255], v243 offset:20480
	s_waitcnt lgkmcnt(6)
	v_mfma_f32_16x16x32_f16 v[124:127], v[166:169], v[152:155], v[124:127]
	v_lshl_add_u64 v[142:143], v[140:141], 0, s[14:15]
	s_add_i32 s13, s11, 0x100
	s_cmpk_lt_u32 s11, 0x300
	v_mfma_f32_16x16x32_f16 v[116:119], v[192:195], v[152:155], v[116:119]
	s_cselect_b32 s42, s13, 0x3c0
	s_lshl_b64 s[14:15], s[42:43], 1
	s_add_i32 s13, s11, 0x80
	v_mfma_f32_16x16x32_f16 v[120:123], v[196:199], v[152:155], v[120:123]
	s_cmpk_lt_u32 s11, 0x380
	s_mov_b32 s11, s13
	v_mfma_f32_16x16x32_f16 v[112:115], v[200:203], v[152:155], v[112:115]
	ds_read_b128 v[152:155], v243 offset:22528
	s_waitcnt vmcnt(15)
	ds_write_b128 v147, v[40:43] offset:32768
	global_load_dwordx4 v[40:43], v[144:145], off
	s_waitcnt lgkmcnt(7)
	v_mfma_f32_16x16x32_f16 v[108:111], v[166:169], v[156:159], v[108:111]
	v_mfma_f32_16x16x32_f16 v[36:39], v[192:195], v[156:159], v[36:39]
	v_mfma_f32_16x16x32_f16 v[104:107], v[196:199], v[156:159], v[104:107]
	v_mfma_f32_16x16x32_f16 v[32:35], v[200:203], v[156:159], v[32:35]
	ds_read_b128 v[156:159], v242
	s_waitcnt vmcnt(14)
	ds_write_b128 v147, v[48:51] offset:36864
	v_add_co_u32_e32 v48, vcc, s94, v144
	s_nop 1
	v_addc_co_u32_e32 v49, vcc, 0, v145, vcc
	global_load_dwordx4 v[48:51], v[48:49], off
	s_waitcnt lgkmcnt(8)
	v_mfma_f32_16x16x32_f16 v[28:31], v[166:169], v[160:163], v[28:31]
	v_mfma_f32_16x16x32_f16 v[20:23], v[192:195], v[160:163], v[20:23]
	v_mfma_f32_16x16x32_f16 v[24:27], v[196:199], v[160:163], v[24:27]
	v_mfma_f32_16x16x32_f16 v[16:19], v[200:203], v[160:163], v[16:19]
	ds_read_b128 v[160:163], v242 offset:2048
	s_waitcnt vmcnt(14)
	ds_write_b128 v147, v[52:55] offset:40960
	v_add_co_u32_e32 v52, vcc, s72, v144
	s_nop 1
	v_addc_co_u32_e32 v53, vcc, 0, v145, vcc
	global_load_dwordx4 v[52:55], v[52:53], off
	s_waitcnt lgkmcnt(9)
	v_mfma_f32_16x16x32_f16 v[12:15], v[166:169], v[128:131], v[12:15]
	v_mfma_f32_16x16x32_f16 v[4:7], v[192:195], v[128:131], v[4:7]
	v_mfma_f32_16x16x32_f16 v[8:11], v[196:199], v[128:131], v[8:11]
	v_mfma_f32_16x16x32_f16 v[0:3], v[200:203], v[128:131], v[0:3]
	ds_read_b128 v[128:131], v242 offset:4096
	ds_read_b128 v[166:169], v242 offset:6144
	s_waitcnt vmcnt(14)
	ds_write_b128 v147, v[56:59] offset:45056
	v_add_co_u32_e32 v56, vcc, s73, v144
	s_nop 1
	v_addc_co_u32_e32 v57, vcc, 0, v145, vcc
	global_load_dwordx4 v[56:59], v[56:57], off
	s_waitcnt lgkmcnt(6)
	v_mfma_f32_16x16x32_f16 v[124:127], v[244:247], v[156:159], v[124:127]
	v_mfma_f32_16x16x32_f16 v[116:119], v[248:251], v[156:159], v[116:119]
	v_mfma_f32_16x16x32_f16 v[120:123], v[252:255], v[156:159], v[120:123]
	v_mfma_f32_16x16x32_f16 v[112:115], v[152:155], v[156:159], v[112:115]
	ds_write_b128 v147, v[44:47] offset:49152
	global_load_dwordx4 v[44:47], v[142:143], off
	v_lshl_add_u64 v[202:203], v[138:139], 0, s[14:15]
	s_waitcnt lgkmcnt(5)
	v_mfma_f32_16x16x32_f16 v[108:111], v[244:247], v[160:163], v[108:111]
	v_lshl_add_u64 v[200:201], v[140:141], 0, s[14:15]
	v_mfma_f32_16x16x32_f16 v[36:39], v[248:251], v[160:163], v[36:39]
	v_mfma_f32_16x16x32_f16 v[104:107], v[252:255], v[160:163], v[104:107]
	v_mfma_f32_16x16x32_f16 v[32:35], v[152:155], v[160:163], v[32:35]
	s_waitcnt vmcnt(15)
	ds_write_b128 v147, v[60:63] offset:53248
	v_add_co_u32_e32 v60, vcc, s94, v142
	s_nop 1
	v_addc_co_u32_e32 v61, vcc, 0, v143, vcc
	global_load_dwordx4 v[60:63], v[60:61], off
	s_waitcnt lgkmcnt(4)
	v_mfma_f32_16x16x32_f16 v[28:31], v[244:247], v[128:131], v[28:31]
	v_mfma_f32_16x16x32_f16 v[20:23], v[248:251], v[128:131], v[20:23]
	v_mfma_f32_16x16x32_f16 v[24:27], v[252:255], v[128:131], v[24:27]
	v_mfma_f32_16x16x32_f16 v[16:19], v[152:155], v[128:131], v[16:19]
	s_waitcnt vmcnt(15)
	ds_write_b128 v147, v[68:71] offset:57344
	v_add_co_u32_e32 v68, vcc, s72, v142
	s_nop 1
	v_addc_co_u32_e32 v69, vcc, 0, v143, vcc
	global_load_dwordx4 v[68:71], v[68:69], off
	s_waitcnt lgkmcnt(4)
	v_mfma_f32_16x16x32_f16 v[12:15], v[244:247], v[166:169], v[12:15]
	v_mfma_f32_16x16x32_f16 v[4:7], v[248:251], v[166:169], v[4:7]
	v_mfma_f32_16x16x32_f16 v[8:11], v[252:255], v[166:169], v[8:11]
	v_mfma_f32_16x16x32_f16 v[0:3], v[152:155], v[166:169], v[0:3]
	s_waitcnt vmcnt(15)
	ds_write_b128 v147, v[72:75] offset:61440
	v_add_co_u32_e32 v72, vcc, s73, v142
	s_nop 1
	v_addc_co_u32_e32 v73, vcc, 0, v143, vcc
	global_load_dwordx4 v[72:75], v[72:73], off
	s_waitcnt lgkmcnt(0)
	s_barrier
; template <int NJ>
; __device__ __forceinline__ void gemm_tile(const f16* __restrict__ A, int lda, const f16* __restrict__ Bt, int ldb,
;                                           int K, f32x4 (&acc)[4][NJ], f16* sA, f16* sB, const int tid) {
;     ...
;   G_LOAD(ra0, rb0, 0)
;   if (K > 64) G_LOAD(ra1, rb1, 64)
;   __syncthreads();
;   G_STORE(ra0, rb0, 0)
;   if (K > 128) G_LOAD(ra0, rb0, 128)
;   __syncthreads();
; #pragma unroll 1
;   for (int k0 = 0; k0 < K; k0 += 128) {
;     {
;       const int kof = (k0 + 192 < K) ? k0 + 192 : K - 64;
;       G_STEP(0, ra1, rb1, true, true, kof)
;     }
;     __syncthreads();
;     if (k0 + 64 >= K) break;
;     {
;       const int kof = (k0 + 256 < K) ? k0 + 256 : K - 64;
;       G_STEP(1, ra0, rb0, true, true, kof)
;     }
;     __syncthreads();
;   }
	ds_read_b128 v[160:163], v148 offset:49152
	ds_read_b128 v[166:169], v148 offset:51200
	ds_read_b128 v[192:195], v148 offset:53248
	ds_read_b128 v[196:199], v148 offset:55296
	ds_read_b128 v[128:131], v150 offset:32768
	ds_read_b128 v[142:145], v150 offset:34816
	ds_read_b128 v[152:155], v150 offset:36864
	ds_read_b128 v[156:159], v150 offset:38912
	ds_read_b128 v[244:247], v243 offset:49152
	ds_read_b128 v[248:251], v243 offset:51200
	ds_read_b128 v[252:255], v243 offset:53248
	s_waitcnt lgkmcnt(6)
	v_mfma_f32_16x16x32_f16 v[124:127], v[160:163], v[128:131], v[124:127]
	v_mfma_f32_16x16x32_f16 v[116:119], v[166:169], v[128:131], v[116:119]
	v_mfma_f32_16x16x32_f16 v[120:123], v[192:195], v[128:131], v[120:123]
	v_mfma_f32_16x16x32_f16 v[112:115], v[196:199], v[128:131], v[112:115]
	ds_read_b128 v[128:131], v243 offset:55296
	s_waitcnt vmcnt(13)
	ds_write_b128 v147, v[64:67]
	global_load_dwordx4 v[64:67], v[202:203], off
	s_waitcnt lgkmcnt(7)
	v_mfma_f32_16x16x32_f16 v[108:111], v[160:163], v[142:145], v[108:111]
	v_mfma_f32_16x16x32_f16 v[36:39], v[166:169], v[142:145], v[36:39]
	v_mfma_f32_16x16x32_f16 v[104:107], v[192:195], v[142:145], v[104:107]
	v_mfma_f32_16x16x32_f16 v[32:35], v[196:199], v[142:145], v[32:35]
	ds_read_b128 v[142:145], v242 offset:32768
	ds_write_b128 v147, v[80:83] offset:4096
	v_add_co_u32_e32 v80, vcc, s94, v202
	s_nop 1
	v_addc_co_u32_e32 v81, vcc, 0, v203, vcc
	global_load_dwordx4 v[80:83], v[80:81], off
	s_waitcnt lgkmcnt(8)
	v_mfma_f32_16x16x32_f16 v[28:31], v[160:163], v[152:155], v[28:31]
	v_mfma_f32_16x16x32_f16 v[20:23], v[166:169], v[152:155], v[20:23]
	v_mfma_f32_16x16x32_f16 v[24:27], v[192:195], v[152:155], v[24:27]
	v_mfma_f32_16x16x32_f16 v[16:19], v[196:199], v[152:155], v[16:19]
	ds_read_b128 v[152:155], v242 offset:34816
	ds_write_b128 v147, v[84:87] offset:8192
	v_add_co_u32_e32 v84, vcc, s72, v202
	s_nop 1
	v_addc_co_u32_e32 v85, vcc, 0, v203, vcc
	global_load_dwordx4 v[84:87], v[84:85], off
	s_waitcnt lgkmcnt(9)
	v_mfma_f32_16x16x32_f16 v[12:15], v[160:163], v[156:159], v[12:15]
	v_mfma_f32_16x16x32_f16 v[4:7], v[166:169], v[156:159], v[4:7]
	v_mfma_f32_16x16x32_f16 v[8:11], v[192:195], v[156:159], v[8:11]
	v_mfma_f32_16x16x32_f16 v[0:3], v[196:199], v[156:159], v[0:3]
	ds_read_b128 v[156:159], v242 offset:36864
	ds_read_b128 v[160:163], v242 offset:38912
	s_waitcnt vmcnt(14)
	ds_write_b128 v147, v[88:91] offset:12288
	v_add_co_u32_e32 v88, vcc, s73, v202
	s_nop 1
	v_addc_co_u32_e32 v89, vcc, 0, v203, vcc
	global_load_dwordx4 v[88:91], v[88:89], off
	s_waitcnt lgkmcnt(6)
	v_mfma_f32_16x16x32_f16 v[124:127], v[244:247], v[142:145], v[124:127]
	v_mfma_f32_16x16x32_f16 v[116:119], v[248:251], v[142:145], v[116:119]
	v_mfma_f32_16x16x32_f16 v[120:123], v[252:255], v[142:145], v[120:123]
	v_mfma_f32_16x16x32_f16 v[112:115], v[128:131], v[142:145], v[112:115]
	ds_write_b128 v147, v[76:79] offset:16384
	global_load_dwordx4 v[76:79], v[200:201], off
	s_waitcnt lgkmcnt(5)
	v_mfma_f32_16x16x32_f16 v[108:111], v[244:247], v[152:155], v[108:111]
	v_mfma_f32_16x16x32_f16 v[36:39], v[248:251], v[152:155], v[36:39]
	v_mfma_f32_16x16x32_f16 v[104:107], v[252:255], v[152:155], v[104:107]
	v_mfma_f32_16x16x32_f16 v[32:35], v[128:131], v[152:155], v[32:35]
	s_waitcnt vmcnt(15)
	ds_write_b128 v147, v[92:95] offset:20480
	v_add_co_u32_e32 v92, vcc, s94, v200
	s_nop 1
	v_addc_co_u32_e32 v93, vcc, 0, v201, vcc
	global_load_dwordx4 v[92:95], v[92:93], off
	s_waitcnt lgkmcnt(4)
	v_mfma_f32_16x16x32_f16 v[28:31], v[244:247], v[156:159], v[28:31]
	v_mfma_f32_16x16x32_f16 v[20:23], v[248:251], v[156:159], v[20:23]
	v_mfma_f32_16x16x32_f16 v[24:27], v[252:255], v[156:159], v[24:27]
	v_mfma_f32_16x16x32_f16 v[16:19], v[128:131], v[156:159], v[16:19]
	s_waitcnt vmcnt(15)
	ds_write_b128 v147, v[96:99] offset:24576
	v_add_co_u32_e32 v96, vcc, s72, v200
	s_nop 1
	v_addc_co_u32_e32 v97, vcc, 0, v201, vcc
	global_load_dwordx4 v[96:99], v[96:97], off
	s_waitcnt lgkmcnt(4)
	v_mfma_f32_16x16x32_f16 v[12:15], v[244:247], v[160:163], v[12:15]
	v_mfma_f32_16x16x32_f16 v[4:7], v[248:251], v[160:163], v[4:7]
	v_mfma_f32_16x16x32_f16 v[8:11], v[252:255], v[160:163], v[8:11]
	v_mfma_f32_16x16x32_f16 v[0:3], v[128:131], v[160:163], v[0:3]
	s_waitcnt vmcnt(15)
	ds_write_b128 v147, v[100:103] offset:28672
	v_add_co_u32_e32 v100, vcc, s73, v200
	s_nop 1
	v_addc_co_u32_e32 v101, vcc, 0, v201, vcc
	global_load_dwordx4 v[100:103], v[100:101], off
	s_waitcnt lgkmcnt(0)
	s_barrier
	s_cbranch_scc1 .LBB0_1398
; __device__ __forceinline__ float siluf_(float x) { return x / (1.0f + __expf(-x)); }
; __device__ __forceinline__ void phase_g4(const Params& p, f16* smem) {
;     ...
; #pragma unroll
;     for (int i = 0; i < 4; ++i) {
;       int m = m0 + wm * 64 + i * 16 + (lane & 15);
; #pragma unroll
;       for (int jj = 0; jj < 2; ++jj) {
;         int u = nt * 64 + wn * 32 + jj * 16 + 4 * (lane >> 4);
;         f16x4 o;
; #pragma unroll
;         for (int r = 0; r < 4; ++r) o[r] = (f16)(siluf_(acc[i][jj][r]) * acc[i][jj + 2][r]);
;         *(f16x4*)(hid + (size_t)m * FF + u) = o;
;       }
;     }
	s_waitcnt vmcnt(15)
	v_mul_f32_e32 v41, 0xbfb8aa3b, v124
	s_waitcnt vmcnt(11)
	v_exp_f32_e32 v46, v41
	v_mul_f32_e32 v41, 0xbfb8aa3b, v125
	v_exp_f32_e32 v47, v41
	v_add_u32_e32 v42, s10, v146
	v_lshl_or_b32 v40, s12, 6, v149
	v_mad_i64_i32 v[44:45], s[10:11], v42, s96, v[132:133]
	v_pk_add_f32 v[46:47], v[46:47], 1.0 op_sel_hi:[1,0]
	s_add_i32 s5, s5, s26
	s_movk_i32 s14, 0x2cb0
	s_cmp_eq_u32 s4, 3
	s_cselect_b32 s14, 0x2c00, s14
	s_cmp_lt_i32 s5, s14
	v_rcp_f32_e32 v43, v47
	s_nop 0
	v_mul_f32_e32 v41, v125, v43
	v_mov_b32_e32 v47, v41
	s_nop 0
	v_rcp_f32_e32 v43, v46
	s_nop 0
	v_mul_f32_e32 v41, v124, v43
	v_mov_b32_e32 v46, v41
	v_mul_f32_e32 v41, 0xbfb8aa3b, v126
	v_exp_f32_e32 v48, v41
	v_mul_f32_e32 v41, 0xbfb8aa3b, v127
	v_exp_f32_e32 v49, v41
	v_pk_mul_f32 v[46:47], v[120:121], v[46:47]
	v_pk_add_f32 v[48:49], v[48:49], 1.0 op_sel_hi:[1,0]
	s_nop 0
	v_cvt_pk_f16_f32 v46, v46, v47
	v_rcp_f32_e32 v43, v49
	s_nop 0
	v_mul_f32_e32 v41, v127, v43
	v_mov_b32_e32 v49, v41
	s_nop 0
	v_rcp_f32_e32 v43, v48
	s_nop 0
	v_mul_f32_e32 v41, v126, v43
	v_mov_b32_e32 v48, v41
	v_ashrrev_i32_e32 v41, 31, v40
	v_pk_mul_f32 v[48:49], v[122:123], v[48:49]
	v_lshlrev_b64 v[40:41], 1, v[40:41]
	v_cvt_pk_f16_f32 v47, v48, v49
	v_lshl_add_u64 v[44:45], v[44:45], 0, v[40:41]
	v_mul_f32_e32 v43, 0xbfb8aa3b, v116
	global_store_dwordx2 v[44:45], v[46:47], off
	v_exp_f32_e32 v46, v43
	v_mul_f32_e32 v43, 0xbfb8aa3b, v117
	v_exp_f32_e32 v47, v43
	s_nop 0
	v_pk_add_f32 v[46:47], v[46:47], 1.0 op_sel_hi:[1,0]
	s_nop 0
	s_nop 0
	v_rcp_f32_e32 v48, v47
	s_nop 0
	v_mul_f32_e32 v43, v117, v48
	v_mov_b32_e32 v47, v43
	s_nop 0
	v_rcp_f32_e32 v48, v46
	s_nop 0
	v_mul_f32_e32 v43, v116, v48
	v_mov_b32_e32 v46, v43
	v_mul_f32_e32 v43, 0xbfb8aa3b, v118
	v_exp_f32_e32 v48, v43
	v_mul_f32_e32 v43, 0xbfb8aa3b, v119
	v_exp_f32_e32 v49, v43
	v_pk_mul_f32 v[46:47], v[112:113], v[46:47]
	v_pk_add_f32 v[48:49], v[48:49], 1.0 op_sel_hi:[1,0]
	s_nop 0
	v_cvt_pk_f16_f32 v46, v46, v47
	s_nop 0
	v_rcp_f32_e32 v47, v49
	s_nop 0
	v_mul_f32_e32 v43, v119, v47
	v_mov_b32_e32 v49, v43
	s_nop 0
	v_rcp_f32_e32 v47, v48
	s_nop 0
	v_mul_f32_e32 v43, v118, v47
	v_mov_b32_e32 v48, v43
	v_pk_mul_f32 v[48:49], v[114:115], v[48:49]
	v_or_b32_e32 v43, 16, v42
	v_cvt_pk_f16_f32 v47, v48, v49
	global_store_dwordx2 v[44:45], v[46:47], off offset:32
	v_mad_i64_i32 v[44:45], s[10:11], v43, s96, v[132:133]
	v_mul_f32_e32 v43, 0xbfb8aa3b, v108
	v_exp_f32_e32 v46, v43
	v_mul_f32_e32 v43, 0xbfb8aa3b, v109
	v_exp_f32_e32 v47, v43
	v_lshl_add_u64 v[44:45], v[44:45], 0, v[40:41]
	v_pk_add_f32 v[46:47], v[46:47], 1.0 op_sel_hi:[1,0]
	s_nop 0
	s_nop 0
	v_rcp_f32_e32 v48, v47
	s_nop 0
	v_mul_f32_e32 v43, v109, v48
	v_mov_b32_e32 v47, v43
	s_nop 0
	v_rcp_f32_e32 v48, v46
	s_nop 0
	v_mul_f32_e32 v43, v108, v48
	v_mov_b32_e32 v46, v43
	v_mul_f32_e32 v43, 0xbfb8aa3b, v110
	v_exp_f32_e32 v48, v43
	v_mul_f32_e32 v43, 0xbfb8aa3b, v111
	v_exp_f32_e32 v49, v43
	v_pk_mul_f32 v[46:47], v[104:105], v[46:47]
	v_pk_add_f32 v[48:49], v[48:49], 1.0 op_sel_hi:[1,0]
	s_nop 0
	v_cvt_pk_f16_f32 v46, v46, v47
	s_nop 0
	v_rcp_f32_e32 v47, v49
	s_nop 0
	v_mul_f32_e32 v43, v111, v47
	v_mov_b32_e32 v49, v43
	s_nop 0
	v_rcp_f32_e32 v47, v48
	s_nop 0
	v_mul_f32_e32 v43, v110, v47
	v_mov_b32_e32 v48, v43
	v_pk_mul_f32 v[48:49], v[106:107], v[48:49]
	v_mul_f32_e32 v43, 0xbfb8aa3b, v36
	v_cvt_pk_f16_f32 v47, v48, v49
	global_store_dwordx2 v[44:45], v[46:47], off
	v_exp_f32_e32 v46, v43
	v_mul_f32_e32 v43, 0xbfb8aa3b, v37
	v_exp_f32_e32 v47, v43
	s_nop 0
	v_pk_add_f32 v[46:47], v[46:47], 1.0 op_sel_hi:[1,0]
	s_nop 0
	s_nop 0
	v_rcp_f32_e32 v48, v47
	s_nop 0
	v_mul_f32_e32 v43, v37, v48
	v_mov_b32_e32 v37, v43
	s_nop 0
	v_rcp_f32_e32 v47, v46
	s_nop 0
	v_mul_f32_e32 v43, v36, v47
	v_mov_b32_e32 v36, v43
	v_pk_mul_f32 v[32:33], v[32:33], v[36:37]
	s_nop 0
	v_cvt_pk_f16_f32 v32, v32, v33
	v_mul_f32_e32 v33, 0xbfb8aa3b, v38
	v_exp_f32_e32 v36, v33
	v_mul_f32_e32 v33, 0xbfb8aa3b, v39
	v_exp_f32_e32 v37, v33
	s_nop 0
	v_pk_add_f32 v[36:37], v[36:37], 1.0 op_sel_hi:[1,0]
	s_nop 0
	s_nop 0
	v_rcp_f32_e32 v43, v37
	s_nop 0
	v_mul_f32_e32 v33, v39, v43
	v_mov_b32_e32 v37, v33
	s_nop 0
	v_rcp_f32_e32 v39, v36
	s_nop 0
	v_mul_f32_e32 v33, v38, v39
	v_mov_b32_e32 v36, v33
; __device__ __forceinline__ float siluf_(float x) { return x / (1.0f + __expf(-x)); }
; __device__ __forceinline__ void phase_g4(const Params& p, f16* smem) {
;     ...
; #pragma unroll
;     for (int i = 0; i < 4; ++i) {
;       int m = m0 + wm * 64 + i * 16 + (lane & 15);
; #pragma unroll
;       for (int jj = 0; jj < 2; ++jj) {
;         int u = nt * 64 + wn * 32 + jj * 16 + 4 * (lane >> 4);
;         f16x4 o;
; #pragma unroll
;         for (int r = 0; r < 4; ++r) o[r] = (f16)(siluf_(acc[i][jj][r]) * acc[i][jj + 2][r]);
;         *(f16x4*)(hid + (size_t)m * FF + u) = o;
;       }
;     }
	v_pk_mul_f32 v[34:35], v[34:35], v[36:37]
	s_nop 0
	v_cvt_pk_f16_f32 v33, v34, v35
	v_mul_f32_e32 v34, 0xbfb8aa3b, v28
	v_mul_f32_e32 v35, 0xbfb8aa3b, v29
	v_exp_f32_e32 v34, v34
	v_exp_f32_e32 v35, v35
	global_store_dwordx2 v[44:45], v[32:33], off offset:32
	v_or_b32_e32 v32, 32, v42
	v_mad_i64_i32 v[32:33], s[10:11], v32, s96, v[132:133]
	v_pk_add_f32 v[34:35], v[34:35], 1.0 op_sel_hi:[1,0]
	s_nop 0
	s_nop 0
	v_rcp_f32_e32 v37, v35
	s_nop 0
	v_mul_f32_e32 v36, v29, v37
	v_mov_b32_e32 v29, v36
	s_nop 0
	v_rcp_f32_e32 v36, v34
	s_nop 0
	v_mul_f32_e32 v35, v28, v36
	v_mov_b32_e32 v28, v35
	v_pk_mul_f32 v[24:25], v[24:25], v[28:29]
	s_nop 0
	v_cvt_pk_f16_f32 v24, v24, v25
	v_mul_f32_e32 v25, 0xbfb8aa3b, v30
	v_exp_f32_e32 v28, v25
	v_mul_f32_e32 v25, 0xbfb8aa3b, v31
	v_exp_f32_e32 v29, v25
	s_nop 0
	v_pk_add_f32 v[28:29], v[28:29], 1.0 op_sel_hi:[1,0]
	s_nop 0
	s_nop 0
	v_rcp_f32_e32 v34, v29
	s_nop 0
	v_mul_f32_e32 v25, v31, v34
	v_mov_b32_e32 v29, v25
	s_nop 0
	v_rcp_f32_e32 v31, v28
	s_nop 0
	v_mul_f32_e32 v25, v30, v31
	v_mov_b32_e32 v28, v25
	v_pk_mul_f32 v[26:27], v[26:27], v[28:29]
	s_nop 0
	v_cvt_pk_f16_f32 v25, v26, v27
	v_lshl_add_u64 v[26:27], v[32:33], 0, v[40:41]
	global_store_dwordx2 v[26:27], v[24:25], off
	v_mul_f32_e32 v24, 0xbfb8aa3b, v20
	v_mul_f32_e32 v25, 0xbfb8aa3b, v21
	v_exp_f32_e32 v24, v24
	v_exp_f32_e32 v25, v25
	s_nop 0
	v_pk_add_f32 v[24:25], v[24:25], 1.0 op_sel_hi:[1,0]
	s_nop 0
	s_nop 0
	v_rcp_f32_e32 v29, v25
	s_nop 0
	v_mul_f32_e32 v28, v21, v29
	v_mov_b32_e32 v21, v28
	s_nop 0
	v_rcp_f32_e32 v28, v24
	s_nop 0
	v_mul_f32_e32 v25, v20, v28
	v_mov_b32_e32 v20, v25
	v_pk_mul_f32 v[16:17], v[16:17], v[20:21]
	s_nop 0
	v_cvt_pk_f16_f32 v16, v16, v17
	v_mul_f32_e32 v17, 0xbfb8aa3b, v22
	v_exp_f32_e32 v20, v17
	v_mul_f32_e32 v17, 0xbfb8aa3b, v23
	v_exp_f32_e32 v21, v17
	s_nop 0
	v_pk_add_f32 v[20:21], v[20:21], 1.0 op_sel_hi:[1,0]
	s_nop 0
	s_nop 0
	v_rcp_f32_e32 v24, v21
	s_nop 0
	v_mul_f32_e32 v17, v23, v24
	v_mov_b32_e32 v21, v17
	s_nop 0
	v_rcp_f32_e32 v23, v20
	s_nop 0
	v_mul_f32_e32 v17, v22, v23
	v_mov_b32_e32 v20, v17
	v_pk_mul_f32 v[18:19], v[18:19], v[20:21]
	s_nop 0
	v_cvt_pk_f16_f32 v17, v18, v19
	v_mul_f32_e32 v18, 0xbfb8aa3b, v12
	v_mul_f32_e32 v19, 0xbfb8aa3b, v13
	v_exp_f32_e32 v18, v18
	v_exp_f32_e32 v19, v19
	global_store_dwordx2 v[26:27], v[16:17], off offset:32
	v_or_b32_e32 v16, 48, v42
	v_mad_i64_i32 v[16:17], s[10:11], v16, s96, v[132:133]
	v_pk_add_f32 v[18:19], v[18:19], 1.0 op_sel_hi:[1,0]
	s_nop 0
	s_nop 0
	v_rcp_f32_e32 v21, v19
	s_nop 0
	v_mul_f32_e32 v20, v13, v21
	v_mov_b32_e32 v13, v20
	s_nop 0
	v_rcp_f32_e32 v20, v18
	s_nop 0
	v_mul_f32_e32 v19, v12, v20
	v_mov_b32_e32 v12, v19
	v_pk_mul_f32 v[8:9], v[8:9], v[12:13]
	s_nop 0
	v_cvt_pk_f16_f32 v8, v8, v9
	v_mul_f32_e32 v9, 0xbfb8aa3b, v14
	v_exp_f32_e32 v12, v9
	v_mul_f32_e32 v9, 0xbfb8aa3b, v15
	v_exp_f32_e32 v13, v9
	s_nop 0
	v_pk_add_f32 v[12:13], v[12:13], 1.0 op_sel_hi:[1,0]
	s_nop 0
	s_nop 0
	v_rcp_f32_e32 v18, v13
	s_nop 0
	v_mul_f32_e32 v9, v15, v18
	v_mov_b32_e32 v13, v9
	s_nop 0
	v_rcp_f32_e32 v15, v12
	s_nop 0
	v_mul_f32_e32 v9, v14, v15
	v_mov_b32_e32 v12, v9
	v_pk_mul_f32 v[10:11], v[10:11], v[12:13]
	s_nop 0
	v_cvt_pk_f16_f32 v9, v10, v11
	v_lshl_add_u64 v[10:11], v[16:17], 0, v[40:41]
	global_store_dwordx2 v[10:11], v[8:9], off
	v_mul_f32_e32 v8, 0xbfb8aa3b, v4
	v_mul_f32_e32 v9, 0xbfb8aa3b, v5
	v_exp_f32_e32 v8, v8
	v_exp_f32_e32 v9, v9
	s_nop 0
	v_pk_add_f32 v[8:9], v[8:9], 1.0 op_sel_hi:[1,0]
	s_nop 0
	s_nop 0
	v_rcp_f32_e32 v13, v9
	s_nop 0
	v_mul_f32_e32 v12, v5, v13
	v_mov_b32_e32 v5, v12
	s_nop 0
	v_rcp_f32_e32 v12, v8
	s_nop 0
	v_mul_f32_e32 v9, v4, v12
	v_mov_b32_e32 v4, v9
	v_pk_mul_f32 v[0:1], v[0:1], v[4:5]
	s_nop 0
	v_cvt_pk_f16_f32 v0, v0, v1
	v_mul_f32_e32 v1, 0xbfb8aa3b, v6
	v_exp_f32_e32 v4, v1
	v_mul_f32_e32 v1, 0xbfb8aa3b, v7
	v_exp_f32_e32 v5, v1
	s_nop 0
	v_pk_add_f32 v[4:5], v[4:5], 1.0 op_sel_hi:[1,0]
	s_nop 0
	s_nop 0
	v_rcp_f32_e32 v8, v5
	s_nop 0
	v_mul_f32_e32 v1, v7, v8
	v_mov_b32_e32 v5, v1
	s_nop 0
	v_rcp_f32_e32 v7, v4
	s_nop 0
	v_mul_f32_e32 v1, v6, v7
	v_mov_b32_e32 v4, v1
	v_pk_mul_f32 v[2:3], v[2:3], v[4:5]
	s_nop 0
	v_cvt_pk_f16_f32 v1, v2, v3
	global_store_dwordx2 v[10:11], v[0:1], off offset:32
	s_cbranch_scc1 .LBB0_1397
